# add DPP/permlane-swap butterfly (bit-identical) for the norm tails row reductions instead of ds_bpermute
# speedup vs baseline: 1.0132x; 1.0104x over previous
.LBB0_793:
	s_lshl_b64 s[18:19], s[38:39], 12
	s_add_u32 s18, s36, s18
	s_addc_u32 s19, s37, s19
	s_lshl_b64 s[0:1], s[0:1], 12
	s_add_u32 s0, s6, s0
	s_addc_u32 s1, s7, s1
	s_lshl_b64 s[6:7], s[8:9], 12
	s_add_u32 s6, s40, s6
	s_addc_u32 s7, s41, s7
	v_lshl_add_u64 v[66:67], v[48:49], 3, s[6:7]
	v_lshl_add_u64 v[68:69], v[64:65], 0, s[88:89]
	s_mov_b32 s6, 0xda00000
	v_add_co_u32_e32 v70, vcc, s6, v68
	s_mov_b32 s6, 0xdb80000
	s_nop 0
	v_addc_co_u32_e32 v71, vcc, 0, v69, vcc
	v_add_co_u32_e32 v72, vcc, s6, v68
	s_mov_b32 s6, 0xdd00000
	s_nop 0
	v_addc_co_u32_e32 v73, vcc, 0, v69, vcc
	v_lshl_add_u64 v[32:33], s[18:19], 0, v[50:51]
	v_add_co_u32_e32 v74, vcc, s6, v68
	global_load_dwordx4 v[44:47], v[32:33], off
	global_load_dwordx4 v[40:43], v[32:33], off offset:1024
	global_load_dwordx4 v[36:39], v[32:33], off offset:2048
	s_nop 0
	global_load_dwordx4 v[32:35], v[32:33], off offset:3072
	s_nop 0
	global_load_dwordx2 v[84:85], v[70:71], off
	global_load_dwordx2 v[96:97], v[70:71], off offset:512
	global_load_dwordx2 v[82:83], v[70:71], off offset:1024
	global_load_dwordx2 v[76:77], v[70:71], off offset:1536
	v_addc_co_u32_e32 v75, vcc, 0, v69, vcc
	s_mov_b32 s6, 0xde80000
	global_load_dwordx2 v[92:93], v[72:73], off
	global_load_dwordx2 v[100:101], v[72:73], off offset:512
	global_load_dwordx2 v[88:89], v[72:73], off offset:1024
	global_load_dwordx2 v[78:79], v[72:73], off offset:1536
	v_add_co_u32_e32 v68, vcc, s6, v68
	global_load_dwordx2 v[106:107], v[74:75], off
	global_load_dwordx2 v[108:109], v[74:75], off offset:512
	global_load_dwordx2 v[90:91], v[74:75], off offset:1024
	global_load_dwordx2 v[80:81], v[74:75], off offset:1536
	v_addc_co_u32_e32 v69, vcc, 0, v69, vcc
	global_load_dwordx2 v[110:111], v[68:69], off
	global_load_dwordx2 v[112:113], v[68:69], off offset:512
	global_load_dwordx2 v[98:99], v[68:69], off offset:1024
	global_load_dwordx2 v[94:95], v[68:69], off offset:1536
	s_waitcnt vmcnt(15)
	v_lshlrev_b32_e32 v86, 16, v84
	v_and_b32_e32 v87, 0xffff0000, v84
	v_lshlrev_b32_e32 v84, 16, v85
	v_and_b32_e32 v85, 0xffff0000, v85
	s_waitcnt vmcnt(11)
	v_lshlrev_b32_e32 v114, 16, v92
	v_and_b32_e32 v115, 0xffff0000, v92
	v_pk_add_f32 v[84:85], v[84:85], 0 op_sel_hi:[1,0]
	v_lshlrev_b32_e32 v92, 16, v93
	v_and_b32_e32 v93, 0xffff0000, v93
	v_pk_add_f32 v[84:85], v[84:85], v[92:93]
	s_waitcnt vmcnt(7)
	v_lshlrev_b32_e32 v92, 16, v107
	v_and_b32_e32 v93, 0xffff0000, v107
	v_pk_add_f32 v[84:85], v[84:85], v[92:93]
	s_waitcnt vmcnt(3)
	v_lshlrev_b32_e32 v92, 16, v111
	v_and_b32_e32 v93, 0xffff0000, v111
	v_pk_add_f32 v[86:87], v[86:87], 0 op_sel_hi:[1,0]
	v_pk_add_f32 v[92:93], v[84:85], v[92:93]
	v_lshlrev_b32_e32 v84, 16, v96
	v_and_b32_e32 v85, 0xffff0000, v96
	v_lshlrev_b32_e32 v96, 16, v97
	v_and_b32_e32 v97, 0xffff0000, v97
	v_pk_add_f32 v[86:87], v[86:87], v[114:115]
	v_lshlrev_b32_e32 v114, 16, v106
	v_and_b32_e32 v115, 0xffff0000, v106
	v_lshlrev_b32_e32 v106, 16, v100
	v_and_b32_e32 v107, 0xffff0000, v100
	v_pk_add_f32 v[96:97], v[96:97], 0 op_sel_hi:[1,0]
	v_lshlrev_b32_e32 v100, 16, v101
	v_and_b32_e32 v101, 0xffff0000, v101
	v_pk_add_f32 v[84:85], v[84:85], 0 op_sel_hi:[1,0]
	v_pk_add_f32 v[96:97], v[96:97], v[100:101]
	v_lshlrev_b32_e32 v100, 16, v109
	v_and_b32_e32 v101, 0xffff0000, v109
	v_pk_add_f32 v[84:85], v[84:85], v[106:107]
	v_lshlrev_b32_e32 v106, 16, v108
	v_and_b32_e32 v107, 0xffff0000, v108
	v_pk_add_f32 v[96:97], v[96:97], v[100:101]
	s_waitcnt vmcnt(2)
	v_lshlrev_b32_e32 v100, 16, v113
	v_and_b32_e32 v101, 0xffff0000, v113
	v_pk_add_f32 v[84:85], v[84:85], v[106:107]
	v_lshlrev_b32_e32 v106, 16, v112
	v_and_b32_e32 v107, 0xffff0000, v112
	v_pk_add_f32 v[100:101], v[96:97], v[100:101]
	v_lshlrev_b32_e32 v96, 16, v82
	v_and_b32_e32 v97, 0xffff0000, v82
	v_lshlrev_b32_e32 v82, 16, v83
	v_and_b32_e32 v83, 0xffff0000, v83
	v_pk_add_f32 v[84:85], v[84:85], v[106:107]
	v_lshlrev_b32_e32 v106, 16, v88
	v_and_b32_e32 v107, 0xffff0000, v88
	v_pk_add_f32 v[82:83], v[82:83], 0 op_sel_hi:[1,0]
	v_lshlrev_b32_e32 v88, 16, v89
	v_and_b32_e32 v89, 0xffff0000, v89
	v_pk_add_f32 v[82:83], v[82:83], v[88:89]
	v_lshlrev_b32_e32 v88, 16, v91
	v_and_b32_e32 v89, 0xffff0000, v91
	v_pk_add_f32 v[82:83], v[82:83], v[88:89]
	s_waitcnt vmcnt(1)
	v_lshlrev_b32_e32 v88, 16, v99
	v_and_b32_e32 v89, 0xffff0000, v99
	v_pk_add_f32 v[96:97], v[96:97], 0 op_sel_hi:[1,0]
	v_pk_add_f32 v[88:89], v[82:83], v[88:89]
	v_lshlrev_b32_e32 v82, 16, v76
	v_and_b32_e32 v83, 0xffff0000, v76
	v_lshlrev_b32_e32 v76, 16, v77
	v_and_b32_e32 v77, 0xffff0000, v77
	v_pk_add_f32 v[86:87], v[86:87], v[114:115]
	v_lshlrev_b32_e32 v114, 16, v110
	v_and_b32_e32 v115, 0xffff0000, v110
	v_pk_add_f32 v[96:97], v[96:97], v[106:107]
	v_lshlrev_b32_e32 v106, 16, v90
	v_and_b32_e32 v107, 0xffff0000, v90
	v_pk_add_f32 v[82:83], v[82:83], 0 op_sel_hi:[1,0]
	v_lshlrev_b32_e32 v90, 16, v78
	v_and_b32_e32 v91, 0xffff0000, v78
	v_pk_add_f32 v[76:77], v[76:77], 0 op_sel_hi:[1,0]
	v_lshlrev_b32_e32 v78, 16, v79
	v_and_b32_e32 v79, 0xffff0000, v79
	v_pk_add_f32 v[86:87], v[86:87], v[114:115]
	v_pk_add_f32 v[82:83], v[82:83], v[90:91]
	v_lshlrev_b32_e32 v90, 16, v80
	v_and_b32_e32 v91, 0xffff0000, v80
	v_pk_add_f32 v[76:77], v[76:77], v[78:79]
	v_lshlrev_b32_e32 v78, 16, v81
	v_and_b32_e32 v79, 0xffff0000, v81
	v_pk_add_f32 v[96:97], v[96:97], v[106:107]
	v_lshlrev_b32_e32 v106, 16, v98
	v_and_b32_e32 v107, 0xffff0000, v98
	v_pk_add_f32 v[82:83], v[82:83], v[90:91]
	s_waitcnt vmcnt(0)
	v_lshlrev_b32_e32 v90, 16, v94
	v_and_b32_e32 v91, 0xffff0000, v94
	v_pk_add_f32 v[76:77], v[76:77], v[78:79]
	v_lshlrev_b32_e32 v78, 16, v95
	v_and_b32_e32 v79, 0xffff0000, v95
	v_mov_b32_e32 v80, v87
	v_mov_b32_e32 v81, v93
	v_pk_add_f32 v[96:97], v[96:97], v[106:107]
	v_pk_add_f32 v[82:83], v[82:83], v[90:91]
	v_pk_add_f32 v[76:77], v[76:77], v[78:79]
	v_mov_b32_e32 v78, v86
	v_mov_b32_e32 v79, v92
	v_pk_mul_f32 v[80:81], v[80:81], v[80:81]
	v_mov_b32_e32 v90, v85
	v_mov_b32_e32 v91, v101
	v_pk_fma_f32 v[78:79], v[78:79], v[78:79], v[80:81]
	v_mov_b32_e32 v80, v84
	v_mov_b32_e32 v81, v100
	v_pk_mul_f32 v[90:91], v[90:91], v[90:91]
	v_mul_f32_e32 v60, v97, v97
	v_pk_fma_f32 v[80:81], v[80:81], v[80:81], v[90:91]
	v_pk_fma_f32 v[90:91], v[96:97], v[96:97], v[60:61] op_sel_hi:[1,1,0]
	v_mul_f32_e32 v60, v89, v89
	v_pk_add_f32 v[78:79], v[78:79], v[78:79] op_sel:[0,1] op_sel_hi:[1,0]
	v_pk_add_f32 v[80:81], v[80:81], v[80:81] op_sel:[0,1] op_sel_hi:[1,0]
	v_pk_fma_f32 v[94:95], v[88:89], v[88:89], v[60:61] op_sel_hi:[1,1,0]
	v_pk_mul_f32 v[98:99], v[82:83], v[82:83]
	v_pk_mul_f32 v[106:107], v[76:77], v[76:77]
	v_mov_b32_e32 v79, v98
	v_mov_b32_e32 v81, v99
	v_mov_b32_e32 v91, v106
	v_mov_b32_e32 v95, v107
	v_pk_add_f32 v[78:79], v[78:79], v[80:81]
	v_pk_add_f32 v[80:81], v[90:91], v[94:95]
	s_nop 0
	v_pk_add_f32 v[78:79], v[78:79], v[80:81]
	s_nop 0
	v_add_f32_e32 v60, v78, v79
	s_nop 1
	v_mov_b32_dpp v78, v60 quad_perm:[1,0,3,2] row_mask:0xf bank_mask:0xf
	s_waitcnt lgkmcnt(0)
	v_add_f32_e32 v60, v60, v78
	s_nop 1
	v_mov_b32_dpp v78, v60 quad_perm:[2,3,0,1] row_mask:0xf bank_mask:0xf
	s_waitcnt lgkmcnt(0)
	v_add_f32_e32 v60, v60, v78
	s_nop 1
	v_mov_b32_dpp v78, v60 row_half_mirror row_mask:0xf bank_mask:0xf
	s_waitcnt lgkmcnt(0)
	v_add_f32_e32 v60, v60, v78
	s_nop 1
	v_mov_b32_dpp v78, v60 row_mirror row_mask:0xf bank_mask:0xf
	s_waitcnt lgkmcnt(0)
	v_add_f32_e32 v60, v60, v78
	v_mov_b32_e32 v78, v60
	s_nop 1
	v_permlane16_swap_b32 v60, v78
	s_waitcnt lgkmcnt(0)
	v_add_f32_e32 v60, v60, v78
	v_mov_b32_e32 v78, v60
	s_nop 1
	v_permlane32_swap_b32 v60, v78
	s_waitcnt lgkmcnt(0)
	v_add_f32_e32 v60, v60, v78
	v_fmamk_f32 v60, v60, 0x3a800000, v102
	v_cmp_gt_f32_e32 vcc, s84, v60
	v_mul_f32_e32 v78, 0x4b800000, v60
	s_nop 0
	v_cndmask_b32_e32 v60, v60, v78, vcc
	v_rsq_f32_e32 v60, v60
	s_nop 0
	v_mul_f32_e32 v78, 0x45800000, v60
	v_cndmask_b32_e32 v78, v60, v78, vcc
	v_pk_mul_f32 v[80:81], v[92:93], v[78:79] op_sel_hi:[1,0]
	v_pk_mul_f32 v[86:87], v[86:87], v[78:79] op_sel_hi:[1,0]
	v_pk_fma_f32 v[46:47], v[2:3], v[80:81], v[46:47]
	v_pk_fma_f32 v[44:45], v[0:1], v[86:87], v[44:45]
	s_and_b64 vcc, exec, s[10:11]
	s_cbranch_vccnz .LBB0_819
	v_lshl_add_u64 v[80:81], v[66:67], 0, s[70:71]
	v_cvt_pk_bf16_f32 v86, v44, v45
	v_cvt_pk_bf16_f32 v87, v46, v47
	s_nop 0
	global_store_dwordx2 v[80:81], v[86:87], off sc0 sc1
	s_nop 1
	v_lshl_add_u64 v[80:81], s[0:1], 0, v[50:51]
	s_cbranch_execnz .LBB0_796

.LBB0_805:
	s_and_b64 vcc, exec, s[10:11]
	v_lshl_add_u64 v[66:67], v[62:63], 0, s[88:89]
	s_cbranch_vccnz .LBB0_807
	v_mul_f32_e32 v60, v44, v44
	v_mul_f32_e32 v76, v46, v46
	v_fmac_f32_e32 v60, v45, v45
	v_fmac_f32_e32 v76, v47, v47
	v_add_f32_e32 v60, v76, v60
	v_mul_f32_e32 v76, v40, v40
	v_mul_f32_e32 v77, v43, v43
	v_fmac_f32_e32 v76, v41, v41
	v_fmac_f32_e32 v77, v42, v42
	v_add_f32_e32 v76, v77, v76
	v_add_f32_e32 v60, v60, v76
	v_mul_f32_e32 v76, v36, v36
	v_mul_f32_e32 v77, v39, v39
	v_fmac_f32_e32 v76, v37, v37
	v_fmac_f32_e32 v77, v38, v38
	v_add_f32_e32 v76, v77, v76
	v_add_f32_e32 v60, v60, v76
	v_mov_b32_e32 v76, v35
	v_mov_b32_e32 v77, v32
	v_pk_mul_f32 v[76:77], v[76:77], v[76:77]
	v_mov_b32_e32 v78, v34
	v_mov_b32_e32 v79, v33
	v_pk_fma_f32 v[76:77], v[78:79], v[78:79], v[76:77]
	s_mov_b64 s[0:1], 0x3800000
	v_add_f32_e32 v76, v76, v77
	v_add_f32_e32 v60, v60, v76
	s_nop 1
	v_mov_b32_dpp v76, v60 quad_perm:[1,0,3,2] row_mask:0xf bank_mask:0xf
	s_waitcnt lgkmcnt(0)
	v_add_f32_e32 v60, v60, v76
	s_nop 1
	v_mov_b32_dpp v76, v60 quad_perm:[2,3,0,1] row_mask:0xf bank_mask:0xf
	s_waitcnt lgkmcnt(0)
	v_add_f32_e32 v60, v60, v76
	s_nop 1
	v_mov_b32_dpp v76, v60 row_half_mirror row_mask:0xf bank_mask:0xf
	s_waitcnt lgkmcnt(0)
	v_add_f32_e32 v60, v60, v76
	s_nop 1
	v_mov_b32_dpp v76, v60 row_mirror row_mask:0xf bank_mask:0xf
	s_waitcnt lgkmcnt(0)
	v_add_f32_e32 v60, v60, v76
	v_mov_b32_e32 v76, v60
	s_nop 1
	v_permlane16_swap_b32 v60, v76
	s_waitcnt lgkmcnt(0)
	v_add_f32_e32 v60, v60, v76
	v_mov_b32_e32 v76, v60
	s_nop 1
	v_permlane32_swap_b32 v60, v76
	s_waitcnt lgkmcnt(0)
	v_add_f32_e32 v60, v60, v76
	v_fmamk_f32 v60, v60, 0x3a800000, v102
	v_mul_f32_e32 v76, 0x4b800000, v60
	v_cmp_gt_f32_e32 vcc, s84, v60
	s_nop 1
	v_cndmask_b32_e32 v60, v60, v76, vcc
	v_rsq_f32_e32 v60, v60
	v_lshl_add_u64 v[76:77], v[66:67], 0, s[0:1]
	s_mov_b64 s[0:1], 0x3800200
	v_mul_f32_e32 v78, 0x45800000, v60
	v_cndmask_b32_e32 v60, v60, v78, vcc
	v_pk_mul_f32 v[44:45], v[44:45], v[60:61] op_sel_hi:[1,0]
	v_pk_mul_f32 v[40:41], v[40:41], v[60:61] op_sel_hi:[1,0]
	v_pk_mul_f32 v[42:43], v[42:43], v[60:61] op_sel_hi:[1,0]
	v_pk_mul_f32 v[46:47], v[46:47], v[60:61] op_sel_hi:[1,0]
	v_pk_mul_f32 v[44:45], v[8:9], v[44:45]
	v_pk_mul_f32 v[42:43], v[6:7], v[42:43]
	v_pk_mul_f32 v[40:41], v[4:5], v[40:41]
	v_pk_mul_f32 v[36:37], v[36:37], v[60:61] op_sel_hi:[1,0]
	v_pk_mul_f32 v[38:39], v[38:39], v[60:61] op_sel_hi:[1,0]
	v_pk_mul_f32 v[46:47], v[10:11], v[46:47]
	v_cvt_pk_bf16_f32 v44, v44, v45
	v_pk_mul_f32 v[38:39], v[26:27], v[38:39]
	v_cvt_pk_bf16_f32 v45, v46, v47
	v_pk_mul_f32 v[36:37], v[24:25], v[36:37]
	global_store_dwordx2 v[76:77], v[44:45], off sc0 sc1
	s_nop 1
	v_cvt_pk_bf16_f32 v40, v40, v41
	v_cvt_pk_bf16_f32 v41, v42, v43
	v_lshl_add_u64 v[42:43], v[66:67], 0, s[0:1]
	s_mov_b64 s[0:1], 0x3800400
	v_pk_mul_f32 v[32:33], v[32:33], v[60:61] op_sel_hi:[1,0]
	v_pk_mul_f32 v[34:35], v[34:35], v[60:61] op_sel_hi:[1,0]
	global_store_dwordx2 v[42:43], v[40:41], off sc0 sc1
	s_nop 1
	v_cvt_pk_bf16_f32 v36, v36, v37
	v_cvt_pk_bf16_f32 v37, v38, v39
	v_lshl_add_u64 v[38:39], v[66:67], 0, s[0:1]
	v_pk_mul_f32 v[34:35], v[22:23], v[34:35]
	v_pk_mul_f32 v[32:33], v[20:21], v[32:33]
	s_mov_b64 s[0:1], 0x3800600
	global_store_dwordx2 v[38:39], v[36:37], off sc0 sc1
	s_nop 1
	v_cvt_pk_bf16_f32 v32, v32, v33
	v_cvt_pk_bf16_f32 v33, v34, v35
	v_lshl_add_u64 v[34:35], v[66:67], 0, s[0:1]
	global_store_dwordx2 v[34:35], v[32:33], off sc0 sc1
	s_nop 1

.LBB0_832:
	s_lshl_b64 s[0:1], s[38:39], 12
	s_add_u32 s0, s36, s0
	s_addc_u32 s1, s37, s1
	v_lshl_add_u64 v[32:33], s[0:1], 0, v[50:51]
	global_load_dwordx4 v[44:47], v[32:33], off
	global_load_dwordx4 v[40:43], v[32:33], off offset:1024
	global_load_dwordx4 v[36:39], v[32:33], off offset:2048
	s_nop 0
	global_load_dwordx4 v[32:35], v[32:33], off offset:3072
	s_nop 0
	global_load_dwordx2 v[82:83], v[70:71], off offset:2048
	global_load_dwordx2 v[88:89], v[70:71], off offset:2560
	global_load_dwordx2 v[80:81], v[70:71], off offset:3072
	s_nop 0
	global_load_dwordx2 v[70:71], v[70:71], off offset:3584
	s_nop 0
	global_load_dwordx2 v[90:91], v[72:73], off offset:2048
	global_load_dwordx2 v[96:97], v[72:73], off offset:2560
	global_load_dwordx2 v[84:85], v[72:73], off offset:3072
	s_nop 0
	global_load_dwordx2 v[72:73], v[72:73], off offset:3584
	s_nop 0
	global_load_dwordx2 v[98:99], v[74:75], off offset:2048
	global_load_dwordx2 v[100:101], v[74:75], off offset:2560
	global_load_dwordx2 v[86:87], v[74:75], off offset:3072
	s_nop 0
	global_load_dwordx2 v[74:75], v[74:75], off offset:3584
	s_nop 0
	global_load_dwordx2 v[106:107], v[68:69], off offset:2048
	global_load_dwordx2 v[108:109], v[68:69], off offset:2560
	global_load_dwordx2 v[94:95], v[68:69], off offset:3072
	global_load_dwordx2 v[92:93], v[68:69], off offset:3584
	s_lshl_b64 s[0:1], s[6:7], 12
	s_add_u32 s0, s8, s0
	s_addc_u32 s1, s9, s1
	s_lshl_b64 s[6:7], s[50:51], 12
	s_add_u32 s6, s40, s6
	s_addc_u32 s7, s41, s7
	v_lshl_add_u64 v[76:77], v[48:49], 3, s[6:7]
	s_waitcnt vmcnt(15)
	v_lshlrev_b32_e32 v68, 16, v82
	v_and_b32_e32 v69, 0xffff0000, v82
	v_pk_add_f32 v[68:69], v[68:69], 0 op_sel_hi:[1,0]
	s_waitcnt vmcnt(11)
	v_lshlrev_b32_e32 v78, 16, v90
	v_and_b32_e32 v79, 0xffff0000, v90
	v_pk_add_f32 v[68:69], v[68:69], v[78:79]
	v_lshlrev_b32_e32 v82, 16, v91
	s_waitcnt vmcnt(7)
	v_lshlrev_b32_e32 v78, 16, v98
	v_and_b32_e32 v79, 0xffff0000, v98
	v_pk_add_f32 v[68:69], v[68:69], v[78:79]
	s_waitcnt vmcnt(3)
	v_lshlrev_b32_e32 v78, 16, v106
	v_and_b32_e32 v79, 0xffff0000, v106
	v_pk_add_f32 v[78:79], v[68:69], v[78:79]
	v_lshlrev_b32_e32 v68, 16, v83
	v_and_b32_e32 v69, 0xffff0000, v83
	v_pk_add_f32 v[68:69], v[68:69], 0 op_sel_hi:[1,0]
	v_and_b32_e32 v83, 0xffff0000, v91
	v_pk_add_f32 v[68:69], v[68:69], v[82:83]
	v_lshlrev_b32_e32 v82, 16, v99
	v_and_b32_e32 v83, 0xffff0000, v99
	v_pk_add_f32 v[68:69], v[68:69], v[82:83]
	v_lshlrev_b32_e32 v82, 16, v107
	v_and_b32_e32 v83, 0xffff0000, v107
	v_pk_add_f32 v[90:91], v[68:69], v[82:83]
	v_lshlrev_b32_e32 v68, 16, v88
	v_and_b32_e32 v69, 0xffff0000, v88
	v_pk_add_f32 v[68:69], v[68:69], 0 op_sel_hi:[1,0]
	v_lshlrev_b32_e32 v82, 16, v96
	v_and_b32_e32 v83, 0xffff0000, v96
	v_pk_add_f32 v[68:69], v[68:69], v[82:83]
	v_lshlrev_b32_e32 v82, 16, v100
	v_and_b32_e32 v83, 0xffff0000, v100
	v_pk_add_f32 v[68:69], v[68:69], v[82:83]
	s_waitcnt vmcnt(2)
	v_lshlrev_b32_e32 v82, 16, v108
	v_and_b32_e32 v83, 0xffff0000, v108
	v_pk_add_f32 v[68:69], v[68:69], v[82:83]
	v_lshlrev_b32_e32 v82, 16, v89
	v_and_b32_e32 v83, 0xffff0000, v89
	v_pk_add_f32 v[82:83], v[82:83], 0 op_sel_hi:[1,0]
	v_lshlrev_b32_e32 v88, 16, v97
	v_and_b32_e32 v89, 0xffff0000, v97
	v_pk_add_f32 v[82:83], v[82:83], v[88:89]
	v_lshlrev_b32_e32 v88, 16, v101
	v_and_b32_e32 v89, 0xffff0000, v101
	v_pk_add_f32 v[82:83], v[82:83], v[88:89]
	v_lshlrev_b32_e32 v88, 16, v109
	v_and_b32_e32 v89, 0xffff0000, v109
	v_pk_add_f32 v[88:89], v[82:83], v[88:89]
	v_lshlrev_b32_e32 v82, 16, v80
	v_and_b32_e32 v83, 0xffff0000, v80
	v_lshlrev_b32_e32 v80, 16, v81
	v_and_b32_e32 v81, 0xffff0000, v81
	v_lshlrev_b32_e32 v96, 16, v84
	v_and_b32_e32 v97, 0xffff0000, v84
	v_pk_add_f32 v[80:81], v[80:81], 0 op_sel_hi:[1,0]
	v_lshlrev_b32_e32 v84, 16, v85
	v_and_b32_e32 v85, 0xffff0000, v85
	v_pk_add_f32 v[80:81], v[80:81], v[84:85]
	v_lshlrev_b32_e32 v84, 16, v87
	v_and_b32_e32 v85, 0xffff0000, v87
	v_pk_add_f32 v[80:81], v[80:81], v[84:85]
	s_waitcnt vmcnt(1)
	v_lshlrev_b32_e32 v84, 16, v95
	v_and_b32_e32 v85, 0xffff0000, v95
	v_pk_add_f32 v[82:83], v[82:83], 0 op_sel_hi:[1,0]
	v_pk_add_f32 v[84:85], v[80:81], v[84:85]
	v_lshlrev_b32_e32 v80, 16, v70
	v_and_b32_e32 v81, 0xffff0000, v70
	v_lshlrev_b32_e32 v70, 16, v71
	v_and_b32_e32 v71, 0xffff0000, v71
	v_pk_add_f32 v[82:83], v[82:83], v[96:97]
	v_lshlrev_b32_e32 v96, 16, v86
	v_and_b32_e32 v97, 0xffff0000, v86
	v_pk_add_f32 v[80:81], v[80:81], 0 op_sel_hi:[1,0]
	v_lshlrev_b32_e32 v86, 16, v72
	v_and_b32_e32 v87, 0xffff0000, v72
	v_pk_add_f32 v[70:71], v[70:71], 0 op_sel_hi:[1,0]
	v_lshlrev_b32_e32 v72, 16, v73
	v_and_b32_e32 v73, 0xffff0000, v73
	v_pk_add_f32 v[80:81], v[80:81], v[86:87]
	v_lshlrev_b32_e32 v86, 16, v74
	v_and_b32_e32 v87, 0xffff0000, v74
	v_pk_add_f32 v[70:71], v[70:71], v[72:73]
	v_lshlrev_b32_e32 v72, 16, v75
	v_and_b32_e32 v73, 0xffff0000, v75
	v_pk_add_f32 v[82:83], v[82:83], v[96:97]
	v_lshlrev_b32_e32 v96, 16, v94
	v_and_b32_e32 v97, 0xffff0000, v94
	v_pk_add_f32 v[80:81], v[80:81], v[86:87]
	s_waitcnt vmcnt(0)
	v_lshlrev_b32_e32 v86, 16, v92
	v_and_b32_e32 v87, 0xffff0000, v92
	v_pk_add_f32 v[70:71], v[70:71], v[72:73]
	v_lshlrev_b32_e32 v72, 16, v93
	v_and_b32_e32 v73, 0xffff0000, v93
	v_mov_b32_e32 v74, v79
	v_mov_b32_e32 v75, v91
	v_pk_add_f32 v[82:83], v[82:83], v[96:97]
	v_pk_add_f32 v[80:81], v[80:81], v[86:87]
	v_pk_add_f32 v[70:71], v[70:71], v[72:73]
	v_mov_b32_e32 v72, v78
	v_mov_b32_e32 v73, v90
	v_pk_mul_f32 v[74:75], v[74:75], v[74:75]
	v_mov_b32_e32 v86, v69
	v_mov_b32_e32 v87, v89
	v_pk_fma_f32 v[72:73], v[72:73], v[72:73], v[74:75]
	v_mov_b32_e32 v74, v68
	v_mov_b32_e32 v75, v88
	v_pk_mul_f32 v[86:87], v[86:87], v[86:87]
	v_mul_f32_e32 v60, v83, v83
	v_pk_fma_f32 v[74:75], v[74:75], v[74:75], v[86:87]
	v_pk_fma_f32 v[86:87], v[82:83], v[82:83], v[60:61] op_sel_hi:[1,1,0]
	v_mul_f32_e32 v60, v85, v85
	v_pk_add_f32 v[72:73], v[72:73], v[72:73] op_sel:[0,1] op_sel_hi:[1,0]
	v_pk_add_f32 v[74:75], v[74:75], v[74:75] op_sel:[0,1] op_sel_hi:[1,0]
	v_pk_fma_f32 v[92:93], v[84:85], v[84:85], v[60:61] op_sel_hi:[1,1,0]
	v_pk_mul_f32 v[94:95], v[80:81], v[80:81]
	v_pk_mul_f32 v[96:97], v[70:71], v[70:71]
	v_mov_b32_e32 v73, v94
	v_mov_b32_e32 v75, v95
	v_mov_b32_e32 v87, v96
	v_mov_b32_e32 v93, v97
	v_pk_add_f32 v[72:73], v[72:73], v[74:75]
	v_pk_add_f32 v[74:75], v[86:87], v[92:93]
	s_nop 0
	v_pk_add_f32 v[72:73], v[72:73], v[74:75]
	s_nop 0
	v_add_f32_e32 v60, v72, v73
	s_nop 1
	v_mov_b32_dpp v72, v60 quad_perm:[1,0,3,2] row_mask:0xf bank_mask:0xf
	s_waitcnt lgkmcnt(0)
	v_add_f32_e32 v60, v60, v72
	s_nop 1
	v_mov_b32_dpp v72, v60 quad_perm:[2,3,0,1] row_mask:0xf bank_mask:0xf
	s_waitcnt lgkmcnt(0)
	v_add_f32_e32 v60, v60, v72
	s_nop 1
	v_mov_b32_dpp v72, v60 row_half_mirror row_mask:0xf bank_mask:0xf
	s_waitcnt lgkmcnt(0)
	v_add_f32_e32 v60, v60, v72
	s_nop 1
	v_mov_b32_dpp v72, v60 row_mirror row_mask:0xf bank_mask:0xf
	s_waitcnt lgkmcnt(0)
	v_add_f32_e32 v60, v60, v72
	v_mov_b32_e32 v72, v60
	s_nop 1
	v_permlane16_swap_b32 v60, v72
	s_waitcnt lgkmcnt(0)
	v_add_f32_e32 v60, v60, v72
	v_mov_b32_e32 v72, v60
	s_nop 1
	v_permlane32_swap_b32 v60, v72
	s_waitcnt lgkmcnt(0)
	v_add_f32_e32 v60, v60, v72
	v_fmamk_f32 v60, v60, 0x3a800000, v102
	v_cmp_gt_f32_e32 vcc, s84, v60
	v_mul_f32_e32 v72, 0x4b800000, v60
	s_nop 0
	v_cndmask_b32_e32 v60, v60, v72, vcc
	v_rsq_f32_e32 v60, v60
	s_nop 0
	v_mul_f32_e32 v72, 0x45800000, v60
	v_cndmask_b32_e32 v72, v60, v72, vcc
	v_pk_mul_f32 v[74:75], v[90:91], v[72:73] op_sel_hi:[1,0]
	v_pk_mul_f32 v[78:79], v[78:79], v[72:73] op_sel_hi:[1,0]
	v_pk_fma_f32 v[46:47], v[2:3], v[74:75], v[46:47]
	v_pk_fma_f32 v[44:45], v[0:1], v[78:79], v[44:45]
	s_and_b64 vcc, exec, s[10:11]
	s_cbranch_vccnz .LBB0_846
	v_lshl_add_u64 v[74:75], v[76:77], 0, s[70:71]
	v_cvt_pk_bf16_f32 v78, v44, v45
	v_cvt_pk_bf16_f32 v79, v46, v47
	s_nop 0
	global_store_dwordx2 v[74:75], v[78:79], off sc0 sc1
	s_nop 1
	v_lshl_add_u64 v[74:75], s[0:1], 0, v[50:51]
	s_cbranch_execnz .LBB0_835

.LBB0_844:
	s_and_b64 vcc, exec, s[10:11]
	s_cbranch_vccnz .LBB0_771
	v_mul_f32_e32 v60, v44, v44
	v_mul_f32_e32 v68, v46, v46
	v_fmac_f32_e32 v60, v45, v45
	v_fmac_f32_e32 v68, v47, v47
	v_add_f32_e32 v60, v68, v60
	v_mul_f32_e32 v68, v40, v40
	v_mul_f32_e32 v69, v43, v43
	v_fmac_f32_e32 v68, v41, v41
	v_fmac_f32_e32 v69, v42, v42
	v_add_f32_e32 v68, v69, v68
	v_add_f32_e32 v60, v60, v68
	v_mul_f32_e32 v68, v36, v36
	v_mul_f32_e32 v69, v39, v39
	v_fmac_f32_e32 v68, v37, v37
	v_fmac_f32_e32 v69, v38, v38
	v_add_f32_e32 v68, v69, v68
	v_add_f32_e32 v60, v60, v68
	v_mov_b32_e32 v68, v35
	v_mov_b32_e32 v69, v32
	v_pk_mul_f32 v[68:69], v[68:69], v[68:69]
	v_mov_b32_e32 v70, v34
	v_mov_b32_e32 v71, v33
	v_pk_fma_f32 v[68:69], v[70:71], v[70:71], v[68:69]
	s_mov_b64 s[0:1], 0x3800800
	v_add_f32_e32 v68, v68, v69
	v_add_f32_e32 v60, v60, v68
	s_nop 1
	v_mov_b32_dpp v68, v60 quad_perm:[1,0,3,2] row_mask:0xf bank_mask:0xf
	s_waitcnt lgkmcnt(0)
	v_add_f32_e32 v60, v60, v68
	s_nop 1
	v_mov_b32_dpp v68, v60 quad_perm:[2,3,0,1] row_mask:0xf bank_mask:0xf
	s_waitcnt lgkmcnt(0)
	v_add_f32_e32 v60, v60, v68
	s_nop 1
	v_mov_b32_dpp v68, v60 row_half_mirror row_mask:0xf bank_mask:0xf
	s_waitcnt lgkmcnt(0)
	v_add_f32_e32 v60, v60, v68
	s_nop 1
	v_mov_b32_dpp v68, v60 row_mirror row_mask:0xf bank_mask:0xf
	s_waitcnt lgkmcnt(0)
	v_add_f32_e32 v60, v60, v68
	v_mov_b32_e32 v68, v60
	s_nop 1
	v_permlane16_swap_b32 v60, v68
	s_waitcnt lgkmcnt(0)
	v_add_f32_e32 v60, v60, v68
	v_mov_b32_e32 v68, v60
	s_nop 1
	v_permlane32_swap_b32 v60, v68
	s_waitcnt lgkmcnt(0)
	v_add_f32_e32 v60, v60, v68
	v_fmamk_f32 v60, v60, 0x3a800000, v102
	v_mul_f32_e32 v68, 0x4b800000, v60
	v_cmp_gt_f32_e32 vcc, s84, v60
	s_nop 1
	v_cndmask_b32_e32 v60, v60, v68, vcc
	v_rsq_f32_e32 v60, v60
	v_lshl_add_u64 v[68:69], v[66:67], 0, s[0:1]
	s_mov_b64 s[0:1], 0x3800a00
	v_mul_f32_e32 v70, 0x45800000, v60
	v_cndmask_b32_e32 v60, v60, v70, vcc
	v_pk_mul_f32 v[44:45], v[44:45], v[60:61] op_sel_hi:[1,0]
	v_pk_mul_f32 v[40:41], v[40:41], v[60:61] op_sel_hi:[1,0]
	v_pk_mul_f32 v[42:43], v[42:43], v[60:61] op_sel_hi:[1,0]
	v_pk_mul_f32 v[46:47], v[46:47], v[60:61] op_sel_hi:[1,0]
	v_pk_mul_f32 v[44:45], v[8:9], v[44:45]
	v_pk_mul_f32 v[42:43], v[6:7], v[42:43]
	v_pk_mul_f32 v[40:41], v[4:5], v[40:41]
	v_pk_mul_f32 v[36:37], v[36:37], v[60:61] op_sel_hi:[1,0]
	v_pk_mul_f32 v[38:39], v[38:39], v[60:61] op_sel_hi:[1,0]
	v_pk_mul_f32 v[46:47], v[10:11], v[46:47]
	v_cvt_pk_bf16_f32 v44, v44, v45
	v_pk_mul_f32 v[38:39], v[26:27], v[38:39]
	v_cvt_pk_bf16_f32 v45, v46, v47
	v_pk_mul_f32 v[36:37], v[24:25], v[36:37]
	global_store_dwordx2 v[68:69], v[44:45], off sc0 sc1
	s_nop 1
	v_cvt_pk_bf16_f32 v40, v40, v41
	v_cvt_pk_bf16_f32 v41, v42, v43
	v_lshl_add_u64 v[42:43], v[66:67], 0, s[0:1]
	s_mov_b64 s[0:1], 0x3800c00
	v_pk_mul_f32 v[32:33], v[32:33], v[60:61] op_sel_hi:[1,0]
	v_pk_mul_f32 v[34:35], v[34:35], v[60:61] op_sel_hi:[1,0]
	global_store_dwordx2 v[42:43], v[40:41], off sc0 sc1
	s_nop 1
	v_cvt_pk_bf16_f32 v36, v36, v37
	v_cvt_pk_bf16_f32 v37, v38, v39
	v_lshl_add_u64 v[38:39], v[66:67], 0, s[0:1]
	v_pk_mul_f32 v[34:35], v[22:23], v[34:35]
	v_pk_mul_f32 v[32:33], v[20:21], v[32:33]
	s_mov_b64 s[0:1], 0x3800e00
	global_store_dwordx2 v[38:39], v[36:37], off sc0 sc1
	s_nop 1
	v_cvt_pk_bf16_f32 v32, v32, v33
	v_cvt_pk_bf16_f32 v33, v34, v35
	v_lshl_add_u64 v[34:35], v[66:67], 0, s[0:1]
	global_store_dwordx2 v[34:35], v[32:33], off sc0 sc1
	s_nop 1
	s_branch .LBB0_771

.LBB0_875:
	s_or_b64 exec, exec, s[48:49]
	s_lshl_b64 s[16:17], s[38:39], 12
	s_add_u32 s16, s40, s16
	s_addc_u32 s17, s41, s17
	s_lshl_b64 s[18:19], s[86:87], 11
	v_lshl_add_u64 v[34:35], v[56:57], 0, s[18:19]
	global_load_dwordx2 v[68:69], v[34:35], off
	s_lshl_b64 s[18:19], s[36:37], 12
	s_add_u32 s8, s8, s18
	s_addc_u32 s9, s9, s19
	v_lshl_add_u64 v[44:45], s[8:9], 0, v[50:51]
	global_load_dwordx4 v[74:77], v[44:45], off
	global_load_dwordx4 v[36:39], v[44:45], off offset:1024
	global_load_dwordx2 v[72:73], v[34:35], off offset:512
	global_load_dwordx2 v[70:71], v[34:35], off offset:1024
	global_load_dwordx2 v[64:65], v[34:35], off offset:1536
	global_load_dwordx4 v[40:43], v[44:45], off offset:2048
	s_nop 0
	global_load_dwordx4 v[44:47], v[44:45], off offset:3072
	s_waitcnt vmcnt(8)
	s_nop 1
	v_mov_b32_dpp v33, v32 quad_perm:[1,0,3,2] row_mask:0xf bank_mask:0xf
	s_lshl_b64 s[8:9], s[0:1], 12
	s_add_u32 s6, s6, s8
	v_lshl_add_u64 v[62:63], v[48:49], 3, s[16:17]
	s_addc_u32 s7, s7, s9
	s_waitcnt lgkmcnt(0)
	v_add_f32_e32 v32, v32, v33
	s_nop 1
	v_mov_b32_dpp v33, v32 quad_perm:[2,3,0,1] row_mask:0xf bank_mask:0xf
	s_and_b64 vcc, exec, s[10:11]
	s_waitcnt lgkmcnt(0)
	v_add_f32_e32 v32, v32, v33
	s_nop 1
	v_mov_b32_dpp v33, v32 row_half_mirror row_mask:0xf bank_mask:0xf
	s_waitcnt lgkmcnt(0)
	v_add_f32_e32 v32, v32, v33
	s_nop 1
	v_mov_b32_dpp v33, v32 row_mirror row_mask:0xf bank_mask:0xf
	s_waitcnt lgkmcnt(0)
	v_add_f32_e32 v32, v32, v33
	v_mov_b32_e32 v33, v32
	s_nop 1
	v_permlane16_swap_b32 v32, v33
	s_waitcnt lgkmcnt(0)
	v_add_f32_e32 v32, v32, v33
	v_mov_b32_e32 v33, v32
	s_nop 1
	v_permlane32_swap_b32 v32, v33
	s_waitcnt lgkmcnt(0)
	v_add_f32_e32 v32, v32, v33
	v_fmamk_f32 v32, v32, 0x3a800000, v102
	v_mul_f32_e32 v33, 0x4b800000, v32
	v_cmp_gt_f32_e64 s[0:1], s84, v32
	s_waitcnt vmcnt(7)
	v_lshlrev_b32_e32 v34, 16, v69
	v_cndmask_b32_e64 v32, v32, v33, s[0:1]
	v_rsq_f32_e32 v32, v32
	v_and_b32_e32 v35, 0xffff0000, v69
	v_mul_f32_e32 v33, 0x45800000, v32
	v_cndmask_b32_e64 v66, v32, v33, s[0:1]
	v_lshlrev_b32_e32 v32, 16, v68
	v_and_b32_e32 v33, 0xffff0000, v68
	v_pk_mul_f32 v[34:35], v[66:67], v[34:35] op_sel_hi:[0,1]
	v_pk_mul_f32 v[32:33], v[66:67], v[32:33] op_sel_hi:[0,1]
	s_waitcnt vmcnt(6)
	v_pk_fma_f32 v[32:33], v[0:1], v[32:33], v[74:75]
	v_pk_fma_f32 v[34:35], v[2:3], v[34:35], v[76:77]
	s_cbranch_vccnz .LBB0_901
	v_lshl_add_u64 v[68:69], v[62:63], 0, s[70:71]
	v_cvt_pk_bf16_f32 v74, v32, v33
	v_cvt_pk_bf16_f32 v75, v34, v35
	s_nop 0
	global_store_dwordx2 v[68:69], v[74:75], off sc0 sc1
	s_nop 1
	v_lshl_add_u64 v[68:69], s[6:7], 0, v[50:51]
	s_cbranch_execnz .LBB0_878

.LBB0_887:
	s_and_b64 vcc, exec, s[10:11]
	s_cbranch_vccnz .LBB0_889
	v_mul_f32_e32 v60, v32, v32
	v_mul_f32_e32 v62, v34, v34
	v_fmac_f32_e32 v60, v33, v33
	v_fmac_f32_e32 v62, v35, v35
	v_add_f32_e32 v60, v62, v60
	v_mul_f32_e32 v62, v36, v36
	v_mul_f32_e32 v63, v39, v39
	v_fmac_f32_e32 v62, v37, v37
	v_fmac_f32_e32 v63, v38, v38
	v_add_f32_e32 v62, v63, v62
	v_add_f32_e32 v60, v60, v62
	v_mul_f32_e32 v62, v40, v40
	v_mul_f32_e32 v63, v43, v43
	v_fmac_f32_e32 v62, v41, v41
	v_fmac_f32_e32 v63, v42, v42
	v_add_f32_e32 v62, v63, v62
	v_add_f32_e32 v60, v60, v62
	v_mov_b32_e32 v62, v47
	v_mov_b32_e32 v63, v44
	v_pk_mul_f32 v[62:63], v[62:63], v[62:63]
	v_mov_b32_e32 v64, v46
	v_mov_b32_e32 v65, v45
	v_pk_fma_f32 v[62:63], v[64:65], v[64:65], v[62:63]
	s_lshl_b64 s[0:1], s[86:87], 10
	v_add_f32_e32 v62, v62, v63
	v_add_f32_e32 v60, v60, v62
	s_nop 1
	v_mov_b32_dpp v62, v60 quad_perm:[1,0,3,2] row_mask:0xf bank_mask:0xf
	s_waitcnt lgkmcnt(0)
	v_add_f32_e32 v60, v60, v62
	s_nop 1
	v_mov_b32_dpp v62, v60 quad_perm:[2,3,0,1] row_mask:0xf bank_mask:0xf
	s_waitcnt lgkmcnt(0)
	v_add_f32_e32 v60, v60, v62
	s_nop 1
	v_mov_b32_dpp v62, v60 row_half_mirror row_mask:0xf bank_mask:0xf
	s_waitcnt lgkmcnt(0)
	v_add_f32_e32 v60, v60, v62
	s_nop 1
	v_mov_b32_dpp v62, v60 row_mirror row_mask:0xf bank_mask:0xf
	s_waitcnt lgkmcnt(0)
	v_add_f32_e32 v60, v60, v62
	v_mov_b32_e32 v62, v60
	s_nop 1
	v_permlane16_swap_b32 v60, v62
	s_waitcnt lgkmcnt(0)
	v_add_f32_e32 v60, v60, v62
	v_mov_b32_e32 v62, v60
	s_nop 1
	v_permlane32_swap_b32 v60, v62
	s_waitcnt lgkmcnt(0)
	v_add_f32_e32 v60, v60, v62
	v_fmamk_f32 v60, v60, 0x3a800000, v102
	v_cmp_gt_f32_e32 vcc, s84, v60
	v_mul_f32_e32 v62, 0x4b800000, v60
	s_nop 0
	v_cndmask_b32_e32 v60, v60, v62, vcc
	v_rsq_f32_e32 v60, v60
	s_nop 0
	v_mul_f32_e32 v62, 0x45800000, v60
	v_cndmask_b32_e32 v60, v60, v62, vcc
	v_pk_mul_f32 v[32:33], v[32:33], v[60:61] op_sel_hi:[1,0]
	v_pk_mul_f32 v[34:35], v[34:35], v[60:61] op_sel_hi:[1,0]
	v_pk_mul_f32 v[32:33], v[8:9], v[32:33]
	v_pk_mul_f32 v[34:35], v[10:11], v[34:35]
	v_cvt_pk_bf16_f32 v32, v32, v33
	v_lshl_add_u64 v[62:63], s[0:1], 1, v[54:55]
	v_cvt_pk_bf16_f32 v33, v34, v35
	v_pk_mul_f32 v[34:35], v[38:39], v[60:61] op_sel_hi:[1,0]
	global_store_dwordx2 v[62:63], v[32:33], off sc0 sc1
	s_nop 1
	v_pk_mul_f32 v[32:33], v[36:37], v[60:61] op_sel_hi:[1,0]
	v_pk_mul_f32 v[34:35], v[6:7], v[34:35]
	v_pk_mul_f32 v[32:33], v[4:5], v[32:33]
	s_mov_b64 s[0:1], 0x600
	v_cvt_pk_bf16_f32 v32, v32, v33
	v_cvt_pk_bf16_f32 v33, v34, v35
	v_lshl_add_u64 v[34:35], v[62:63], 0, s[42:43]
	global_store_dwordx2 v[34:35], v[32:33], off sc0 sc1
	s_nop 1
	v_pk_mul_f32 v[32:33], v[40:41], v[60:61] op_sel_hi:[1,0]
	v_pk_mul_f32 v[34:35], v[42:43], v[60:61] op_sel_hi:[1,0]
	v_pk_mul_f32 v[32:33], v[24:25], v[32:33]
	v_pk_mul_f32 v[34:35], v[26:27], v[34:35]
	v_cvt_pk_bf16_f32 v32, v32, v33
	s_nop 0
	v_cvt_pk_bf16_f32 v33, v34, v35
	v_lshl_add_u64 v[34:35], v[62:63], 0, s[28:29]
	global_store_dwordx2 v[34:35], v[32:33], off sc0 sc1
	s_nop 1
	v_pk_mul_f32 v[32:33], v[44:45], v[60:61] op_sel_hi:[1,0]
	v_pk_mul_f32 v[34:35], v[46:47], v[60:61] op_sel_hi:[1,0]
	v_pk_mul_f32 v[32:33], v[20:21], v[32:33]
	v_pk_mul_f32 v[34:35], v[22:23], v[34:35]
	v_cvt_pk_bf16_f32 v32, v32, v33
	s_nop 0
	v_cvt_pk_bf16_f32 v33, v34, v35
	v_lshl_add_u64 v[34:35], v[62:63], 0, s[0:1]
	global_store_dwordx2 v[34:35], v[32:33], off sc0 sc1
	s_nop 1

.LBB0_916:
	s_or_b64 exec, exec, s[48:49]
	s_lshl_b64 s[16:17], s[38:39], 12
	s_add_u32 s16, s40, s16
	s_addc_u32 s17, s41, s17
	s_lshl_b64 s[18:19], s[68:69], 11
	v_lshl_add_u64 v[34:35], v[56:57], 0, s[18:19]
	global_load_dwordx2 v[68:69], v[34:35], off
	s_lshl_b64 s[14:15], s[14:15], 12
	s_add_u32 s14, s36, s14
	s_addc_u32 s15, s37, s15
	v_lshl_add_u64 v[44:45], s[14:15], 0, v[50:51]
	global_load_dwordx4 v[74:77], v[44:45], off
	global_load_dwordx4 v[36:39], v[44:45], off offset:1024
	global_load_dwordx2 v[72:73], v[34:35], off offset:512
	global_load_dwordx2 v[70:71], v[34:35], off offset:1024
	global_load_dwordx2 v[64:65], v[34:35], off offset:1536
	global_load_dwordx4 v[40:43], v[44:45], off offset:2048
	s_nop 0
	global_load_dwordx4 v[44:47], v[44:45], off offset:3072
	s_waitcnt vmcnt(8)
	s_nop 1
	v_mov_b32_dpp v33, v32 quad_perm:[1,0,3,2] row_mask:0xf bank_mask:0xf
	s_lshl_b64 s[6:7], s[6:7], 12
	s_add_u32 s6, s8, s6
	v_lshl_add_u64 v[62:63], v[48:49], 3, s[16:17]
	s_addc_u32 s7, s9, s7
	s_waitcnt lgkmcnt(0)
	v_add_f32_e32 v32, v32, v33
	s_nop 1
	v_mov_b32_dpp v33, v32 quad_perm:[2,3,0,1] row_mask:0xf bank_mask:0xf
	s_and_b64 vcc, exec, s[10:11]
	s_waitcnt lgkmcnt(0)
	v_add_f32_e32 v32, v32, v33
	s_nop 1
	v_mov_b32_dpp v33, v32 row_half_mirror row_mask:0xf bank_mask:0xf
	s_waitcnt lgkmcnt(0)
	v_add_f32_e32 v32, v32, v33
	s_nop 1
	v_mov_b32_dpp v33, v32 row_mirror row_mask:0xf bank_mask:0xf
	s_waitcnt lgkmcnt(0)
	v_add_f32_e32 v32, v32, v33
	v_mov_b32_e32 v33, v32
	s_nop 1
	v_permlane16_swap_b32 v32, v33
	s_waitcnt lgkmcnt(0)
	v_add_f32_e32 v32, v32, v33
	v_mov_b32_e32 v33, v32
	s_nop 1
	v_permlane32_swap_b32 v32, v33
	s_waitcnt lgkmcnt(0)
	v_add_f32_e32 v32, v32, v33
	v_fmamk_f32 v32, v32, 0x3a800000, v102
	v_mul_f32_e32 v33, 0x4b800000, v32
	v_cmp_gt_f32_e64 s[14:15], s84, v32
	s_waitcnt vmcnt(7)
	v_lshlrev_b32_e32 v34, 16, v69
	v_cndmask_b32_e64 v32, v32, v33, s[14:15]
	v_rsq_f32_e32 v32, v32
	v_and_b32_e32 v35, 0xffff0000, v69
	v_mul_f32_e32 v33, 0x45800000, v32
	v_cndmask_b32_e64 v66, v32, v33, s[14:15]
	v_lshlrev_b32_e32 v32, 16, v68
	v_and_b32_e32 v33, 0xffff0000, v68
	v_pk_mul_f32 v[34:35], v[66:67], v[34:35] op_sel_hi:[0,1]
	v_pk_mul_f32 v[32:33], v[66:67], v[32:33] op_sel_hi:[0,1]
	s_waitcnt vmcnt(6)
	v_pk_fma_f32 v[32:33], v[0:1], v[32:33], v[74:75]
	v_pk_fma_f32 v[34:35], v[2:3], v[34:35], v[76:77]
	s_cbranch_vccnz .LBB0_942
	v_lshl_add_u64 v[68:69], v[62:63], 0, s[70:71]
	v_cvt_pk_bf16_f32 v74, v32, v33
	v_cvt_pk_bf16_f32 v75, v34, v35
	s_nop 0
	global_store_dwordx2 v[68:69], v[74:75], off sc0 sc1
	s_nop 1
	v_lshl_add_u64 v[68:69], s[6:7], 0, v[50:51]
	s_cbranch_execnz .LBB0_919

.LBB0_928:
	s_and_b64 vcc, exec, s[10:11]
	s_cbranch_vccnz .LBB0_930
	v_mul_f32_e32 v60, v32, v32
	v_mul_f32_e32 v62, v34, v34
	v_fmac_f32_e32 v60, v33, v33
	v_fmac_f32_e32 v62, v35, v35
	v_add_f32_e32 v60, v62, v60
	v_mul_f32_e32 v62, v36, v36
	v_mul_f32_e32 v63, v39, v39
	v_fmac_f32_e32 v62, v37, v37
	v_fmac_f32_e32 v63, v38, v38
	v_add_f32_e32 v62, v63, v62
	v_add_f32_e32 v60, v60, v62
	v_mul_f32_e32 v62, v40, v40
	v_mul_f32_e32 v63, v43, v43
	v_fmac_f32_e32 v62, v41, v41
	v_fmac_f32_e32 v63, v42, v42
	v_add_f32_e32 v62, v63, v62
	v_add_f32_e32 v60, v60, v62
	v_mov_b32_e32 v62, v47
	v_mov_b32_e32 v63, v44
	v_pk_mul_f32 v[62:63], v[62:63], v[62:63]
	v_mov_b32_e32 v64, v46
	v_mov_b32_e32 v65, v45
	v_pk_fma_f32 v[62:63], v[64:65], v[64:65], v[62:63]
	s_lshl_b64 s[6:7], s[68:69], 10
	v_add_f32_e32 v62, v62, v63
	v_add_f32_e32 v60, v60, v62
	s_nop 1
	v_mov_b32_dpp v62, v60 quad_perm:[1,0,3,2] row_mask:0xf bank_mask:0xf
	s_waitcnt lgkmcnt(0)
	v_add_f32_e32 v60, v60, v62
	s_nop 1
	v_mov_b32_dpp v62, v60 quad_perm:[2,3,0,1] row_mask:0xf bank_mask:0xf
	s_waitcnt lgkmcnt(0)
	v_add_f32_e32 v60, v60, v62
	s_nop 1
	v_mov_b32_dpp v62, v60 row_half_mirror row_mask:0xf bank_mask:0xf
	s_waitcnt lgkmcnt(0)
	v_add_f32_e32 v60, v60, v62
	s_nop 1
	v_mov_b32_dpp v62, v60 row_mirror row_mask:0xf bank_mask:0xf
	s_waitcnt lgkmcnt(0)
	v_add_f32_e32 v60, v60, v62
	v_mov_b32_e32 v62, v60
	s_nop 1
	v_permlane16_swap_b32 v60, v62
	s_waitcnt lgkmcnt(0)
	v_add_f32_e32 v60, v60, v62
	v_mov_b32_e32 v62, v60
	s_nop 1
	v_permlane32_swap_b32 v60, v62
	s_waitcnt lgkmcnt(0)
	v_add_f32_e32 v60, v60, v62
	v_fmamk_f32 v60, v60, 0x3a800000, v102
	v_cmp_gt_f32_e32 vcc, s84, v60
	v_mul_f32_e32 v62, 0x4b800000, v60
	s_nop 0
	v_cndmask_b32_e32 v60, v60, v62, vcc
	v_rsq_f32_e32 v60, v60
	s_nop 0
	v_mul_f32_e32 v62, 0x45800000, v60
	v_cndmask_b32_e32 v60, v60, v62, vcc
	v_pk_mul_f32 v[32:33], v[32:33], v[60:61] op_sel_hi:[1,0]
	v_pk_mul_f32 v[34:35], v[34:35], v[60:61] op_sel_hi:[1,0]
	v_pk_mul_f32 v[32:33], v[8:9], v[32:33]
	v_pk_mul_f32 v[34:35], v[10:11], v[34:35]
	v_cvt_pk_bf16_f32 v32, v32, v33
	v_lshl_add_u64 v[62:63], s[6:7], 1, v[54:55]
	v_cvt_pk_bf16_f32 v33, v34, v35
	v_pk_mul_f32 v[34:35], v[38:39], v[60:61] op_sel_hi:[1,0]
	global_store_dwordx2 v[62:63], v[32:33], off sc0 sc1
	s_nop 1
	v_pk_mul_f32 v[32:33], v[36:37], v[60:61] op_sel_hi:[1,0]
	v_pk_mul_f32 v[34:35], v[6:7], v[34:35]
	v_pk_mul_f32 v[32:33], v[4:5], v[32:33]
	s_mov_b64 s[6:7], 0x600
	v_cvt_pk_bf16_f32 v32, v32, v33
	v_cvt_pk_bf16_f32 v33, v34, v35
	v_lshl_add_u64 v[34:35], v[62:63], 0, s[42:43]
	global_store_dwordx2 v[34:35], v[32:33], off sc0 sc1
	s_nop 1
	v_pk_mul_f32 v[32:33], v[40:41], v[60:61] op_sel_hi:[1,0]
	v_pk_mul_f32 v[34:35], v[42:43], v[60:61] op_sel_hi:[1,0]
	v_pk_mul_f32 v[32:33], v[24:25], v[32:33]
	v_pk_mul_f32 v[34:35], v[26:27], v[34:35]
	v_cvt_pk_bf16_f32 v32, v32, v33
	s_nop 0
	v_cvt_pk_bf16_f32 v33, v34, v35
	v_lshl_add_u64 v[34:35], v[62:63], 0, s[28:29]
	global_store_dwordx2 v[34:35], v[32:33], off sc0 sc1
	s_nop 1
	v_pk_mul_f32 v[32:33], v[44:45], v[60:61] op_sel_hi:[1,0]
	v_pk_mul_f32 v[34:35], v[46:47], v[60:61] op_sel_hi:[1,0]
	v_pk_mul_f32 v[32:33], v[20:21], v[32:33]
	v_pk_mul_f32 v[34:35], v[22:23], v[34:35]
	v_cvt_pk_bf16_f32 v32, v32, v33
	s_nop 0
	v_cvt_pk_bf16_f32 v33, v34, v35
	v_lshl_add_u64 v[34:35], v[62:63], 0, s[6:7]
	global_store_dwordx2 v[34:35], v[32:33], off sc0 sc1
	s_nop 1

.LBB0_998:
	s_or_b64 exec, exec, s[40:41]
	s_lshl_b64 s[0:1], s[0:1], 12
	s_add_u32 s0, s38, s0
	s_addc_u32 s1, s39, s1
	s_lshl_b64 s[16:17], s[68:69], 11
	v_lshl_add_u64 v[34:35], v[56:57], 0, s[16:17]
	global_load_dwordx2 v[68:69], v[34:35], off
	s_lshl_b64 s[14:15], s[14:15], 12
	s_add_u32 s14, s36, s14
	s_addc_u32 s15, s37, s15
	v_lshl_add_u64 v[44:45], s[14:15], 0, v[50:51]
	global_load_dwordx4 v[74:77], v[44:45], off
	global_load_dwordx4 v[36:39], v[44:45], off offset:1024
	global_load_dwordx2 v[72:73], v[34:35], off offset:512
	global_load_dwordx2 v[70:71], v[34:35], off offset:1024
	global_load_dwordx2 v[64:65], v[34:35], off offset:1536
	global_load_dwordx4 v[40:43], v[44:45], off offset:2048
	s_nop 0
	global_load_dwordx4 v[44:47], v[44:45], off offset:3072
	s_waitcnt vmcnt(8)
	s_nop 1
	v_mov_b32_dpp v33, v32 quad_perm:[1,0,3,2] row_mask:0xf bank_mask:0xf
	v_lshl_add_u64 v[62:63], v[48:49], 3, s[0:1]
	s_lshl_b64 s[6:7], s[6:7], 12
	s_add_u32 s6, s8, s6
	s_addc_u32 s7, s9, s7
	s_waitcnt lgkmcnt(0)
	v_add_f32_e32 v32, v32, v33
	s_nop 1
	v_mov_b32_dpp v33, v32 quad_perm:[2,3,0,1] row_mask:0xf bank_mask:0xf
	s_and_b64 vcc, exec, s[10:11]
	s_waitcnt lgkmcnt(0)
	v_add_f32_e32 v32, v32, v33
	s_nop 1
	v_mov_b32_dpp v33, v32 row_half_mirror row_mask:0xf bank_mask:0xf
	s_waitcnt lgkmcnt(0)
	v_add_f32_e32 v32, v32, v33
	s_nop 1
	v_mov_b32_dpp v33, v32 row_mirror row_mask:0xf bank_mask:0xf
	s_waitcnt lgkmcnt(0)
	v_add_f32_e32 v32, v32, v33
	v_mov_b32_e32 v33, v32
	s_nop 1
	v_permlane16_swap_b32 v32, v33
	s_waitcnt lgkmcnt(0)
	v_add_f32_e32 v32, v32, v33
	v_mov_b32_e32 v33, v32
	s_nop 1
	v_permlane32_swap_b32 v32, v33
	s_waitcnt lgkmcnt(0)
	v_add_f32_e32 v32, v32, v33
	v_fmamk_f32 v32, v32, 0x3a800000, v102
	v_mul_f32_e32 v33, 0x4b800000, v32
	v_cmp_gt_f32_e64 s[0:1], s84, v32
	s_waitcnt vmcnt(7)
	v_lshlrev_b32_e32 v34, 16, v69
	v_cndmask_b32_e64 v32, v32, v33, s[0:1]
	v_rsq_f32_e32 v32, v32
	v_and_b32_e32 v35, 0xffff0000, v69
	v_mul_f32_e32 v33, 0x45800000, v32
	v_cndmask_b32_e64 v66, v32, v33, s[0:1]
	v_lshlrev_b32_e32 v32, 16, v68
	v_and_b32_e32 v33, 0xffff0000, v68
	v_pk_mul_f32 v[34:35], v[66:67], v[34:35] op_sel_hi:[0,1]
	v_pk_mul_f32 v[32:33], v[66:67], v[32:33] op_sel_hi:[0,1]
	s_waitcnt vmcnt(6)
	v_pk_fma_f32 v[32:33], v[0:1], v[32:33], v[74:75]
	v_pk_fma_f32 v[34:35], v[2:3], v[34:35], v[76:77]
	s_cbranch_vccnz .LBB0_1012
	v_lshl_add_u64 v[68:69], v[62:63], 0, s[70:71]
	v_cvt_pk_bf16_f32 v74, v32, v33
	v_cvt_pk_bf16_f32 v75, v34, v35
	s_nop 0
	global_store_dwordx2 v[68:69], v[74:75], off sc0 sc1
	s_nop 1
	v_lshl_add_u64 v[68:69], s[6:7], 0, v[50:51]
	s_cbranch_execnz .LBB0_1001

.LBB0_1010:
	s_and_b64 vcc, exec, s[10:11]
	s_cbranch_vccnz .LBB0_728
	v_mul_f32_e32 v60, v32, v32
	v_mul_f32_e32 v62, v34, v34
	v_fmac_f32_e32 v60, v33, v33
	v_fmac_f32_e32 v62, v35, v35
	v_add_f32_e32 v60, v62, v60
	v_mul_f32_e32 v62, v36, v36
	v_mul_f32_e32 v63, v39, v39
	v_fmac_f32_e32 v62, v37, v37
	v_fmac_f32_e32 v63, v38, v38
	v_add_f32_e32 v62, v63, v62
	v_add_f32_e32 v60, v60, v62
	v_mul_f32_e32 v62, v40, v40
	v_mul_f32_e32 v63, v43, v43
	v_fmac_f32_e32 v62, v41, v41
	v_fmac_f32_e32 v63, v42, v42
	v_add_f32_e32 v62, v63, v62
	v_add_f32_e32 v60, v60, v62
	v_mov_b32_e32 v62, v47
	v_mov_b32_e32 v63, v44
	v_pk_mul_f32 v[62:63], v[62:63], v[62:63]
	v_mov_b32_e32 v64, v46
	v_mov_b32_e32 v65, v45
	v_pk_fma_f32 v[62:63], v[64:65], v[64:65], v[62:63]
	s_lshl_b64 s[0:1], s[68:69], 10
	v_add_f32_e32 v62, v62, v63
	v_add_f32_e32 v60, v60, v62
	s_nop 1
	v_mov_b32_dpp v62, v60 quad_perm:[1,0,3,2] row_mask:0xf bank_mask:0xf
	s_waitcnt lgkmcnt(0)
	v_add_f32_e32 v60, v60, v62
	s_nop 1
	v_mov_b32_dpp v62, v60 quad_perm:[2,3,0,1] row_mask:0xf bank_mask:0xf
	s_waitcnt lgkmcnt(0)
	v_add_f32_e32 v60, v60, v62
	s_nop 1
	v_mov_b32_dpp v62, v60 row_half_mirror row_mask:0xf bank_mask:0xf
	s_waitcnt lgkmcnt(0)
	v_add_f32_e32 v60, v60, v62
	s_nop 1
	v_mov_b32_dpp v62, v60 row_mirror row_mask:0xf bank_mask:0xf
	s_waitcnt lgkmcnt(0)
	v_add_f32_e32 v60, v60, v62
	v_mov_b32_e32 v62, v60
	s_nop 1
	v_permlane16_swap_b32 v60, v62
	s_waitcnt lgkmcnt(0)
	v_add_f32_e32 v60, v60, v62
	v_mov_b32_e32 v62, v60
	s_nop 1
	v_permlane32_swap_b32 v60, v62
	s_waitcnt lgkmcnt(0)
	v_add_f32_e32 v60, v60, v62
	v_fmamk_f32 v60, v60, 0x3a800000, v102
	v_mul_f32_e32 v62, 0x4b800000, v60
	v_cmp_gt_f32_e32 vcc, s84, v60
	s_nop 1
	v_cndmask_b32_e32 v60, v60, v62, vcc
	v_rsq_f32_e32 v60, v60
	v_lshl_add_u64 v[62:63], s[0:1], 1, v[54:55]
	s_mov_b64 s[0:1], 0x600
	v_mul_f32_e32 v64, 0x45800000, v60
	v_cndmask_b32_e32 v60, v60, v64, vcc
	v_pk_mul_f32 v[32:33], v[32:33], v[60:61] op_sel_hi:[1,0]
	v_pk_mul_f32 v[34:35], v[34:35], v[60:61] op_sel_hi:[1,0]
	v_pk_mul_f32 v[32:33], v[8:9], v[32:33]
	v_pk_mul_f32 v[36:37], v[36:37], v[60:61] op_sel_hi:[1,0]
	v_pk_mul_f32 v[38:39], v[38:39], v[60:61] op_sel_hi:[1,0]
	v_pk_mul_f32 v[34:35], v[10:11], v[34:35]
	v_cvt_pk_bf16_f32 v32, v32, v33
	s_nop 0
	v_cvt_pk_bf16_f32 v33, v34, v35
	v_pk_mul_f32 v[34:35], v[4:5], v[36:37]
	global_store_dwordx2 v[62:63], v[32:33], off sc0 sc1
	s_nop 1
	v_pk_mul_f32 v[32:33], v[6:7], v[38:39]
	v_cvt_pk_bf16_f32 v34, v34, v35
	s_nop 0
	v_cvt_pk_bf16_f32 v35, v32, v33
	v_lshl_add_u64 v[32:33], v[62:63], 0, s[42:43]
	global_store_dwordx2 v[32:33], v[34:35], off sc0 sc1
	s_nop 1
	v_pk_mul_f32 v[32:33], v[40:41], v[60:61] op_sel_hi:[1,0]
	v_pk_mul_f32 v[34:35], v[42:43], v[60:61] op_sel_hi:[1,0]
	v_pk_mul_f32 v[32:33], v[24:25], v[32:33]
	v_pk_mul_f32 v[34:35], v[26:27], v[34:35]
	v_cvt_pk_bf16_f32 v32, v32, v33
	s_nop 0
	v_cvt_pk_bf16_f32 v33, v34, v35
	v_lshl_add_u64 v[34:35], v[62:63], 0, s[28:29]
	global_store_dwordx2 v[34:35], v[32:33], off sc0 sc1
	s_nop 1
	v_pk_mul_f32 v[32:33], v[44:45], v[60:61] op_sel_hi:[1,0]
	v_pk_mul_f32 v[34:35], v[46:47], v[60:61] op_sel_hi:[1,0]
	v_pk_mul_f32 v[32:33], v[20:21], v[32:33]
	v_pk_mul_f32 v[34:35], v[22:23], v[34:35]
	v_cvt_pk_bf16_f32 v32, v32, v33
	s_nop 0
	v_cvt_pk_bf16_f32 v33, v34, v35
	v_lshl_add_u64 v[34:35], v[62:63], 0, s[0:1]
	global_store_dwordx2 v[34:35], v[32:33], off sc0 sc1
	s_nop 1
	s_branch .LBB0_728

.LBB0_1351:
	s_or_b64 exec, exec, s[8:9]
	s_lshl_b64 s[0:1], s[0:1], 12
	s_add_u32 s0, s6, s0
	s_addc_u32 s1, s7, s1
	v_lshl_add_u64 v[44:45], v[32:33], 3, s[0:1]
	s_lshl_b64 s[0:1], s[56:57], 11
	v_lshl_add_u64 v[54:55], v[38:39], 0, s[0:1]
	global_load_dwordx2 v[46:47], v[44:45], off offset:2048
	global_load_dwordx2 v[48:49], v[44:45], off offset:2560
	global_load_dwordx2 v[50:51], v[44:45], off offset:3072
	global_load_dwordx2 v[52:53], v[44:45], off offset:3584
	global_load_dwordx2 v[56:57], v[54:55], off
	global_load_dwordx2 v[58:59], v[54:55], off offset:512
	global_load_dwordx2 v[60:61], v[54:55], off offset:1024
	s_nop 0
	global_load_dwordx2 v[54:55], v[54:55], off offset:1536
	s_waitcnt vmcnt(8)
	s_nop 1
	v_mov_b32_dpp v62, v42 quad_perm:[1,0,3,2] row_mask:0xf bank_mask:0xf
	s_waitcnt lgkmcnt(0)
	v_add_f32_e32 v42, v42, v62
	s_nop 1
	v_mov_b32_dpp v62, v42 quad_perm:[2,3,0,1] row_mask:0xf bank_mask:0xf
	s_waitcnt lgkmcnt(0)
	v_add_f32_e32 v42, v42, v62
	s_nop 1
	v_mov_b32_dpp v62, v42 row_half_mirror row_mask:0xf bank_mask:0xf
	s_waitcnt lgkmcnt(0)
	v_add_f32_e32 v42, v42, v62
	s_nop 1
	v_mov_b32_dpp v62, v42 row_mirror row_mask:0xf bank_mask:0xf
	s_waitcnt lgkmcnt(0)
	v_add_f32_e32 v42, v42, v62
	v_mov_b32_e32 v62, v42
	s_nop 1
	v_permlane16_swap_b32 v42, v62
	s_waitcnt lgkmcnt(0)
	v_add_f32_e32 v42, v42, v62
	v_mov_b32_e32 v62, v42
	s_nop 1
	v_permlane32_swap_b32 v42, v62
	s_waitcnt lgkmcnt(0)
	v_add_f32_e32 v42, v42, v62
	v_fmamk_f32 v42, v42, 0x3a800000, v146
	v_mul_f32_e32 v62, 0x4b800000, v42
	v_cmp_gt_f32_e32 vcc, s97, v42
	s_waitcnt vmcnt(7)
	v_and_b32_e32 v63, 0xffff0000, v46
	v_cndmask_b32_e32 v42, v42, v62, vcc
	v_rsq_f32_e32 v42, v42
	s_waitcnt vmcnt(3)
	v_lshlrev_b32_e32 v70, 16, v56
	v_and_b32_e32 v71, 0xffff0000, v56
	v_lshlrev_b32_e32 v56, 16, v57
	v_mul_f32_e32 v62, 0x45800000, v42
	v_cndmask_b32_e32 v42, v42, v62, vcc
	v_and_b32_e32 v57, 0xffff0000, v57
	s_waitcnt vmcnt(2)
	v_lshlrev_b32_e32 v72, 16, v58
	v_and_b32_e32 v73, 0xffff0000, v58
	v_lshlrev_b32_e32 v58, 16, v59
	v_and_b32_e32 v59, 0xffff0000, v59
	v_lshlrev_b32_e32 v62, 16, v46
	v_lshlrev_b32_e32 v46, 16, v47
	v_and_b32_e32 v47, 0xffff0000, v47
	v_lshlrev_b32_e32 v64, 16, v48
	v_and_b32_e32 v65, 0xffff0000, v48
	v_lshlrev_b32_e32 v48, 16, v49
	v_and_b32_e32 v49, 0xffff0000, v49
	s_waitcnt vmcnt(1)
	v_lshlrev_b32_e32 v74, 16, v60
	v_and_b32_e32 v75, 0xffff0000, v60
	v_lshlrev_b32_e32 v60, 16, v61
	v_and_b32_e32 v61, 0xffff0000, v61
	v_pk_mul_f32 v[70:71], v[42:43], v[70:71] op_sel_hi:[0,1]
	v_pk_mul_f32 v[56:57], v[42:43], v[56:57] op_sel_hi:[0,1]
	v_pk_mul_f32 v[58:59], v[42:43], v[58:59] op_sel_hi:[0,1]
	v_pk_mul_f32 v[72:73], v[42:43], v[72:73] op_sel_hi:[0,1]
	v_lshlrev_b32_e32 v66, 16, v50
	v_and_b32_e32 v67, 0xffff0000, v50
	v_lshlrev_b32_e32 v50, 16, v51
	v_and_b32_e32 v51, 0xffff0000, v51
	v_pk_mul_f32 v[60:61], v[42:43], v[60:61] op_sel_hi:[0,1]
	v_pk_mul_f32 v[74:75], v[42:43], v[74:75] op_sel_hi:[0,1]
	v_pk_fma_f32 v[46:47], v[2:3], v[56:57], v[46:47]
	v_pk_fma_f32 v[56:57], v[0:1], v[70:71], v[62:63]
	v_pk_fma_f32 v[62:63], v[4:5], v[72:73], v[64:65]
	v_pk_fma_f32 v[48:49], v[6:7], v[58:59], v[48:49]
	v_pk_fma_f32 v[58:59], v[16:17], v[74:75], v[66:67]
	v_pk_fma_f32 v[50:51], v[18:19], v[60:61], v[50:51]
	v_pk_mul_f32 v[60:61], v[46:47], v[46:47]
	v_pk_mul_f32 v[64:65], v[56:57], v[56:57]
	v_pk_mul_f32 v[66:67], v[48:49], v[48:49]
	v_pk_mul_f32 v[70:71], v[62:63], v[62:63]
	v_pk_mov_b32 v[74:75], v[64:65], v[60:61] op_sel:[1,0]
	v_mov_b32_e32 v65, v61
	v_pk_mov_b32 v[60:61], v[70:71], v[66:67] op_sel:[1,0]
	v_mov_b32_e32 v71, v67
	v_pk_add_f32 v[60:61], v[60:61], v[70:71]
	s_waitcnt vmcnt(0)
	v_lshlrev_b32_e32 v76, 16, v54
	v_and_b32_e32 v77, 0xffff0000, v54
	v_lshlrev_b32_e32 v54, 16, v55
	v_and_b32_e32 v55, 0xffff0000, v55
	v_mul_f32_e32 v72, v58, v58
	v_pk_add_f32 v[60:61], v[60:61], v[60:61] op_sel_hi:[0,1]
	v_lshlrev_b32_e32 v68, 16, v52
	v_and_b32_e32 v69, 0xffff0000, v52
	v_lshlrev_b32_e32 v52, 16, v53
	v_and_b32_e32 v53, 0xffff0000, v53
	v_pk_fma_f32 v[66:67], v[58:59], v[58:59], v[72:73] op_sel_hi:[1,1,0]
	v_pk_add_f32 v[64:65], v[74:75], v[64:65]
	v_mul_f32_e32 v60, v50, v50
	v_pk_mul_f32 v[54:55], v[42:43], v[54:55] op_sel_hi:[0,1]
	v_pk_mul_f32 v[72:73], v[42:43], v[76:77] op_sel_hi:[0,1]
	v_pk_add_f32 v[64:65], v[64:65], v[64:65] op_sel_hi:[0,1]
	v_pk_fma_f32 v[70:71], v[50:51], v[50:51], v[60:61] op_sel_hi:[1,1,0]
	v_pk_fma_f32 v[68:69], v[20:21], v[72:73], v[68:69]
	v_pk_fma_f32 v[52:53], v[22:23], v[54:55], v[52:53]
	v_mul_f32_e32 v66, v68, v68
	v_mul_f32_e32 v70, v69, v69
	v_mul_f32_e32 v64, v52, v52
	v_mul_f32_e32 v60, v53, v53
	v_pk_add_f32 v[54:55], v[66:67], v[70:71]
	v_pk_add_f32 v[60:61], v[64:65], v[60:61]
	v_cvt_pk_bf16_f32 v66, v56, v57
	v_lshl_add_u64 v[64:65], v[44:45], 0, s[68:69]
	v_pk_add_f32 v[54:55], v[54:55], v[60:61]
	s_nop 0
	v_add_f32_e32 v42, v54, v55
	s_nop 1
	v_mov_b32_dpp v54, v42 quad_perm:[1,0,3,2] row_mask:0xf bank_mask:0xf
	s_waitcnt lgkmcnt(0)
	v_add_f32_e32 v42, v42, v54
	s_nop 1
	v_mov_b32_dpp v54, v42 quad_perm:[2,3,0,1] row_mask:0xf bank_mask:0xf
	s_waitcnt lgkmcnt(0)
	v_add_f32_e32 v42, v42, v54
	s_nop 1
	v_mov_b32_dpp v60, v42 row_half_mirror row_mask:0xf bank_mask:0xf
	v_lshl_add_u64 v[54:55], v[44:45], 0, s[62:63]
	s_waitcnt lgkmcnt(0)
	v_add_f32_e32 v42, v42, v60
	s_nop 1
	v_mov_b32_dpp v67, v42 row_mirror row_mask:0xf bank_mask:0xf
	v_lshl_add_u64 v[60:61], v[44:45], 0, s[64:65]
	v_lshl_add_u64 v[44:45], v[44:45], 0, s[70:71]
	s_waitcnt lgkmcnt(0)
	v_add_f32_e32 v42, v42, v67
	v_mov_b32_e32 v70, v42
	s_nop 1
	v_permlane16_swap_b32 v42, v70
	v_cvt_pk_bf16_f32 v67, v46, v47
	s_waitcnt lgkmcnt(0)
	v_add_f32_e32 v42, v42, v70
	global_store_dwordx2 v[54:55], v[66:67], off sc0 sc1
	s_nop 1
	v_mov_b32_e32 v66, v42
	s_nop 1
	v_permlane32_swap_b32 v42, v66
	v_cvt_pk_bf16_f32 v54, v62, v63
	v_cvt_pk_bf16_f32 v55, v48, v49
	s_waitcnt lgkmcnt(0)
	v_add_f32_e32 v42, v42, v66
	global_store_dwordx2 v[60:61], v[54:55], off sc0 sc1
	s_nop 1
	v_cvt_pk_bf16_f32 v54, v58, v59
	v_fmamk_f32 v42, v42, 0x3a800000, v146
	v_cvt_pk_bf16_f32 v55, v50, v51
	v_cmp_gt_f32_e32 vcc, s97, v42
	global_store_dwordx2 v[64:65], v[54:55], off sc0 sc1
	s_nop 1
	v_mul_f32_e32 v54, 0x4b800000, v42
	s_nop 0
	v_cndmask_b32_e32 v42, v42, v54, vcc
	v_rsq_f32_e32 v42, v42
	v_cvt_pk_bf16_f32 v54, v68, v69
	v_cvt_pk_bf16_f32 v55, v52, v53
	s_nop 0
	global_store_dwordx2 v[44:45], v[54:55], off sc0 sc1
	s_nop 1
	v_mul_f32_e32 v44, 0x45800000, v42
	v_cndmask_b32_e32 v42, v42, v44, vcc
	v_pk_mul_f32 v[54:55], v[56:57], v[42:43] op_sel_hi:[1,0]
	v_pk_mul_f32 v[46:47], v[46:47], v[42:43] op_sel_hi:[1,0]
	v_pk_mul_f32 v[54:55], v[24:25], v[54:55]
	v_pk_mul_f32 v[46:47], v[26:27], v[46:47]
	v_cvt_pk_bf16_f32 v54, v54, v55
	v_pk_mul_f32 v[48:49], v[48:49], v[42:43] op_sel_hi:[1,0]
	v_cvt_pk_bf16_f32 v55, v46, v47
	v_pk_mul_f32 v[46:47], v[62:63], v[42:43] op_sel_hi:[1,0]
	v_lshl_add_u64 v[44:45], v[36:37], 0, s[0:1]
	v_pk_mul_f32 v[46:47], v[8:9], v[46:47]
	global_store_dwordx2 v[44:45], v[54:55], off sc0 sc1
	s_nop 1
	v_pk_mul_f32 v[48:49], v[10:11], v[48:49]
	v_cvt_pk_bf16_f32 v46, v46, v47
	s_nop 0
	v_cvt_pk_bf16_f32 v47, v48, v49
	v_lshl_add_u64 v[48:49], v[44:45], 0, s[72:73]
	global_store_dwordx2 v[48:49], v[46:47], off sc0 sc1
	s_nop 1
	v_pk_mul_f32 v[46:47], v[58:59], v[42:43] op_sel_hi:[1,0]
	v_pk_mul_f32 v[48:49], v[50:51], v[42:43] op_sel_hi:[1,0]
	v_pk_mul_f32 v[46:47], v[12:13], v[46:47]
	v_pk_mul_f32 v[48:49], v[14:15], v[48:49]
	v_cvt_pk_bf16_f32 v46, v46, v47
	s_nop 0
	v_cvt_pk_bf16_f32 v47, v48, v49
	v_lshl_add_u64 v[48:49], v[44:45], 0, s[74:75]
	global_store_dwordx2 v[48:49], v[46:47], off sc0 sc1
	s_nop 1
	v_pk_mul_f32 v[46:47], v[68:69], v[42:43] op_sel_hi:[1,0]
	v_pk_mul_f32 v[48:49], v[52:53], v[42:43] op_sel_hi:[1,0]
	v_pk_mul_f32 v[46:47], v[28:29], v[46:47]
	v_pk_mul_f32 v[48:49], v[30:31], v[48:49]
	v_cvt_pk_bf16_f32 v46, v46, v47
	v_lshl_add_u64 v[44:45], v[44:45], 0, s[78:79]
	v_cvt_pk_bf16_f32 v47, v48, v49
	s_nop 0
	global_store_dwordx2 v[44:45], v[46:47], off sc0 sc1
	s_nop 1

.LBB0_1395:
	global_load_dwordx2 v[76:77], v[50:51], off offset:2048
	global_load_dwordx2 v[78:79], v[50:51], off offset:2560
	global_load_dwordx2 v[80:81], v[50:51], off offset:3072
	global_load_dwordx2 v[82:83], v[50:51], off offset:3584
	global_load_dwordx2 v[88:89], v[52:53], off offset:2048
	global_load_dwordx2 v[96:97], v[52:53], off offset:2560
	global_load_dwordx2 v[106:107], v[52:53], off offset:3072
	global_load_dwordx2 v[108:109], v[52:53], off offset:3584
	global_load_dwordx2 v[118:119], v[54:55], off offset:2048
	global_load_dwordx2 v[122:123], v[54:55], off offset:2560
	global_load_dwordx2 v[124:125], v[54:55], off offset:3072
	global_load_dwordx2 v[126:127], v[54:55], off offset:3584
	global_load_dwordx2 v[128:129], v[56:57], off offset:2048
	global_load_dwordx2 v[110:111], v[56:57], off offset:2560
	global_load_dwordx2 v[84:85], v[56:57], off offset:3072
	global_load_dwordx2 v[72:73], v[56:57], off offset:3584
	global_load_dwordx2 v[130:131], v[58:59], off offset:2048
	global_load_dwordx2 v[114:115], v[58:59], off offset:2560
	global_load_dwordx2 v[86:87], v[58:59], off offset:3072
	global_load_dwordx2 v[74:75], v[58:59], off offset:3584
	global_load_dwordx2 v[132:133], v[60:61], off offset:2048
	global_load_dwordx2 v[120:121], v[60:61], off offset:2560
	global_load_dwordx2 v[90:91], v[60:61], off offset:3072
	s_nop 0
	global_load_dwordx2 v[60:61], v[60:61], off offset:3584
	s_nop 0
	global_load_dwordx2 v[134:135], v[62:63], off offset:2048
	global_load_dwordx2 v[136:137], v[62:63], off offset:2560
	global_load_dwordx2 v[92:93], v[62:63], off offset:3072
	s_nop 0
	global_load_dwordx2 v[62:63], v[62:63], off offset:3584
	s_nop 0
	global_load_dwordx2 v[138:139], v[64:65], off offset:2048
	global_load_dwordx2 v[140:141], v[64:65], off offset:2560
	global_load_dwordx2 v[94:95], v[64:65], off offset:3072
	s_nop 0
	global_load_dwordx2 v[64:65], v[64:65], off offset:3584
	s_nop 0
	global_load_dwordx2 v[142:143], v[66:67], off offset:2048
	global_load_dwordx2 v[144:145], v[66:67], off offset:2560
	global_load_dwordx2 v[98:99], v[66:67], off offset:3072
	s_nop 0
	global_load_dwordx2 v[66:67], v[66:67], off offset:3584
	s_nop 0
	global_load_dwordx2 v[156:157], v[68:69], off offset:2048
	global_load_dwordx2 v[158:159], v[68:69], off offset:2560
	global_load_dwordx2 v[100:101], v[68:69], off offset:3072
	s_nop 0
	global_load_dwordx2 v[68:69], v[68:69], off offset:3584
	s_nop 0
	global_load_dwordx2 v[160:161], v[70:71], off offset:2048
	global_load_dwordx2 v[162:163], v[70:71], off offset:2560
	global_load_dwordx2 v[102:103], v[70:71], off offset:3072
	s_nop 0
	global_load_dwordx2 v[70:71], v[70:71], off offset:3584
	s_lshl_b64 s[8:9], s[8:9], 12
	s_add_u32 s6, s6, s8
	s_addc_u32 s7, s7, s9
	v_lshl_add_u64 v[50:51], v[32:33], 3, s[6:7]
	global_load_dwordx2 v[58:59], v[50:51], off offset:2048
	global_load_dwordx2 v[56:57], v[50:51], off offset:2560
	global_load_dwordx2 v[54:55], v[50:51], off offset:3072
	global_load_dwordx2 v[52:53], v[50:51], off offset:3584
	s_mov_b64 s[6:7], 0x3800800
	s_add_u32 s82, s82, 0x1000
	s_addc_u32 s83, s83, 0
	s_add_i32 s12, s12, 2
	s_add_u32 s0, s0, 2
	s_addc_u32 s1, s1, 0
	s_add_i32 s3, s3, 2
	s_cmpk_lg_i32 s82, 0x2000
	s_waitcnt vmcnt(37)
	v_lshlrev_b32_e32 v184, 16, v124
	v_and_b32_e32 v185, 0xffff0000, v124
	v_lshlrev_b32_e32 v164, 16, v76
	v_and_b32_e32 v165, 0xffff0000, v76
	v_lshlrev_b32_e32 v166, 16, v77
	v_and_b32_e32 v167, 0xffff0000, v77
	v_lshlrev_b32_e32 v76, 16, v88
	v_and_b32_e32 v77, 0xffff0000, v88
	v_lshlrev_b32_e32 v174, 16, v96
	v_and_b32_e32 v175, 0xffff0000, v96
	v_lshlrev_b32_e32 v176, 16, v97
	v_and_b32_e32 v177, 0xffff0000, v97
	v_lshlrev_b32_e32 v96, 16, v118
	v_and_b32_e32 v97, 0xffff0000, v118
	v_lshlrev_b32_e32 v180, 16, v119
	v_and_b32_e32 v181, 0xffff0000, v119
	v_lshlrev_b32_e32 v118, 16, v125
	v_and_b32_e32 v119, 0xffff0000, v125
	v_pk_add_f32 v[124:125], v[164:165], 0 op_sel_hi:[1,0]
	v_lshlrev_b32_e32 v172, 16, v80
	v_pk_add_f32 v[76:77], v[124:125], v[76:77]
	v_and_b32_e32 v173, 0xffff0000, v80
	v_pk_add_f32 v[76:77], v[76:77], v[96:97]
	s_waitcnt vmcnt(35)
	v_lshlrev_b32_e32 v96, 16, v128
	v_and_b32_e32 v97, 0xffff0000, v128
	v_pk_add_f32 v[76:77], v[76:77], v[96:97]
	s_waitcnt vmcnt(31)
	v_lshlrev_b32_e32 v96, 16, v130
	v_and_b32_e32 v97, 0xffff0000, v130
	v_pk_add_f32 v[76:77], v[76:77], v[96:97]
	s_waitcnt vmcnt(27)
	v_lshlrev_b32_e32 v96, 16, v132
	v_and_b32_e32 v97, 0xffff0000, v132
	v_pk_add_f32 v[76:77], v[76:77], v[96:97]
	s_waitcnt vmcnt(23)
	v_lshlrev_b32_e32 v96, 16, v134
	v_and_b32_e32 v97, 0xffff0000, v134
	v_pk_add_f32 v[76:77], v[76:77], v[96:97]
	s_waitcnt vmcnt(19)
	v_lshlrev_b32_e32 v96, 16, v138
	v_and_b32_e32 v97, 0xffff0000, v138
	v_pk_add_f32 v[76:77], v[76:77], v[96:97]
	s_waitcnt vmcnt(15)
	v_lshlrev_b32_e32 v96, 16, v142
	v_and_b32_e32 v97, 0xffff0000, v142
	v_pk_add_f32 v[76:77], v[76:77], v[96:97]
	s_waitcnt vmcnt(11)
	v_lshlrev_b32_e32 v96, 16, v156
	v_and_b32_e32 v97, 0xffff0000, v156
	v_pk_add_f32 v[76:77], v[76:77], v[96:97]
	s_waitcnt vmcnt(7)
	v_lshlrev_b32_e32 v96, 16, v160
	v_and_b32_e32 v97, 0xffff0000, v160
	v_lshlrev_b32_e32 v112, 16, v81
	v_and_b32_e32 v113, 0xffff0000, v81
	v_lshlrev_b32_e32 v80, 16, v89
	v_and_b32_e32 v81, 0xffff0000, v89
	v_pk_add_f32 v[76:77], v[76:77], v[96:97]
	v_pk_add_f32 v[96:97], v[166:167], 0 op_sel_hi:[1,0]
	v_lshlrev_b32_e32 v168, 16, v78
	v_pk_add_f32 v[80:81], v[96:97], v[80:81]
	v_lshlrev_b32_e32 v96, 16, v129
	v_pk_add_f32 v[80:81], v[80:81], v[180:181]
	v_and_b32_e32 v97, 0xffff0000, v129
	v_pk_add_f32 v[80:81], v[80:81], v[96:97]
	v_lshlrev_b32_e32 v96, 16, v131
	v_and_b32_e32 v97, 0xffff0000, v131
	v_pk_add_f32 v[80:81], v[80:81], v[96:97]
	v_lshlrev_b32_e32 v96, 16, v133
	v_and_b32_e32 v97, 0xffff0000, v133
	v_pk_add_f32 v[80:81], v[80:81], v[96:97]
	v_lshlrev_b32_e32 v96, 16, v135
	v_and_b32_e32 v97, 0xffff0000, v135
	v_pk_add_f32 v[80:81], v[80:81], v[96:97]
	v_lshlrev_b32_e32 v96, 16, v139
	v_and_b32_e32 v97, 0xffff0000, v139
	v_pk_add_f32 v[80:81], v[80:81], v[96:97]
	v_lshlrev_b32_e32 v96, 16, v143
	v_and_b32_e32 v97, 0xffff0000, v143
	v_pk_add_f32 v[80:81], v[80:81], v[96:97]
	v_lshlrev_b32_e32 v96, 16, v157
	v_and_b32_e32 v97, 0xffff0000, v157
	v_and_b32_e32 v169, 0xffff0000, v78
	v_pk_add_f32 v[80:81], v[80:81], v[96:97]
	v_lshlrev_b32_e32 v96, 16, v161
	v_and_b32_e32 v97, 0xffff0000, v161
	v_pk_add_f32 v[80:81], v[80:81], v[96:97]
	v_pk_add_f32 v[96:97], v[168:169], 0 op_sel_hi:[1,0]
	v_lshlrev_b32_e32 v182, 16, v122
	v_and_b32_e32 v183, 0xffff0000, v122
	v_pk_add_f32 v[96:97], v[96:97], v[174:175]
	v_lshlrev_b32_e32 v124, 16, v110
	v_pk_add_f32 v[96:97], v[96:97], v[182:183]
	v_and_b32_e32 v125, 0xffff0000, v110
	v_pk_add_f32 v[96:97], v[96:97], v[124:125]
	v_lshlrev_b32_e32 v124, 16, v114
	v_and_b32_e32 v125, 0xffff0000, v114
	v_pk_add_f32 v[96:97], v[96:97], v[124:125]
	v_lshlrev_b32_e32 v124, 16, v120
	v_and_b32_e32 v125, 0xffff0000, v120
	v_pk_add_f32 v[96:97], v[96:97], v[124:125]
	v_lshlrev_b32_e32 v124, 16, v136
	v_and_b32_e32 v125, 0xffff0000, v136
	v_pk_add_f32 v[96:97], v[96:97], v[124:125]
	v_lshlrev_b32_e32 v124, 16, v140
	v_and_b32_e32 v125, 0xffff0000, v140
	v_pk_add_f32 v[96:97], v[96:97], v[124:125]
	v_lshlrev_b32_e32 v124, 16, v144
	v_and_b32_e32 v125, 0xffff0000, v144
	v_pk_add_f32 v[96:97], v[96:97], v[124:125]
	v_lshlrev_b32_e32 v124, 16, v158
	v_and_b32_e32 v125, 0xffff0000, v158
	v_lshlrev_b32_e32 v170, 16, v79
	v_and_b32_e32 v171, 0xffff0000, v79
	v_pk_add_f32 v[96:97], v[96:97], v[124:125]
	s_waitcnt vmcnt(6)
	v_lshlrev_b32_e32 v124, 16, v162
	v_and_b32_e32 v125, 0xffff0000, v162
	v_pk_add_f32 v[96:97], v[96:97], v[124:125]
	v_pk_add_f32 v[124:125], v[170:171], 0 op_sel_hi:[1,0]
	v_lshlrev_b32_e32 v122, 16, v123
	v_and_b32_e32 v123, 0xffff0000, v123
	v_pk_add_f32 v[124:125], v[124:125], v[176:177]
	v_lshlrev_b32_e32 v110, 16, v111
	v_pk_add_f32 v[122:123], v[124:125], v[122:123]
	v_and_b32_e32 v111, 0xffff0000, v111
	v_pk_add_f32 v[110:111], v[122:123], v[110:111]
	v_lshlrev_b32_e32 v114, 16, v115
	v_and_b32_e32 v115, 0xffff0000, v115
	v_pk_add_f32 v[110:111], v[110:111], v[114:115]
	v_lshlrev_b32_e32 v114, 16, v121
	v_and_b32_e32 v115, 0xffff0000, v121
	v_pk_add_f32 v[110:111], v[110:111], v[114:115]
	v_lshlrev_b32_e32 v114, 16, v137
	v_and_b32_e32 v115, 0xffff0000, v137
	v_pk_add_f32 v[110:111], v[110:111], v[114:115]
	v_lshlrev_b32_e32 v114, 16, v141
	v_and_b32_e32 v115, 0xffff0000, v141
	v_pk_add_f32 v[110:111], v[110:111], v[114:115]
	v_lshlrev_b32_e32 v114, 16, v145
	v_and_b32_e32 v115, 0xffff0000, v145
	v_pk_add_f32 v[110:111], v[110:111], v[114:115]
	v_lshlrev_b32_e32 v114, 16, v159
	v_and_b32_e32 v115, 0xffff0000, v159
	v_pk_add_f32 v[110:111], v[110:111], v[114:115]
	v_lshlrev_b32_e32 v114, 16, v163
	v_and_b32_e32 v115, 0xffff0000, v163
	v_lshlrev_b32_e32 v178, 16, v106
	v_and_b32_e32 v179, 0xffff0000, v106
	v_lshlrev_b32_e32 v116, 16, v107
	v_and_b32_e32 v117, 0xffff0000, v107
	v_pk_add_f32 v[110:111], v[110:111], v[114:115]
	v_pk_add_f32 v[114:115], v[172:173], 0 op_sel_hi:[1,0]
	v_pk_add_f32 v[112:113], v[112:113], 0 op_sel_hi:[1,0]
	v_pk_add_f32 v[114:115], v[114:115], v[178:179]
	v_pk_add_f32 v[112:113], v[112:113], v[116:117]
	v_pk_add_f32 v[114:115], v[114:115], v[184:185]
	v_lshlrev_b32_e32 v120, 16, v84
	v_and_b32_e32 v121, 0xffff0000, v84
	v_pk_add_f32 v[112:113], v[112:113], v[118:119]
	v_lshlrev_b32_e32 v84, 16, v85
	v_and_b32_e32 v85, 0xffff0000, v85
	v_pk_add_f32 v[114:115], v[114:115], v[120:121]
	v_lshlrev_b32_e32 v120, 16, v86
	v_and_b32_e32 v121, 0xffff0000, v86
	v_pk_add_f32 v[84:85], v[112:113], v[84:85]
	v_lshlrev_b32_e32 v86, 16, v87
	v_and_b32_e32 v87, 0xffff0000, v87
	v_pk_add_f32 v[84:85], v[84:85], v[86:87]
	v_lshlrev_b32_e32 v86, 16, v91
	v_and_b32_e32 v87, 0xffff0000, v91
	v_pk_add_f32 v[84:85], v[84:85], v[86:87]
	v_lshlrev_b32_e32 v86, 16, v93
	v_and_b32_e32 v87, 0xffff0000, v93
	v_pk_add_f32 v[84:85], v[84:85], v[86:87]
	v_lshlrev_b32_e32 v86, 16, v95
	v_and_b32_e32 v87, 0xffff0000, v95
	v_pk_add_f32 v[84:85], v[84:85], v[86:87]
	v_lshlrev_b32_e32 v86, 16, v99
	v_and_b32_e32 v87, 0xffff0000, v99
	v_pk_add_f32 v[84:85], v[84:85], v[86:87]
	v_lshlrev_b32_e32 v86, 16, v101
	v_and_b32_e32 v87, 0xffff0000, v101
	v_lshlrev_b32_e32 v104, 16, v82
	v_and_b32_e32 v105, 0xffff0000, v82
	v_lshlrev_b32_e32 v78, 16, v83
	v_and_b32_e32 v79, 0xffff0000, v83
	v_pk_add_f32 v[84:85], v[84:85], v[86:87]
	s_waitcnt vmcnt(5)
	v_lshlrev_b32_e32 v86, 16, v103
	v_and_b32_e32 v87, 0xffff0000, v103
	v_lshlrev_b32_e32 v106, 16, v108
	v_and_b32_e32 v107, 0xffff0000, v108
	v_lshlrev_b32_e32 v82, 16, v109
	v_and_b32_e32 v83, 0xffff0000, v109
	v_pk_add_f32 v[84:85], v[84:85], v[86:87]
	v_pk_add_f32 v[86:87], v[104:105], 0 op_sel_hi:[1,0]
	v_pk_add_f32 v[78:79], v[78:79], 0 op_sel_hi:[1,0]
	v_lshlrev_b32_e32 v108, 16, v126
	v_and_b32_e32 v109, 0xffff0000, v126
	v_lshlrev_b32_e32 v88, 16, v127
	v_and_b32_e32 v89, 0xffff0000, v127
	v_pk_add_f32 v[86:87], v[86:87], v[106:107]
	v_pk_add_f32 v[78:79], v[78:79], v[82:83]
	v_pk_add_f32 v[114:115], v[114:115], v[120:121]
	v_lshlrev_b32_e32 v120, 16, v90
	v_and_b32_e32 v121, 0xffff0000, v90
	v_pk_add_f32 v[86:87], v[86:87], v[108:109]
	v_lshlrev_b32_e32 v90, 16, v72
	v_and_b32_e32 v91, 0xffff0000, v72
	v_pk_add_f32 v[78:79], v[78:79], v[88:89]
	v_lshlrev_b32_e32 v72, 16, v73
	v_and_b32_e32 v73, 0xffff0000, v73
	v_pk_add_f32 v[86:87], v[86:87], v[90:91]
	v_lshlrev_b32_e32 v90, 16, v74
	v_and_b32_e32 v91, 0xffff0000, v74
	v_pk_add_f32 v[72:73], v[78:79], v[72:73]
	v_lshlrev_b32_e32 v74, 16, v75
	v_and_b32_e32 v75, 0xffff0000, v75
	v_pk_add_f32 v[86:87], v[86:87], v[90:91]
	v_lshlrev_b32_e32 v90, 16, v60
	v_and_b32_e32 v91, 0xffff0000, v60
	v_pk_add_f32 v[72:73], v[72:73], v[74:75]
	v_lshlrev_b32_e32 v60, 16, v61
	v_and_b32_e32 v61, 0xffff0000, v61
	v_pk_add_f32 v[114:115], v[114:115], v[120:121]
	v_lshlrev_b32_e32 v120, 16, v92
	v_and_b32_e32 v121, 0xffff0000, v92
	v_pk_add_f32 v[86:87], v[86:87], v[90:91]
	v_lshlrev_b32_e32 v90, 16, v62
	v_and_b32_e32 v91, 0xffff0000, v62
	v_pk_add_f32 v[60:61], v[72:73], v[60:61]
	v_lshlrev_b32_e32 v62, 16, v63
	v_and_b32_e32 v63, 0xffff0000, v63
	v_pk_add_f32 v[114:115], v[114:115], v[120:121]
	v_lshlrev_b32_e32 v120, 16, v94
	v_and_b32_e32 v121, 0xffff0000, v94
	v_pk_add_f32 v[60:61], v[60:61], v[62:63]
	v_lshlrev_b32_e32 v62, 16, v65
	v_and_b32_e32 v63, 0xffff0000, v65
	v_pk_add_f32 v[114:115], v[114:115], v[120:121]
	v_lshlrev_b32_e32 v120, 16, v98
	v_and_b32_e32 v121, 0xffff0000, v98
	v_pk_add_f32 v[60:61], v[60:61], v[62:63]
	v_lshlrev_b32_e32 v62, 16, v67
	v_and_b32_e32 v63, 0xffff0000, v67
	v_pk_add_f32 v[114:115], v[114:115], v[120:121]
	v_lshlrev_b32_e32 v120, 16, v100
	v_and_b32_e32 v121, 0xffff0000, v100
	v_pk_add_f32 v[86:87], v[86:87], v[90:91]
	v_lshlrev_b32_e32 v90, 16, v64
	v_and_b32_e32 v91, 0xffff0000, v64
	v_pk_add_f32 v[60:61], v[60:61], v[62:63]
	v_lshlrev_b32_e32 v62, 16, v69
	v_and_b32_e32 v63, 0xffff0000, v69
	v_pk_add_f32 v[114:115], v[114:115], v[120:121]
	v_lshlrev_b32_e32 v120, 16, v102
	v_and_b32_e32 v121, 0xffff0000, v102
	v_pk_add_f32 v[86:87], v[86:87], v[90:91]
	v_lshlrev_b32_e32 v90, 16, v66
	v_and_b32_e32 v91, 0xffff0000, v66
	v_pk_add_f32 v[60:61], v[60:61], v[62:63]
	s_waitcnt vmcnt(4)
	v_lshlrev_b32_e32 v62, 16, v71
	v_and_b32_e32 v63, 0xffff0000, v71
	v_mov_b32_e32 v64, v77
	v_mov_b32_e32 v65, v81
	v_pk_add_f32 v[114:115], v[114:115], v[120:121]
	v_pk_add_f32 v[86:87], v[86:87], v[90:91]
	v_lshlrev_b32_e32 v90, 16, v68
	v_and_b32_e32 v91, 0xffff0000, v68
	v_pk_add_f32 v[60:61], v[60:61], v[62:63]
	v_mov_b32_e32 v62, v76
	v_mov_b32_e32 v63, v80
	v_pk_mul_f32 v[64:65], v[64:65], v[64:65]
	v_mov_b32_e32 v66, v97
	v_mov_b32_e32 v67, v111
	v_pk_add_f32 v[86:87], v[86:87], v[90:91]
	v_lshlrev_b32_e32 v90, 16, v70
	v_and_b32_e32 v91, 0xffff0000, v70
	v_pk_fma_f32 v[62:63], v[62:63], v[62:63], v[64:65]
	v_mov_b32_e32 v64, v96
	v_mov_b32_e32 v65, v110
	v_pk_mul_f32 v[66:67], v[66:67], v[66:67]
	v_mul_f32_e32 v42, v115, v115
	v_pk_add_f32 v[86:87], v[86:87], v[90:91]
	v_pk_fma_f32 v[64:65], v[64:65], v[64:65], v[66:67]
	v_pk_fma_f32 v[66:67], v[114:115], v[114:115], v[42:43] op_sel_hi:[1,1,0]
	v_mul_f32_e32 v42, v85, v85
	v_pk_add_f32 v[62:63], v[62:63], v[62:63] op_sel:[0,1] op_sel_hi:[1,0]
	v_pk_add_f32 v[64:65], v[64:65], v[64:65] op_sel:[0,1] op_sel_hi:[1,0]
	v_pk_fma_f32 v[68:69], v[84:85], v[84:85], v[42:43] op_sel_hi:[1,1,0]
	v_pk_mul_f32 v[70:71], v[86:87], v[86:87]
	v_pk_mul_f32 v[72:73], v[60:61], v[60:61]
	v_mov_b32_e32 v63, v70
	v_mov_b32_e32 v65, v71
	v_mov_b32_e32 v67, v72
	v_mov_b32_e32 v69, v73
	v_pk_add_f32 v[62:63], v[62:63], v[64:65]
	v_pk_add_f32 v[64:65], v[66:67], v[68:69]
	s_waitcnt vmcnt(1)
	v_lshlrev_b32_e32 v66, 16, v54
	v_pk_add_f32 v[62:63], v[62:63], v[64:65]
	v_lshlrev_b32_e32 v64, 16, v56
	v_add_f32_e32 v42, v62, v63
	s_nop 1
	v_mov_b32_dpp v62, v42 quad_perm:[1,0,3,2] row_mask:0xf bank_mask:0xf
	s_waitcnt vmcnt(0)
	v_lshlrev_b32_e32 v68, 16, v52
	s_waitcnt lgkmcnt(0)
	v_add_f32_e32 v42, v42, v62
	s_nop 1
	v_mov_b32_dpp v62, v42 quad_perm:[2,3,0,1] row_mask:0xf bank_mask:0xf
	s_waitcnt lgkmcnt(0)
	v_add_f32_e32 v42, v42, v62
	s_nop 1
	v_mov_b32_dpp v63, v42 row_half_mirror row_mask:0xf bank_mask:0xf
	v_lshlrev_b32_e32 v62, 16, v58
	s_waitcnt lgkmcnt(0)
	v_add_f32_e32 v42, v42, v63
	s_nop 1
	v_mov_b32_dpp v65, v42 row_mirror row_mask:0xf bank_mask:0xf
	v_and_b32_e32 v63, 0xffff0000, v58
	v_lshlrev_b32_e32 v58, 16, v59
	v_and_b32_e32 v59, 0xffff0000, v59
	s_waitcnt lgkmcnt(0)
	v_add_f32_e32 v42, v42, v65
	v_mov_b32_e32 v67, v42
	s_nop 1
	v_permlane16_swap_b32 v42, v67
	v_and_b32_e32 v65, 0xffff0000, v56
	v_lshlrev_b32_e32 v56, 16, v57
	v_and_b32_e32 v57, 0xffff0000, v57
	s_waitcnt lgkmcnt(0)
	v_add_f32_e32 v42, v42, v67
	v_mov_b32_e32 v69, v42
	s_nop 1
	v_permlane32_swap_b32 v42, v69
	v_and_b32_e32 v67, 0xffff0000, v54
	v_lshlrev_b32_e32 v54, 16, v55
	v_and_b32_e32 v55, 0xffff0000, v55
	s_waitcnt lgkmcnt(0)
	v_add_f32_e32 v42, v42, v69
	v_fmamk_f32 v42, v42, 0x3a800000, v146
	v_mul_f32_e32 v69, 0x4b800000, v42
	v_cmp_gt_f32_e32 vcc, s97, v42
	s_nop 1
	v_cndmask_b32_e32 v42, v42, v69, vcc
	v_rsq_f32_e32 v42, v42
	v_and_b32_e32 v69, 0xffff0000, v52
	v_lshlrev_b32_e32 v52, 16, v53
	v_and_b32_e32 v53, 0xffff0000, v53
	v_mul_f32_e32 v70, 0x45800000, v42
	v_cndmask_b32_e32 v42, v42, v70, vcc
	v_pk_mul_f32 v[70:71], v[76:77], v[42:43] op_sel_hi:[1,0]
	v_pk_mul_f32 v[72:73], v[80:81], v[42:43] op_sel_hi:[1,0]
	v_pk_fma_f32 v[62:63], v[0:1], v[70:71], v[62:63]
	v_pk_fma_f32 v[58:59], v[2:3], v[72:73], v[58:59]
	v_pk_mul_f32 v[72:73], v[62:63], v[62:63]
	v_pk_mul_f32 v[70:71], v[58:59], v[58:59]
	v_pk_mul_f32 v[60:61], v[60:61], v[42:43] op_sel_hi:[1,0]
	v_pk_mov_b32 v[74:75], v[72:73], v[70:71] op_sel:[1,0]
	v_mov_b32_e32 v73, v71
	v_pk_add_f32 v[70:71], v[74:75], v[72:73]
	v_pk_mul_f32 v[72:73], v[110:111], v[42:43] op_sel_hi:[1,0]
	v_pk_mul_f32 v[74:75], v[96:97], v[42:43] op_sel_hi:[1,0]
	v_pk_fma_f32 v[56:57], v[6:7], v[72:73], v[56:57]
	v_pk_fma_f32 v[64:65], v[4:5], v[74:75], v[64:65]
	v_pk_mul_f32 v[72:73], v[56:57], v[56:57]
	v_pk_mul_f32 v[74:75], v[64:65], v[64:65]
	v_pk_add_f32 v[70:71], v[70:71], v[70:71] op_sel_hi:[0,1]
	v_pk_mov_b32 v[76:77], v[74:75], v[72:73] op_sel:[1,0]
	v_mov_b32_e32 v75, v73
	v_pk_add_f32 v[72:73], v[76:77], v[74:75]
	v_pk_mul_f32 v[76:77], v[114:115], v[42:43] op_sel_hi:[1,0]
	v_pk_mul_f32 v[74:75], v[84:85], v[42:43] op_sel_hi:[1,0]
	v_pk_fma_f32 v[66:67], v[16:17], v[76:77], v[66:67]
	v_pk_fma_f32 v[54:55], v[18:19], v[74:75], v[54:55]
	v_mul_f32_e32 v70, v66, v66
	v_pk_fma_f32 v[74:75], v[66:67], v[66:67], v[70:71] op_sel_hi:[1,1,0]
	v_mul_f32_e32 v70, v54, v54
	v_pk_mul_f32 v[78:79], v[86:87], v[42:43] op_sel_hi:[1,0]
	v_pk_add_f32 v[72:73], v[72:73], v[72:73] op_sel_hi:[0,1]
	v_pk_fma_f32 v[76:77], v[54:55], v[54:55], v[70:71] op_sel_hi:[1,1,0]
	v_pk_fma_f32 v[68:69], v[20:21], v[78:79], v[68:69]
	v_pk_fma_f32 v[52:53], v[22:23], v[60:61], v[52:53]
	v_mul_f32_e32 v74, v68, v68
	v_mul_f32_e32 v76, v69, v69
	v_mul_f32_e32 v70, v52, v52
	v_mul_f32_e32 v72, v53, v53
	v_pk_add_f32 v[60:61], v[74:75], v[76:77]
	v_pk_add_f32 v[70:71], v[70:71], v[72:73]
	v_cvt_pk_bf16_f32 v74, v62, v63
	v_lshl_add_u64 v[72:73], v[50:51], 0, s[68:69]
	v_pk_add_f32 v[60:61], v[60:61], v[70:71]
	s_nop 0
	v_add_f32_e32 v42, v60, v61
	s_nop 1
	v_mov_b32_dpp v60, v42 quad_perm:[1,0,3,2] row_mask:0xf bank_mask:0xf
	s_waitcnt lgkmcnt(0)
	v_add_f32_e32 v42, v42, v60
	s_nop 1
	v_mov_b32_dpp v60, v42 quad_perm:[2,3,0,1] row_mask:0xf bank_mask:0xf
	s_waitcnt lgkmcnt(0)
	v_add_f32_e32 v42, v42, v60
	s_nop 1
	v_mov_b32_dpp v70, v42 row_half_mirror row_mask:0xf bank_mask:0xf
	v_lshl_add_u64 v[60:61], v[50:51], 0, s[62:63]
	s_waitcnt lgkmcnt(0)
	v_add_f32_e32 v42, v42, v70
	s_nop 1
	v_mov_b32_dpp v75, v42 row_mirror row_mask:0xf bank_mask:0xf
	v_lshl_add_u64 v[70:71], v[50:51], 0, s[64:65]
	v_lshl_add_u64 v[50:51], v[50:51], 0, s[70:71]
	s_waitcnt lgkmcnt(0)
	v_add_f32_e32 v42, v42, v75
	v_mov_b32_e32 v76, v42
	s_nop 1
	v_permlane16_swap_b32 v42, v76
	v_cvt_pk_bf16_f32 v75, v58, v59
	s_waitcnt lgkmcnt(0)
	v_add_f32_e32 v42, v42, v76
	global_store_dwordx2 v[60:61], v[74:75], off sc0 sc1
	s_nop 1
	v_mov_b32_e32 v74, v42
	s_nop 1
	v_permlane32_swap_b32 v42, v74
	v_cvt_pk_bf16_f32 v60, v64, v65
	v_cvt_pk_bf16_f32 v61, v56, v57
	s_waitcnt lgkmcnt(0)
	v_add_f32_e32 v42, v42, v74
	global_store_dwordx2 v[70:71], v[60:61], off sc0 sc1
	s_nop 1
	v_cvt_pk_bf16_f32 v60, v66, v67
	v_fmamk_f32 v42, v42, 0x3a800000, v146
	v_cvt_pk_bf16_f32 v61, v54, v55
	v_cmp_gt_f32_e32 vcc, s97, v42
	global_store_dwordx2 v[72:73], v[60:61], off sc0 sc1
	s_nop 1
	v_mul_f32_e32 v60, 0x4b800000, v42
	s_nop 0
	v_cndmask_b32_e32 v42, v42, v60, vcc
	v_rsq_f32_e32 v42, v42
	v_cvt_pk_bf16_f32 v60, v68, v69
	v_cvt_pk_bf16_f32 v61, v52, v53
	s_nop 0
	global_store_dwordx2 v[50:51], v[60:61], off sc0 sc1
	s_nop 1
	v_mul_f32_e32 v50, 0x45800000, v42
	v_cndmask_b32_e32 v42, v42, v50, vcc
	v_pk_mul_f32 v[60:61], v[62:63], v[42:43] op_sel_hi:[1,0]
	v_lshl_add_u64 v[50:51], v[48:49], 0, s[6:7]
	v_pk_mul_f32 v[58:59], v[58:59], v[42:43] op_sel_hi:[1,0]
	v_pk_mul_f32 v[60:61], v[24:25], v[60:61]
	v_pk_mul_f32 v[58:59], v[26:27], v[58:59]
	v_cvt_pk_bf16_f32 v60, v60, v61
	v_pk_mul_f32 v[56:57], v[56:57], v[42:43] op_sel_hi:[1,0]
	v_cvt_pk_bf16_f32 v61, v58, v59
	s_mov_b64 s[6:7], 0x3800a00
	global_store_dwordx2 v[50:51], v[60:61], off sc0 sc1
	s_nop 1
	v_pk_mul_f32 v[50:51], v[64:65], v[42:43] op_sel_hi:[1,0]
	v_pk_mul_f32 v[56:57], v[10:11], v[56:57]
	v_pk_mul_f32 v[50:51], v[8:9], v[50:51]
	v_pk_mul_f32 v[54:55], v[54:55], v[42:43] op_sel_hi:[1,0]
	v_cvt_pk_bf16_f32 v50, v50, v51
	v_cvt_pk_bf16_f32 v51, v56, v57
	v_lshl_add_u64 v[56:57], v[48:49], 0, s[6:7]
	global_store_dwordx2 v[56:57], v[50:51], off sc0 sc1
	s_nop 1
	v_pk_mul_f32 v[50:51], v[66:67], v[42:43] op_sel_hi:[1,0]
	v_pk_mul_f32 v[54:55], v[14:15], v[54:55]
	v_pk_mul_f32 v[50:51], v[12:13], v[50:51]
	s_mov_b64 s[6:7], 0x3800c00
	v_cvt_pk_bf16_f32 v50, v50, v51
	v_cvt_pk_bf16_f32 v51, v54, v55
	v_lshl_add_u64 v[54:55], v[48:49], 0, s[6:7]
	global_store_dwordx2 v[54:55], v[50:51], off sc0 sc1
	s_nop 1
	v_pk_mul_f32 v[50:51], v[68:69], v[42:43] op_sel_hi:[1,0]
	v_pk_mul_f32 v[52:53], v[52:53], v[42:43] op_sel_hi:[1,0]
	v_pk_mul_f32 v[50:51], v[28:29], v[50:51]
	s_mov_b64 s[6:7], 0x3800e00
	v_pk_mul_f32 v[52:53], v[30:31], v[52:53]
	v_cvt_pk_bf16_f32 v50, v50, v51
	v_lshl_add_u64 v[48:49], v[48:49], 0, s[6:7]
	v_cvt_pk_bf16_f32 v51, v52, v53
	s_nop 0
	global_store_dwordx2 v[48:49], v[50:51], off sc0 sc1
	s_nop 1
	s_cbranch_scc0 .LBB0_1410

.LBB0_1403:
	s_lshl_b64 s[6:7], s[6:7], 12
	s_add_u32 s6, s8, s6
	s_addc_u32 s7, s9, s7
	v_lshl_add_u64 v[48:49], v[32:33], 3, s[6:7]
	v_lshl_add_u64 v[70:71], v[46:47], 0, s[82:83]
	s_mov_b32 s6, 0xda00000
	v_add_co_u32_e32 v50, vcc, s6, v70
	s_mov_b32 s6, 0xdb80000
	s_nop 0
	v_addc_co_u32_e32 v51, vcc, 0, v71, vcc
	v_add_co_u32_e32 v52, vcc, s6, v70
	s_mov_b32 s6, 0xdd00000
	s_nop 0
	v_addc_co_u32_e32 v53, vcc, 0, v71, vcc
	v_add_co_u32_e32 v54, vcc, s6, v70
	s_mov_b32 s6, 0xde80000
	s_nop 0
	v_addc_co_u32_e32 v55, vcc, 0, v71, vcc
	v_add_co_u32_e32 v56, vcc, s6, v70
	s_mov_b32 s6, 0xe000000
	s_nop 0
	v_addc_co_u32_e32 v57, vcc, 0, v71, vcc
	v_add_co_u32_e32 v58, vcc, s6, v70
	s_mov_b32 s6, 0xe180000
	s_nop 0
	v_addc_co_u32_e32 v59, vcc, 0, v71, vcc
	v_add_co_u32_e32 v60, vcc, s6, v70
	s_mov_b32 s6, 0xe300000
	s_nop 0
	v_addc_co_u32_e32 v61, vcc, 0, v71, vcc
	v_add_co_u32_e32 v62, vcc, s6, v70
	global_load_dwordx2 v[74:75], v[48:49], off offset:2048
	global_load_dwordx2 v[76:77], v[48:49], off offset:2560
	global_load_dwordx2 v[78:79], v[48:49], off offset:3072
	global_load_dwordx2 v[72:73], v[48:49], off offset:3584
	global_load_dwordx2 v[96:97], v[50:51], off
	global_load_dwordx2 v[98:99], v[50:51], off offset:512
	global_load_dwordx2 v[102:103], v[50:51], off offset:1024
	global_load_dwordx2 v[108:109], v[50:51], off offset:1536
	global_load_dwordx2 v[114:115], v[52:53], off
	global_load_dwordx2 v[116:117], v[52:53], off offset:512
	global_load_dwordx2 v[126:127], v[52:53], off offset:1024
	global_load_dwordx2 v[128:129], v[52:53], off offset:1536
	global_load_dwordx2 v[144:145], v[54:55], off
	global_load_dwordx2 v[156:157], v[54:55], off offset:512
	global_load_dwordx2 v[158:159], v[54:55], off offset:1024
	global_load_dwordx2 v[160:161], v[54:55], off offset:1536
	v_addc_co_u32_e32 v63, vcc, 0, v71, vcc
	s_mov_b32 s6, 0xe480000
	v_add_co_u32_e32 v64, vcc, s6, v70
	s_mov_b32 s6, 0xe600000
	s_nop 0
	v_addc_co_u32_e32 v65, vcc, 0, v71, vcc
	v_add_co_u32_e32 v66, vcc, s6, v70
	global_load_dwordx2 v[162:163], v[56:57], off
	global_load_dwordx2 v[130:131], v[56:57], off offset:512
	global_load_dwordx2 v[100:101], v[56:57], off offset:1024
	global_load_dwordx2 v[80:81], v[56:57], off offset:1536
	v_addc_co_u32_e32 v67, vcc, 0, v71, vcc
	s_mov_b32 s6, 0xe780000
	global_load_dwordx2 v[164:165], v[58:59], off
	global_load_dwordx2 v[134:135], v[58:59], off offset:512
	global_load_dwordx2 v[104:105], v[58:59], off offset:1024
	global_load_dwordx2 v[82:83], v[58:59], off offset:1536
	v_add_co_u32_e32 v68, vcc, s6, v70
	global_load_dwordx2 v[166:167], v[60:61], off
	global_load_dwordx2 v[138:139], v[60:61], off offset:512
	global_load_dwordx2 v[106:107], v[60:61], off offset:1024
	global_load_dwordx2 v[84:85], v[60:61], off offset:1536
	global_load_dwordx2 v[168:169], v[62:63], off
	global_load_dwordx2 v[140:141], v[62:63], off offset:512
	global_load_dwordx2 v[110:111], v[62:63], off offset:1024
	global_load_dwordx2 v[86:87], v[62:63], off offset:1536
	global_load_dwordx2 v[170:171], v[64:65], off
	global_load_dwordx2 v[142:143], v[64:65], off offset:512
	global_load_dwordx2 v[112:113], v[64:65], off offset:1024
	global_load_dwordx2 v[88:89], v[64:65], off offset:1536
	global_load_dwordx2 v[172:173], v[66:67], off
	v_addc_co_u32_e32 v69, vcc, 0, v71, vcc
	global_load_dwordx2 v[174:175], v[68:69], off
	s_mov_b32 s6, 0xe900000
	v_add_co_u32_e32 v70, vcc, s6, v70
	s_mov_b64 s[6:7], 0x3800000
	s_nop 0
	v_addc_co_u32_e32 v71, vcc, 0, v71, vcc
	global_load_dwordx2 v[176:177], v[70:71], off
	global_load_dwordx2 v[178:179], v[66:67], off offset:512
	global_load_dwordx2 v[122:123], v[66:67], off offset:1024
	global_load_dwordx2 v[94:95], v[66:67], off offset:1536
	global_load_dwordx2 v[180:181], v[68:69], off offset:512
	global_load_dwordx2 v[120:121], v[68:69], off offset:1024
	global_load_dwordx2 v[92:93], v[68:69], off offset:1536
	global_load_dwordx2 v[182:183], v[70:71], off offset:512
	global_load_dwordx2 v[118:119], v[70:71], off offset:1024
	global_load_dwordx2 v[90:91], v[70:71], off offset:1536
	s_add_i32 s17, s17, 1
	s_cmpk_lt_u32 s17, 0x4080
	s_waitcnt vmcnt(43)
	v_lshlrev_b32_e32 v184, 16, v96
	v_and_b32_e32 v185, 0xffff0000, v96
	v_lshlrev_b32_e32 v186, 16, v97
	v_and_b32_e32 v187, 0xffff0000, v97
	s_waitcnt vmcnt(39)
	v_lshlrev_b32_e32 v96, 16, v114
	v_and_b32_e32 v97, 0xffff0000, v114
	s_waitcnt vmcnt(38)
	v_lshlrev_b32_e32 v194, 16, v116
	v_and_b32_e32 v195, 0xffff0000, v116
	v_lshlrev_b32_e32 v196, 16, v117
	v_and_b32_e32 v197, 0xffff0000, v117
	s_waitcnt vmcnt(35)
	v_lshlrev_b32_e32 v116, 16, v144
	v_and_b32_e32 v117, 0xffff0000, v144
	v_lshlrev_b32_e32 v200, 16, v145
	v_and_b32_e32 v201, 0xffff0000, v145
	s_waitcnt vmcnt(33)
	v_lshlrev_b32_e32 v204, 16, v158
	v_and_b32_e32 v205, 0xffff0000, v158
	v_lshlrev_b32_e32 v144, 16, v159
	v_and_b32_e32 v145, 0xffff0000, v159
	v_pk_add_f32 v[158:159], v[184:185], 0 op_sel_hi:[1,0]
	v_lshlrev_b32_e32 v192, 16, v102
	v_pk_add_f32 v[96:97], v[158:159], v[96:97]
	v_and_b32_e32 v193, 0xffff0000, v102
	v_pk_add_f32 v[96:97], v[96:97], v[116:117]
	s_waitcnt vmcnt(31)
	v_lshlrev_b32_e32 v116, 16, v162
	v_and_b32_e32 v117, 0xffff0000, v162
	v_pk_add_f32 v[96:97], v[96:97], v[116:117]
	s_waitcnt vmcnt(27)
	v_lshlrev_b32_e32 v116, 16, v164
	v_and_b32_e32 v117, 0xffff0000, v164
	v_pk_add_f32 v[96:97], v[96:97], v[116:117]
	s_waitcnt vmcnt(23)
	v_lshlrev_b32_e32 v116, 16, v166
	v_and_b32_e32 v117, 0xffff0000, v166
	v_pk_add_f32 v[96:97], v[96:97], v[116:117]
	s_waitcnt vmcnt(19)
	v_lshlrev_b32_e32 v116, 16, v168
	v_and_b32_e32 v117, 0xffff0000, v168
	v_pk_add_f32 v[96:97], v[96:97], v[116:117]
	s_waitcnt vmcnt(15)
	v_lshlrev_b32_e32 v116, 16, v170
	v_and_b32_e32 v117, 0xffff0000, v170
	v_pk_add_f32 v[96:97], v[96:97], v[116:117]
	s_waitcnt vmcnt(11)
	v_lshlrev_b32_e32 v116, 16, v172
	v_and_b32_e32 v117, 0xffff0000, v172
	v_pk_add_f32 v[96:97], v[96:97], v[116:117]
	s_waitcnt vmcnt(10)
	v_lshlrev_b32_e32 v116, 16, v174
	v_and_b32_e32 v117, 0xffff0000, v174
	v_pk_add_f32 v[96:97], v[96:97], v[116:117]
	s_waitcnt vmcnt(9)
	v_lshlrev_b32_e32 v116, 16, v176
	v_and_b32_e32 v117, 0xffff0000, v176
	v_lshlrev_b32_e32 v132, 16, v103
	v_and_b32_e32 v133, 0xffff0000, v103
	v_lshlrev_b32_e32 v102, 16, v115
	v_and_b32_e32 v103, 0xffff0000, v115
	v_pk_add_f32 v[96:97], v[96:97], v[116:117]
	v_pk_add_f32 v[116:117], v[186:187], 0 op_sel_hi:[1,0]
	v_lshlrev_b32_e32 v188, 16, v98
	v_pk_add_f32 v[102:103], v[116:117], v[102:103]
	v_lshlrev_b32_e32 v116, 16, v163
	v_pk_add_f32 v[102:103], v[102:103], v[200:201]
	v_and_b32_e32 v117, 0xffff0000, v163
	v_pk_add_f32 v[102:103], v[102:103], v[116:117]
	v_lshlrev_b32_e32 v116, 16, v165
	v_and_b32_e32 v117, 0xffff0000, v165
	v_pk_add_f32 v[102:103], v[102:103], v[116:117]
	v_lshlrev_b32_e32 v116, 16, v167
	v_and_b32_e32 v117, 0xffff0000, v167
	v_pk_add_f32 v[102:103], v[102:103], v[116:117]
	v_lshlrev_b32_e32 v116, 16, v169
	v_and_b32_e32 v117, 0xffff0000, v169
	v_pk_add_f32 v[102:103], v[102:103], v[116:117]
	v_lshlrev_b32_e32 v116, 16, v171
	v_and_b32_e32 v117, 0xffff0000, v171
	v_pk_add_f32 v[102:103], v[102:103], v[116:117]
	v_lshlrev_b32_e32 v116, 16, v173
	v_and_b32_e32 v117, 0xffff0000, v173
	v_pk_add_f32 v[102:103], v[102:103], v[116:117]
	v_lshlrev_b32_e32 v116, 16, v175
	v_and_b32_e32 v117, 0xffff0000, v175
	v_and_b32_e32 v189, 0xffff0000, v98
	v_pk_add_f32 v[102:103], v[102:103], v[116:117]
	v_lshlrev_b32_e32 v116, 16, v177
	v_and_b32_e32 v117, 0xffff0000, v177
	v_pk_add_f32 v[102:103], v[102:103], v[116:117]
	v_pk_add_f32 v[116:117], v[188:189], 0 op_sel_hi:[1,0]
	v_lshlrev_b32_e32 v202, 16, v156
	v_and_b32_e32 v203, 0xffff0000, v156
	v_pk_add_f32 v[116:117], v[116:117], v[194:195]
	v_lshlrev_b32_e32 v158, 16, v130
	v_pk_add_f32 v[116:117], v[116:117], v[202:203]
	v_and_b32_e32 v159, 0xffff0000, v130
	v_pk_add_f32 v[116:117], v[116:117], v[158:159]
	v_lshlrev_b32_e32 v158, 16, v134
	v_and_b32_e32 v159, 0xffff0000, v134
	v_pk_add_f32 v[116:117], v[116:117], v[158:159]
	v_lshlrev_b32_e32 v158, 16, v138
	v_and_b32_e32 v159, 0xffff0000, v138
	v_pk_add_f32 v[116:117], v[116:117], v[158:159]
	v_lshlrev_b32_e32 v158, 16, v140
	v_and_b32_e32 v159, 0xffff0000, v140
	v_pk_add_f32 v[116:117], v[116:117], v[158:159]
	v_lshlrev_b32_e32 v158, 16, v142
	v_and_b32_e32 v159, 0xffff0000, v142
	v_pk_add_f32 v[116:117], v[116:117], v[158:159]
	s_waitcnt vmcnt(8)
	v_lshlrev_b32_e32 v158, 16, v178
	v_and_b32_e32 v159, 0xffff0000, v178
	v_pk_add_f32 v[116:117], v[116:117], v[158:159]
	s_waitcnt vmcnt(5)
	v_lshlrev_b32_e32 v158, 16, v180
	v_and_b32_e32 v159, 0xffff0000, v180
	v_lshlrev_b32_e32 v190, 16, v99
	v_and_b32_e32 v191, 0xffff0000, v99
	v_pk_add_f32 v[116:117], v[116:117], v[158:159]
	s_waitcnt vmcnt(2)
	v_lshlrev_b32_e32 v158, 16, v182
	v_and_b32_e32 v159, 0xffff0000, v182
	v_pk_add_f32 v[116:117], v[116:117], v[158:159]
	v_pk_add_f32 v[158:159], v[190:191], 0 op_sel_hi:[1,0]
	v_lshlrev_b32_e32 v156, 16, v157
	v_and_b32_e32 v157, 0xffff0000, v157
	v_pk_add_f32 v[158:159], v[158:159], v[196:197]
	v_lshlrev_b32_e32 v130, 16, v131
	v_pk_add_f32 v[156:157], v[158:159], v[156:157]
	v_and_b32_e32 v131, 0xffff0000, v131
	v_pk_add_f32 v[130:131], v[156:157], v[130:131]
	v_lshlrev_b32_e32 v134, 16, v135
	v_and_b32_e32 v135, 0xffff0000, v135
	v_pk_add_f32 v[130:131], v[130:131], v[134:135]
	v_lshlrev_b32_e32 v134, 16, v139
	v_and_b32_e32 v135, 0xffff0000, v139
	v_pk_add_f32 v[130:131], v[130:131], v[134:135]
	v_lshlrev_b32_e32 v134, 16, v141
	v_and_b32_e32 v135, 0xffff0000, v141
	v_pk_add_f32 v[130:131], v[130:131], v[134:135]
	v_lshlrev_b32_e32 v134, 16, v143
	v_and_b32_e32 v135, 0xffff0000, v143
	v_pk_add_f32 v[130:131], v[130:131], v[134:135]
	v_lshlrev_b32_e32 v134, 16, v179
	v_and_b32_e32 v135, 0xffff0000, v179
	v_pk_add_f32 v[130:131], v[130:131], v[134:135]
	v_lshlrev_b32_e32 v134, 16, v181
	v_and_b32_e32 v135, 0xffff0000, v181
	v_pk_add_f32 v[130:131], v[130:131], v[134:135]
	v_lshlrev_b32_e32 v134, 16, v183
	v_and_b32_e32 v135, 0xffff0000, v183
	v_lshlrev_b32_e32 v198, 16, v126
	v_and_b32_e32 v199, 0xffff0000, v126
	v_lshlrev_b32_e32 v136, 16, v127
	v_and_b32_e32 v137, 0xffff0000, v127
	v_pk_add_f32 v[130:131], v[130:131], v[134:135]
	v_pk_add_f32 v[134:135], v[192:193], 0 op_sel_hi:[1,0]
	v_pk_add_f32 v[132:133], v[132:133], 0 op_sel_hi:[1,0]
	v_pk_add_f32 v[134:135], v[134:135], v[198:199]
	v_pk_add_f32 v[132:133], v[132:133], v[136:137]
	v_pk_add_f32 v[134:135], v[134:135], v[204:205]
	v_lshlrev_b32_e32 v138, 16, v100
	v_and_b32_e32 v139, 0xffff0000, v100
	v_pk_add_f32 v[132:133], v[132:133], v[144:145]
	v_lshlrev_b32_e32 v100, 16, v101
	v_and_b32_e32 v101, 0xffff0000, v101
	v_pk_add_f32 v[134:135], v[134:135], v[138:139]
	v_lshlrev_b32_e32 v138, 16, v104
	v_and_b32_e32 v139, 0xffff0000, v104
	v_pk_add_f32 v[100:101], v[132:133], v[100:101]
	v_lshlrev_b32_e32 v104, 16, v105
	v_and_b32_e32 v105, 0xffff0000, v105
	v_pk_add_f32 v[100:101], v[100:101], v[104:105]
	v_lshlrev_b32_e32 v104, 16, v107
	v_and_b32_e32 v105, 0xffff0000, v107
	v_pk_add_f32 v[100:101], v[100:101], v[104:105]
	v_lshlrev_b32_e32 v104, 16, v111
	v_and_b32_e32 v105, 0xffff0000, v111
	v_pk_add_f32 v[100:101], v[100:101], v[104:105]
	v_lshlrev_b32_e32 v104, 16, v113
	v_and_b32_e32 v105, 0xffff0000, v113
	v_pk_add_f32 v[100:101], v[100:101], v[104:105]
	v_lshlrev_b32_e32 v104, 16, v123
	v_and_b32_e32 v105, 0xffff0000, v123
	v_pk_add_f32 v[100:101], v[100:101], v[104:105]
	v_lshlrev_b32_e32 v104, 16, v121
	v_and_b32_e32 v105, 0xffff0000, v121
	v_lshlrev_b32_e32 v124, 16, v108
	v_and_b32_e32 v125, 0xffff0000, v108
	v_lshlrev_b32_e32 v98, 16, v109
	v_and_b32_e32 v99, 0xffff0000, v109
	v_pk_add_f32 v[100:101], v[100:101], v[104:105]
	s_waitcnt vmcnt(1)
	v_lshlrev_b32_e32 v104, 16, v119
	v_and_b32_e32 v105, 0xffff0000, v119
	v_lshlrev_b32_e32 v126, 16, v128
	v_and_b32_e32 v127, 0xffff0000, v128
	v_lshlrev_b32_e32 v108, 16, v129
	v_and_b32_e32 v109, 0xffff0000, v129
	v_pk_add_f32 v[100:101], v[100:101], v[104:105]
	v_pk_add_f32 v[104:105], v[124:125], 0 op_sel_hi:[1,0]
	v_pk_add_f32 v[98:99], v[98:99], 0 op_sel_hi:[1,0]
	v_lshlrev_b32_e32 v128, 16, v160
	v_and_b32_e32 v129, 0xffff0000, v160
	v_lshlrev_b32_e32 v114, 16, v161
	v_and_b32_e32 v115, 0xffff0000, v161
	v_pk_add_f32 v[104:105], v[104:105], v[126:127]
	v_pk_add_f32 v[98:99], v[98:99], v[108:109]
	v_pk_add_f32 v[134:135], v[134:135], v[138:139]
	v_lshlrev_b32_e32 v138, 16, v106
	v_and_b32_e32 v139, 0xffff0000, v106
	v_pk_add_f32 v[104:105], v[104:105], v[128:129]
	v_lshlrev_b32_e32 v106, 16, v80
	v_and_b32_e32 v107, 0xffff0000, v80
	v_pk_add_f32 v[98:99], v[98:99], v[114:115]
	v_lshlrev_b32_e32 v80, 16, v81
	v_and_b32_e32 v81, 0xffff0000, v81
	v_pk_add_f32 v[104:105], v[104:105], v[106:107]
	v_lshlrev_b32_e32 v106, 16, v82
	v_and_b32_e32 v107, 0xffff0000, v82
	v_pk_add_f32 v[80:81], v[98:99], v[80:81]
	v_lshlrev_b32_e32 v82, 16, v83
	v_and_b32_e32 v83, 0xffff0000, v83
	v_pk_add_f32 v[80:81], v[80:81], v[82:83]
	v_lshlrev_b32_e32 v82, 16, v85
	v_and_b32_e32 v83, 0xffff0000, v85
	v_pk_add_f32 v[134:135], v[134:135], v[138:139]
	v_lshlrev_b32_e32 v138, 16, v110
	v_and_b32_e32 v139, 0xffff0000, v110
	v_pk_add_f32 v[80:81], v[80:81], v[82:83]
	v_lshlrev_b32_e32 v82, 16, v87
	v_and_b32_e32 v83, 0xffff0000, v87
	v_pk_add_f32 v[134:135], v[134:135], v[138:139]
	v_lshlrev_b32_e32 v138, 16, v112
	v_and_b32_e32 v139, 0xffff0000, v112
	v_pk_add_f32 v[104:105], v[104:105], v[106:107]
	v_lshlrev_b32_e32 v106, 16, v84
	v_and_b32_e32 v107, 0xffff0000, v84
	v_pk_add_f32 v[80:81], v[80:81], v[82:83]
	v_lshlrev_b32_e32 v82, 16, v89
	v_and_b32_e32 v83, 0xffff0000, v89
	v_pk_add_f32 v[134:135], v[134:135], v[138:139]
	v_lshlrev_b32_e32 v138, 16, v122
	v_and_b32_e32 v139, 0xffff0000, v122
	v_pk_add_f32 v[104:105], v[104:105], v[106:107]
	v_lshlrev_b32_e32 v106, 16, v86
	v_and_b32_e32 v107, 0xffff0000, v86
	v_pk_add_f32 v[80:81], v[80:81], v[82:83]
	v_lshlrev_b32_e32 v82, 16, v95
	v_and_b32_e32 v83, 0xffff0000, v95
	v_pk_add_f32 v[134:135], v[134:135], v[138:139]
	v_lshlrev_b32_e32 v138, 16, v120
	v_and_b32_e32 v139, 0xffff0000, v120
	v_pk_add_f32 v[104:105], v[104:105], v[106:107]
	v_lshlrev_b32_e32 v106, 16, v88
	v_and_b32_e32 v107, 0xffff0000, v88
	v_pk_add_f32 v[80:81], v[80:81], v[82:83]
	v_lshlrev_b32_e32 v82, 16, v93
	v_and_b32_e32 v83, 0xffff0000, v93
	v_pk_add_f32 v[134:135], v[134:135], v[138:139]
	v_lshlrev_b32_e32 v138, 16, v118
	v_and_b32_e32 v139, 0xffff0000, v118
	v_pk_add_f32 v[104:105], v[104:105], v[106:107]
	v_lshlrev_b32_e32 v106, 16, v94
	v_and_b32_e32 v107, 0xffff0000, v94
	v_pk_add_f32 v[80:81], v[80:81], v[82:83]
	s_waitcnt vmcnt(0)
	v_lshlrev_b32_e32 v82, 16, v91
	v_and_b32_e32 v83, 0xffff0000, v91
	v_mov_b32_e32 v84, v97
	v_mov_b32_e32 v85, v103
	v_pk_add_f32 v[134:135], v[134:135], v[138:139]
	v_pk_add_f32 v[104:105], v[104:105], v[106:107]
	v_lshlrev_b32_e32 v106, 16, v92
	v_and_b32_e32 v107, 0xffff0000, v92
	v_pk_add_f32 v[80:81], v[80:81], v[82:83]
	v_mov_b32_e32 v82, v96
	v_mov_b32_e32 v83, v102
	v_pk_mul_f32 v[84:85], v[84:85], v[84:85]
	v_mov_b32_e32 v86, v117
	v_mov_b32_e32 v87, v131
	v_pk_add_f32 v[104:105], v[104:105], v[106:107]
	v_lshlrev_b32_e32 v106, 16, v90
	v_and_b32_e32 v107, 0xffff0000, v90
	v_pk_fma_f32 v[82:83], v[82:83], v[82:83], v[84:85]
	v_mov_b32_e32 v84, v116
	v_mov_b32_e32 v85, v130
	v_pk_mul_f32 v[86:87], v[86:87], v[86:87]
	v_mul_f32_e32 v42, v135, v135
	v_pk_add_f32 v[104:105], v[104:105], v[106:107]
	v_pk_fma_f32 v[84:85], v[84:85], v[84:85], v[86:87]
	v_pk_fma_f32 v[86:87], v[134:135], v[134:135], v[42:43] op_sel_hi:[1,1,0]
	v_mul_f32_e32 v42, v101, v101
	v_pk_add_f32 v[82:83], v[82:83], v[82:83] op_sel:[0,1] op_sel_hi:[1,0]
	v_pk_add_f32 v[84:85], v[84:85], v[84:85] op_sel:[0,1] op_sel_hi:[1,0]
	v_pk_fma_f32 v[88:89], v[100:101], v[100:101], v[42:43] op_sel_hi:[1,1,0]
	v_pk_mul_f32 v[90:91], v[104:105], v[104:105]
	v_pk_mul_f32 v[92:93], v[80:81], v[80:81]
	v_mov_b32_e32 v83, v90
	v_mov_b32_e32 v85, v91
	v_mov_b32_e32 v87, v92
	v_mov_b32_e32 v89, v93
	v_pk_add_f32 v[82:83], v[82:83], v[84:85]
	v_pk_add_f32 v[84:85], v[86:87], v[88:89]
	v_lshlrev_b32_e32 v86, 16, v78
	v_pk_add_f32 v[82:83], v[82:83], v[84:85]
	v_lshlrev_b32_e32 v84, 16, v76
	v_add_f32_e32 v42, v82, v83
	s_nop 1
	v_mov_b32_dpp v82, v42 quad_perm:[1,0,3,2] row_mask:0xf bank_mask:0xf
	v_lshlrev_b32_e32 v88, 16, v72
	s_waitcnt lgkmcnt(0)
	v_add_f32_e32 v42, v42, v82
	s_nop 1
	v_mov_b32_dpp v82, v42 quad_perm:[2,3,0,1] row_mask:0xf bank_mask:0xf
	s_waitcnt lgkmcnt(0)
	v_add_f32_e32 v42, v42, v82
	s_nop 1
	v_mov_b32_dpp v83, v42 row_half_mirror row_mask:0xf bank_mask:0xf
	v_lshlrev_b32_e32 v82, 16, v74
	s_waitcnt lgkmcnt(0)
	v_add_f32_e32 v42, v42, v83
	s_nop 1
	v_mov_b32_dpp v85, v42 row_mirror row_mask:0xf bank_mask:0xf
	v_and_b32_e32 v83, 0xffff0000, v74
	v_lshlrev_b32_e32 v74, 16, v75
	v_and_b32_e32 v75, 0xffff0000, v75
	s_waitcnt lgkmcnt(0)
	v_add_f32_e32 v42, v42, v85
	v_mov_b32_e32 v87, v42
	s_nop 1
	v_permlane16_swap_b32 v42, v87
	v_and_b32_e32 v85, 0xffff0000, v76
	v_lshlrev_b32_e32 v76, 16, v77
	v_and_b32_e32 v77, 0xffff0000, v77
	s_waitcnt lgkmcnt(0)
	v_add_f32_e32 v42, v42, v87
	v_mov_b32_e32 v89, v42
	s_nop 1
	v_permlane32_swap_b32 v42, v89
	v_and_b32_e32 v87, 0xffff0000, v78
	v_lshlrev_b32_e32 v78, 16, v79
	v_and_b32_e32 v79, 0xffff0000, v79
	s_waitcnt lgkmcnt(0)
	v_add_f32_e32 v42, v42, v89
	v_fmamk_f32 v42, v42, 0x3a800000, v146
	v_mul_f32_e32 v89, 0x4b800000, v42
	v_cmp_gt_f32_e32 vcc, s97, v42
	s_nop 1
	v_cndmask_b32_e32 v42, v42, v89, vcc
	v_rsq_f32_e32 v42, v42
	v_and_b32_e32 v89, 0xffff0000, v72
	v_lshlrev_b32_e32 v72, 16, v73
	v_and_b32_e32 v73, 0xffff0000, v73
	v_mul_f32_e32 v90, 0x45800000, v42
	v_cndmask_b32_e32 v42, v42, v90, vcc
	v_pk_mul_f32 v[90:91], v[96:97], v[42:43] op_sel_hi:[1,0]
	v_pk_mul_f32 v[92:93], v[102:103], v[42:43] op_sel_hi:[1,0]
	v_pk_fma_f32 v[82:83], v[0:1], v[90:91], v[82:83]
	v_pk_fma_f32 v[74:75], v[2:3], v[92:93], v[74:75]
	v_pk_mul_f32 v[92:93], v[82:83], v[82:83]
	v_pk_mul_f32 v[90:91], v[74:75], v[74:75]
	v_pk_mul_f32 v[80:81], v[80:81], v[42:43] op_sel_hi:[1,0]
	v_pk_mov_b32 v[94:95], v[92:93], v[90:91] op_sel:[1,0]
	v_mov_b32_e32 v93, v91
	v_pk_add_f32 v[90:91], v[94:95], v[92:93]
	v_pk_mul_f32 v[92:93], v[130:131], v[42:43] op_sel_hi:[1,0]
	v_pk_mul_f32 v[94:95], v[116:117], v[42:43] op_sel_hi:[1,0]
	v_pk_fma_f32 v[76:77], v[6:7], v[92:93], v[76:77]
	v_pk_fma_f32 v[84:85], v[4:5], v[94:95], v[84:85]
	v_pk_mul_f32 v[92:93], v[76:77], v[76:77]
	v_pk_mul_f32 v[94:95], v[84:85], v[84:85]
	v_pk_add_f32 v[90:91], v[90:91], v[90:91] op_sel_hi:[0,1]
	v_pk_mov_b32 v[96:97], v[94:95], v[92:93] op_sel:[1,0]
	v_mov_b32_e32 v95, v93
	v_pk_add_f32 v[92:93], v[96:97], v[94:95]
	v_pk_mul_f32 v[96:97], v[134:135], v[42:43] op_sel_hi:[1,0]
	v_pk_mul_f32 v[94:95], v[100:101], v[42:43] op_sel_hi:[1,0]
	v_pk_fma_f32 v[86:87], v[16:17], v[96:97], v[86:87]
	v_pk_fma_f32 v[78:79], v[18:19], v[94:95], v[78:79]
	v_mul_f32_e32 v90, v86, v86
	v_pk_fma_f32 v[94:95], v[86:87], v[86:87], v[90:91] op_sel_hi:[1,1,0]
	v_mul_f32_e32 v90, v78, v78
	v_pk_mul_f32 v[98:99], v[104:105], v[42:43] op_sel_hi:[1,0]
	v_pk_add_f32 v[92:93], v[92:93], v[92:93] op_sel_hi:[0,1]
	v_pk_fma_f32 v[96:97], v[78:79], v[78:79], v[90:91] op_sel_hi:[1,1,0]
	v_pk_fma_f32 v[88:89], v[20:21], v[98:99], v[88:89]
	v_pk_fma_f32 v[72:73], v[22:23], v[80:81], v[72:73]
	v_mul_f32_e32 v94, v88, v88
	v_mul_f32_e32 v96, v89, v89
	v_mul_f32_e32 v90, v72, v72
	v_mul_f32_e32 v92, v73, v73
	v_pk_add_f32 v[80:81], v[94:95], v[96:97]
	v_pk_add_f32 v[90:91], v[90:91], v[92:93]
	v_cvt_pk_bf16_f32 v94, v82, v83
	v_lshl_add_u64 v[92:93], v[48:49], 0, s[68:69]
	v_pk_add_f32 v[80:81], v[80:81], v[90:91]
	s_nop 0
	v_add_f32_e32 v42, v80, v81
	s_nop 1
	v_mov_b32_dpp v80, v42 quad_perm:[1,0,3,2] row_mask:0xf bank_mask:0xf
	s_waitcnt lgkmcnt(0)
	v_add_f32_e32 v42, v42, v80
	s_nop 1
	v_mov_b32_dpp v80, v42 quad_perm:[2,3,0,1] row_mask:0xf bank_mask:0xf
	s_waitcnt lgkmcnt(0)
	v_add_f32_e32 v42, v42, v80
	s_nop 1
	v_mov_b32_dpp v90, v42 row_half_mirror row_mask:0xf bank_mask:0xf
	v_lshl_add_u64 v[80:81], v[48:49], 0, s[62:63]
	s_waitcnt lgkmcnt(0)
	v_add_f32_e32 v42, v42, v90
	s_nop 1
	v_mov_b32_dpp v95, v42 row_mirror row_mask:0xf bank_mask:0xf
	v_lshl_add_u64 v[90:91], v[48:49], 0, s[64:65]
	v_lshl_add_u64 v[48:49], v[48:49], 0, s[70:71]
	s_waitcnt lgkmcnt(0)
	v_add_f32_e32 v42, v42, v95
	v_mov_b32_e32 v96, v42
	s_nop 1
	v_permlane16_swap_b32 v42, v96
	v_cvt_pk_bf16_f32 v95, v74, v75
	s_waitcnt lgkmcnt(0)
	v_add_f32_e32 v42, v42, v96
	global_store_dwordx2 v[80:81], v[94:95], off sc0 sc1
	s_nop 1
	v_mov_b32_e32 v94, v42
	s_nop 1
	v_permlane32_swap_b32 v42, v94
	v_cvt_pk_bf16_f32 v80, v84, v85
	v_cvt_pk_bf16_f32 v81, v76, v77
	s_waitcnt lgkmcnt(0)
	v_add_f32_e32 v42, v42, v94
	global_store_dwordx2 v[90:91], v[80:81], off sc0 sc1
	s_nop 1
	v_cvt_pk_bf16_f32 v80, v86, v87
	v_fmamk_f32 v42, v42, 0x3a800000, v146
	v_cvt_pk_bf16_f32 v81, v78, v79
	v_cmp_gt_f32_e32 vcc, s97, v42
	global_store_dwordx2 v[92:93], v[80:81], off sc0 sc1
	s_nop 1
	v_mul_f32_e32 v80, 0x4b800000, v42
	s_nop 0
	v_cndmask_b32_e32 v42, v42, v80, vcc
	v_rsq_f32_e32 v42, v42
	v_cvt_pk_bf16_f32 v80, v88, v89
	v_cvt_pk_bf16_f32 v81, v72, v73
	s_nop 0
	global_store_dwordx2 v[48:49], v[80:81], off sc0 sc1
	s_nop 1
	v_mul_f32_e32 v48, 0x45800000, v42
	v_cndmask_b32_e32 v42, v42, v48, vcc
	v_pk_mul_f32 v[82:83], v[82:83], v[42:43] op_sel_hi:[1,0]
	v_pk_mul_f32 v[74:75], v[74:75], v[42:43] op_sel_hi:[1,0]
	v_pk_mul_f32 v[82:83], v[24:25], v[82:83]
	v_pk_mul_f32 v[74:75], v[26:27], v[74:75]
	v_cvt_pk_bf16_f32 v82, v82, v83
	v_lshl_add_u64 v[48:49], v[44:45], 0, s[82:83]
	v_cvt_pk_bf16_f32 v83, v74, v75
	v_pk_mul_f32 v[74:75], v[84:85], v[42:43] op_sel_hi:[1,0]
	v_pk_mul_f32 v[76:77], v[76:77], v[42:43] op_sel_hi:[1,0]
	v_pk_mul_f32 v[74:75], v[8:9], v[74:75]
	v_lshl_add_u64 v[80:81], v[48:49], 0, s[6:7]
	global_store_dwordx2 v[80:81], v[82:83], off sc0 sc1
	s_nop 1
	v_pk_mul_f32 v[76:77], v[10:11], v[76:77]
	v_cvt_pk_bf16_f32 v74, v74, v75
	s_mov_b64 s[6:7], 0x3800200
	v_cvt_pk_bf16_f32 v75, v76, v77
	v_lshl_add_u64 v[76:77], v[48:49], 0, s[6:7]
	global_store_dwordx2 v[76:77], v[74:75], off sc0 sc1
	s_nop 1
	v_pk_mul_f32 v[74:75], v[86:87], v[42:43] op_sel_hi:[1,0]
	v_pk_mul_f32 v[76:77], v[78:79], v[42:43] op_sel_hi:[1,0]
	v_pk_mul_f32 v[74:75], v[12:13], v[74:75]
	v_pk_mul_f32 v[76:77], v[14:15], v[76:77]
	v_cvt_pk_bf16_f32 v74, v74, v75
	s_mov_b64 s[6:7], 0x3800400
	v_cvt_pk_bf16_f32 v75, v76, v77
	v_lshl_add_u64 v[76:77], v[48:49], 0, s[6:7]
	global_store_dwordx2 v[76:77], v[74:75], off sc0 sc1
	s_nop 1
	v_pk_mul_f32 v[74:75], v[88:89], v[42:43] op_sel_hi:[1,0]
	v_pk_mul_f32 v[72:73], v[72:73], v[42:43] op_sel_hi:[1,0]
	v_pk_mul_f32 v[74:75], v[28:29], v[74:75]
	v_pk_mul_f32 v[72:73], v[30:31], v[72:73]
	s_mov_b64 s[6:7], 0x3800600
	v_cvt_pk_bf16_f32 v74, v74, v75
	v_cvt_pk_bf16_f32 v75, v72, v73
	v_lshl_add_u64 v[72:73], v[48:49], 0, s[6:7]
	global_store_dwordx2 v[72:73], v[74:75], off sc0 sc1
	s_nop 1
	s_mov_b64 s[6:7], -1
	s_cbranch_scc1 .LBB0_1405
	s_add_u32 s6, s16, s0
	s_addc_u32 s7, 0, s1
	s_add_u32 s8, s6, 1
	s_addc_u32 s9, s7, 0
	s_mov_b64 s[6:7], 0

.LBB0_1421:
	s_or_b64 exec, exec, s[10:11]
	s_lshl_b64 s[0:1], s[0:1], 12
	s_add_u32 s0, s8, s0
	s_addc_u32 s1, s9, s1
	v_lshl_add_u64 v[44:45], v[32:33], 3, s[0:1]
	s_lshl_b64 s[0:1], s[80:81], 11
	v_lshl_add_u64 v[54:55], v[38:39], 0, s[0:1]
	global_load_dwordx2 v[46:47], v[44:45], off offset:2048
	global_load_dwordx2 v[48:49], v[44:45], off offset:2560
	global_load_dwordx2 v[50:51], v[44:45], off offset:3072
	global_load_dwordx2 v[52:53], v[44:45], off offset:3584
	global_load_dwordx2 v[56:57], v[54:55], off
	global_load_dwordx2 v[58:59], v[54:55], off offset:512
	global_load_dwordx2 v[60:61], v[54:55], off offset:1024
	s_nop 0
	global_load_dwordx2 v[54:55], v[54:55], off offset:1536
	s_waitcnt vmcnt(8)
	s_nop 1
	v_mov_b32_dpp v62, v42 quad_perm:[1,0,3,2] row_mask:0xf bank_mask:0xf
	s_mov_b64 s[8:9], -1
	s_waitcnt lgkmcnt(0)
	v_add_f32_e32 v42, v42, v62
	s_nop 1
	v_mov_b32_dpp v62, v42 quad_perm:[2,3,0,1] row_mask:0xf bank_mask:0xf
	s_waitcnt lgkmcnt(0)
	v_add_f32_e32 v42, v42, v62
	s_nop 1
	v_mov_b32_dpp v62, v42 row_half_mirror row_mask:0xf bank_mask:0xf
	s_waitcnt lgkmcnt(0)
	v_add_f32_e32 v42, v42, v62
	s_nop 1
	v_mov_b32_dpp v62, v42 row_mirror row_mask:0xf bank_mask:0xf
	s_waitcnt lgkmcnt(0)
	v_add_f32_e32 v42, v42, v62
	v_mov_b32_e32 v62, v42
	s_nop 1
	v_permlane16_swap_b32 v42, v62
	s_waitcnt lgkmcnt(0)
	v_add_f32_e32 v42, v42, v62
	v_mov_b32_e32 v62, v42
	s_nop 1
	v_permlane32_swap_b32 v42, v62
	s_waitcnt lgkmcnt(0)
	v_add_f32_e32 v42, v42, v62
	v_fmamk_f32 v42, v42, 0x3a800000, v146
	v_mul_f32_e32 v62, 0x4b800000, v42
	v_cmp_gt_f32_e32 vcc, s97, v42
	s_waitcnt vmcnt(7)
	v_and_b32_e32 v63, 0xffff0000, v46
	v_cndmask_b32_e32 v42, v42, v62, vcc
	v_rsq_f32_e32 v42, v42
	s_waitcnt vmcnt(3)
	v_lshlrev_b32_e32 v70, 16, v56
	v_and_b32_e32 v71, 0xffff0000, v56
	v_lshlrev_b32_e32 v56, 16, v57
	v_mul_f32_e32 v62, 0x45800000, v42
	v_cndmask_b32_e32 v42, v42, v62, vcc
	v_and_b32_e32 v57, 0xffff0000, v57
	s_waitcnt vmcnt(2)
	v_lshlrev_b32_e32 v72, 16, v58
	v_and_b32_e32 v73, 0xffff0000, v58
	v_lshlrev_b32_e32 v58, 16, v59
	v_and_b32_e32 v59, 0xffff0000, v59
	v_lshlrev_b32_e32 v62, 16, v46
	v_lshlrev_b32_e32 v46, 16, v47
	v_and_b32_e32 v47, 0xffff0000, v47
	v_lshlrev_b32_e32 v64, 16, v48
	v_and_b32_e32 v65, 0xffff0000, v48
	v_lshlrev_b32_e32 v48, 16, v49
	v_and_b32_e32 v49, 0xffff0000, v49
	s_waitcnt vmcnt(1)
	v_lshlrev_b32_e32 v74, 16, v60
	v_and_b32_e32 v75, 0xffff0000, v60
	v_lshlrev_b32_e32 v60, 16, v61
	v_and_b32_e32 v61, 0xffff0000, v61
	v_pk_mul_f32 v[70:71], v[42:43], v[70:71] op_sel_hi:[0,1]
	v_pk_mul_f32 v[56:57], v[42:43], v[56:57] op_sel_hi:[0,1]
	v_pk_mul_f32 v[58:59], v[42:43], v[58:59] op_sel_hi:[0,1]
	v_pk_mul_f32 v[72:73], v[42:43], v[72:73] op_sel_hi:[0,1]
	v_lshlrev_b32_e32 v66, 16, v50
	v_and_b32_e32 v67, 0xffff0000, v50
	v_lshlrev_b32_e32 v50, 16, v51
	v_and_b32_e32 v51, 0xffff0000, v51
	v_pk_mul_f32 v[60:61], v[42:43], v[60:61] op_sel_hi:[0,1]
	v_pk_mul_f32 v[74:75], v[42:43], v[74:75] op_sel_hi:[0,1]
	v_pk_fma_f32 v[46:47], v[2:3], v[56:57], v[46:47]
	v_pk_fma_f32 v[56:57], v[0:1], v[70:71], v[62:63]
	v_pk_fma_f32 v[62:63], v[4:5], v[72:73], v[64:65]
	v_pk_fma_f32 v[48:49], v[6:7], v[58:59], v[48:49]
	v_pk_fma_f32 v[58:59], v[16:17], v[74:75], v[66:67]
	v_pk_fma_f32 v[50:51], v[18:19], v[60:61], v[50:51]
	v_pk_mul_f32 v[60:61], v[46:47], v[46:47]
	v_pk_mul_f32 v[64:65], v[56:57], v[56:57]
	v_pk_mul_f32 v[66:67], v[48:49], v[48:49]
	v_pk_mul_f32 v[70:71], v[62:63], v[62:63]
	v_pk_mov_b32 v[74:75], v[64:65], v[60:61] op_sel:[1,0]
	v_mov_b32_e32 v65, v61
	v_pk_mov_b32 v[60:61], v[70:71], v[66:67] op_sel:[1,0]
	v_mov_b32_e32 v71, v67
	v_pk_add_f32 v[60:61], v[60:61], v[70:71]
	s_waitcnt vmcnt(0)
	v_lshlrev_b32_e32 v76, 16, v54
	v_and_b32_e32 v77, 0xffff0000, v54
	v_lshlrev_b32_e32 v54, 16, v55
	v_and_b32_e32 v55, 0xffff0000, v55
	v_mul_f32_e32 v72, v58, v58
	v_pk_add_f32 v[60:61], v[60:61], v[60:61] op_sel_hi:[0,1]
	v_lshlrev_b32_e32 v68, 16, v52
	v_and_b32_e32 v69, 0xffff0000, v52
	v_lshlrev_b32_e32 v52, 16, v53
	v_and_b32_e32 v53, 0xffff0000, v53
	v_pk_fma_f32 v[66:67], v[58:59], v[58:59], v[72:73] op_sel_hi:[1,1,0]
	v_pk_add_f32 v[64:65], v[74:75], v[64:65]
	v_mul_f32_e32 v60, v50, v50
	v_pk_mul_f32 v[54:55], v[42:43], v[54:55] op_sel_hi:[0,1]
	v_pk_mul_f32 v[72:73], v[42:43], v[76:77] op_sel_hi:[0,1]
	v_pk_add_f32 v[64:65], v[64:65], v[64:65] op_sel_hi:[0,1]
	v_pk_fma_f32 v[70:71], v[50:51], v[50:51], v[60:61] op_sel_hi:[1,1,0]
	v_pk_fma_f32 v[68:69], v[20:21], v[72:73], v[68:69]
	v_pk_fma_f32 v[52:53], v[22:23], v[54:55], v[52:53]
	v_mul_f32_e32 v66, v68, v68
	v_mul_f32_e32 v70, v69, v69
	v_mul_f32_e32 v64, v52, v52
	v_mul_f32_e32 v60, v53, v53
	v_pk_add_f32 v[54:55], v[66:67], v[70:71]
	v_pk_add_f32 v[60:61], v[64:65], v[60:61]
	v_cvt_pk_bf16_f32 v66, v56, v57
	v_lshl_add_u64 v[64:65], v[44:45], 0, s[68:69]
	v_pk_add_f32 v[54:55], v[54:55], v[60:61]
	s_nop 0
	v_add_f32_e32 v42, v54, v55
	s_nop 1
	v_mov_b32_dpp v54, v42 quad_perm:[1,0,3,2] row_mask:0xf bank_mask:0xf
	s_waitcnt lgkmcnt(0)
	v_add_f32_e32 v42, v42, v54
	s_nop 1
	v_mov_b32_dpp v54, v42 quad_perm:[2,3,0,1] row_mask:0xf bank_mask:0xf
	s_waitcnt lgkmcnt(0)
	v_add_f32_e32 v42, v42, v54
	s_nop 1
	v_mov_b32_dpp v60, v42 row_half_mirror row_mask:0xf bank_mask:0xf
	v_lshl_add_u64 v[54:55], v[44:45], 0, s[62:63]
	s_waitcnt lgkmcnt(0)
	v_add_f32_e32 v42, v42, v60
	s_nop 1
	v_mov_b32_dpp v67, v42 row_mirror row_mask:0xf bank_mask:0xf
	v_lshl_add_u64 v[60:61], v[44:45], 0, s[64:65]
	v_lshl_add_u64 v[44:45], v[44:45], 0, s[70:71]
	s_waitcnt lgkmcnt(0)
	v_add_f32_e32 v42, v42, v67
	v_mov_b32_e32 v70, v42
	s_nop 1
	v_permlane16_swap_b32 v42, v70
	v_cvt_pk_bf16_f32 v67, v46, v47
	s_waitcnt lgkmcnt(0)
	v_add_f32_e32 v42, v42, v70
	global_store_dwordx2 v[54:55], v[66:67], off sc0 sc1
	s_nop 1
	v_mov_b32_e32 v66, v42
	s_nop 1
	v_permlane32_swap_b32 v42, v66
	v_cvt_pk_bf16_f32 v54, v62, v63
	v_cvt_pk_bf16_f32 v55, v48, v49
	s_waitcnt lgkmcnt(0)
	v_add_f32_e32 v42, v42, v66
	global_store_dwordx2 v[60:61], v[54:55], off sc0 sc1
	s_nop 1
	v_cvt_pk_bf16_f32 v54, v58, v59
	v_fmamk_f32 v42, v42, 0x3a800000, v146
	v_cvt_pk_bf16_f32 v55, v50, v51
	v_cmp_gt_f32_e32 vcc, s97, v42
	global_store_dwordx2 v[64:65], v[54:55], off sc0 sc1
	s_nop 1
	v_mul_f32_e32 v54, 0x4b800000, v42
	s_nop 0
	v_cndmask_b32_e32 v42, v42, v54, vcc
	v_rsq_f32_e32 v42, v42
	v_cvt_pk_bf16_f32 v54, v68, v69
	v_cvt_pk_bf16_f32 v55, v52, v53
	s_nop 0
	global_store_dwordx2 v[44:45], v[54:55], off sc0 sc1
	s_nop 1
	v_mul_f32_e32 v44, 0x45800000, v42
	v_cndmask_b32_e32 v42, v42, v44, vcc
	v_pk_mul_f32 v[54:55], v[56:57], v[42:43] op_sel_hi:[1,0]
	v_pk_mul_f32 v[46:47], v[46:47], v[42:43] op_sel_hi:[1,0]
	v_pk_mul_f32 v[54:55], v[24:25], v[54:55]
	v_pk_mul_f32 v[46:47], v[26:27], v[46:47]
	v_cvt_pk_bf16_f32 v54, v54, v55
	v_pk_mul_f32 v[48:49], v[48:49], v[42:43] op_sel_hi:[1,0]
	v_cvt_pk_bf16_f32 v55, v46, v47
	v_pk_mul_f32 v[46:47], v[62:63], v[42:43] op_sel_hi:[1,0]
	v_lshl_add_u64 v[44:45], v[36:37], 0, s[0:1]
	v_pk_mul_f32 v[46:47], v[8:9], v[46:47]
	global_store_dwordx2 v[44:45], v[54:55], off sc0 sc1
	s_nop 1
	v_pk_mul_f32 v[48:49], v[10:11], v[48:49]
	v_cvt_pk_bf16_f32 v46, v46, v47
	s_andn2_b64 vcc, exec, s[6:7]
	v_cvt_pk_bf16_f32 v47, v48, v49
	v_lshl_add_u64 v[48:49], v[44:45], 0, s[72:73]
	global_store_dwordx2 v[48:49], v[46:47], off sc0 sc1
	s_nop 1
	v_pk_mul_f32 v[46:47], v[58:59], v[42:43] op_sel_hi:[1,0]
	v_pk_mul_f32 v[48:49], v[50:51], v[42:43] op_sel_hi:[1,0]
	v_pk_mul_f32 v[46:47], v[12:13], v[46:47]
	v_pk_mul_f32 v[48:49], v[14:15], v[48:49]
	v_cvt_pk_bf16_f32 v46, v46, v47
	s_nop 0
	v_cvt_pk_bf16_f32 v47, v48, v49
	v_lshl_add_u64 v[48:49], v[44:45], 0, s[74:75]
	global_store_dwordx2 v[48:49], v[46:47], off sc0 sc1
	s_nop 1
	v_pk_mul_f32 v[46:47], v[68:69], v[42:43] op_sel_hi:[1,0]
	v_pk_mul_f32 v[48:49], v[52:53], v[42:43] op_sel_hi:[1,0]
	v_pk_mul_f32 v[46:47], v[28:29], v[46:47]
	v_pk_mul_f32 v[48:49], v[30:31], v[48:49]
	v_cvt_pk_bf16_f32 v46, v46, v47
	v_lshl_add_u64 v[44:45], v[44:45], 0, s[78:79]
	v_cvt_pk_bf16_f32 v47, v48, v49
	v_cndmask_b32_e64 v42, 0, 1, s[6:7]
	global_store_dwordx2 v[44:45], v[46:47], off sc0 sc1
	s_nop 1
	v_cmp_ne_u32_e64 s[0:1], 1, v42
	s_cbranch_vccnz .LBB0_1423
	s_add_i32 s56, s80, 0xffffbf81
	s_mov_b64 s[8:9], 0
	s_mov_b64 s[6:7], s[56:57]

.LBB0_1430:
	s_or_b64 exec, exec, s[10:11]
	s_lshl_b64 s[6:7], s[6:7], 12
	s_add_u32 s6, s8, s6
	s_addc_u32 s7, s9, s7
	v_lshl_add_u64 v[44:45], v[32:33], 3, s[6:7]
	s_lshl_b64 s[6:7], s[56:57], 11
	v_lshl_add_u64 v[54:55], v[38:39], 0, s[6:7]
	global_load_dwordx2 v[46:47], v[44:45], off offset:2048
	global_load_dwordx2 v[48:49], v[44:45], off offset:2560
	global_load_dwordx2 v[50:51], v[44:45], off offset:3072
	global_load_dwordx2 v[52:53], v[44:45], off offset:3584
	global_load_dwordx2 v[56:57], v[54:55], off
	global_load_dwordx2 v[58:59], v[54:55], off offset:512
	global_load_dwordx2 v[60:61], v[54:55], off offset:1024
	s_nop 0
	global_load_dwordx2 v[54:55], v[54:55], off offset:1536
	s_waitcnt vmcnt(8)
	s_nop 1
	v_mov_b32_dpp v62, v42 quad_perm:[1,0,3,2] row_mask:0xf bank_mask:0xf
	s_mov_b64 s[8:9], -1
	s_waitcnt lgkmcnt(0)
	v_add_f32_e32 v42, v42, v62
	s_nop 1
	v_mov_b32_dpp v62, v42 quad_perm:[2,3,0,1] row_mask:0xf bank_mask:0xf
	s_waitcnt lgkmcnt(0)
	v_add_f32_e32 v42, v42, v62
	s_nop 1
	v_mov_b32_dpp v62, v42 row_half_mirror row_mask:0xf bank_mask:0xf
	s_waitcnt lgkmcnt(0)
	v_add_f32_e32 v42, v42, v62
	s_nop 1
	v_mov_b32_dpp v62, v42 row_mirror row_mask:0xf bank_mask:0xf
	s_waitcnt lgkmcnt(0)
	v_add_f32_e32 v42, v42, v62
	v_mov_b32_e32 v62, v42
	s_nop 1
	v_permlane16_swap_b32 v42, v62
	s_waitcnt lgkmcnt(0)
	v_add_f32_e32 v42, v42, v62
	v_mov_b32_e32 v62, v42
	s_nop 1
	v_permlane32_swap_b32 v42, v62
	s_waitcnt lgkmcnt(0)
	v_add_f32_e32 v42, v42, v62
	v_fmamk_f32 v42, v42, 0x3a800000, v146
	v_mul_f32_e32 v62, 0x4b800000, v42
	v_cmp_gt_f32_e32 vcc, s97, v42
	s_waitcnt vmcnt(7)
	v_and_b32_e32 v63, 0xffff0000, v46
	v_cndmask_b32_e32 v42, v42, v62, vcc
	v_rsq_f32_e32 v42, v42
	s_waitcnt vmcnt(3)
	v_lshlrev_b32_e32 v70, 16, v56
	v_and_b32_e32 v71, 0xffff0000, v56
	v_lshlrev_b32_e32 v56, 16, v57
	v_mul_f32_e32 v62, 0x45800000, v42
	v_cndmask_b32_e32 v42, v42, v62, vcc
	v_and_b32_e32 v57, 0xffff0000, v57
	s_waitcnt vmcnt(2)
	v_lshlrev_b32_e32 v72, 16, v58
	v_and_b32_e32 v73, 0xffff0000, v58
	v_lshlrev_b32_e32 v58, 16, v59
	v_and_b32_e32 v59, 0xffff0000, v59
	v_lshlrev_b32_e32 v62, 16, v46
	v_lshlrev_b32_e32 v46, 16, v47
	v_and_b32_e32 v47, 0xffff0000, v47
	v_lshlrev_b32_e32 v64, 16, v48
	v_and_b32_e32 v65, 0xffff0000, v48
	v_lshlrev_b32_e32 v48, 16, v49
	v_and_b32_e32 v49, 0xffff0000, v49
	s_waitcnt vmcnt(1)
	v_lshlrev_b32_e32 v74, 16, v60
	v_and_b32_e32 v75, 0xffff0000, v60
	v_lshlrev_b32_e32 v60, 16, v61
	v_and_b32_e32 v61, 0xffff0000, v61
	v_pk_mul_f32 v[70:71], v[42:43], v[70:71] op_sel_hi:[0,1]
	v_pk_mul_f32 v[56:57], v[42:43], v[56:57] op_sel_hi:[0,1]
	v_pk_mul_f32 v[58:59], v[42:43], v[58:59] op_sel_hi:[0,1]
	v_pk_mul_f32 v[72:73], v[42:43], v[72:73] op_sel_hi:[0,1]
	v_lshlrev_b32_e32 v66, 16, v50
	v_and_b32_e32 v67, 0xffff0000, v50
	v_lshlrev_b32_e32 v50, 16, v51
	v_and_b32_e32 v51, 0xffff0000, v51
	v_pk_mul_f32 v[60:61], v[42:43], v[60:61] op_sel_hi:[0,1]
	v_pk_mul_f32 v[74:75], v[42:43], v[74:75] op_sel_hi:[0,1]
	v_pk_fma_f32 v[46:47], v[2:3], v[56:57], v[46:47]
	v_pk_fma_f32 v[56:57], v[0:1], v[70:71], v[62:63]
	v_pk_fma_f32 v[62:63], v[4:5], v[72:73], v[64:65]
	v_pk_fma_f32 v[48:49], v[6:7], v[58:59], v[48:49]
	v_pk_fma_f32 v[58:59], v[16:17], v[74:75], v[66:67]
	v_pk_fma_f32 v[50:51], v[18:19], v[60:61], v[50:51]
	v_pk_mul_f32 v[60:61], v[46:47], v[46:47]
	v_pk_mul_f32 v[64:65], v[56:57], v[56:57]
	v_pk_mul_f32 v[66:67], v[48:49], v[48:49]
	v_pk_mul_f32 v[70:71], v[62:63], v[62:63]
	v_pk_mov_b32 v[74:75], v[64:65], v[60:61] op_sel:[1,0]
	v_mov_b32_e32 v65, v61
	v_pk_mov_b32 v[60:61], v[70:71], v[66:67] op_sel:[1,0]
	v_mov_b32_e32 v71, v67
	v_pk_add_f32 v[60:61], v[60:61], v[70:71]
	s_waitcnt vmcnt(0)
	v_lshlrev_b32_e32 v76, 16, v54
	v_and_b32_e32 v77, 0xffff0000, v54
	v_lshlrev_b32_e32 v54, 16, v55
	v_and_b32_e32 v55, 0xffff0000, v55
	v_mul_f32_e32 v72, v58, v58
	v_pk_add_f32 v[60:61], v[60:61], v[60:61] op_sel_hi:[0,1]
	v_lshlrev_b32_e32 v68, 16, v52
	v_and_b32_e32 v69, 0xffff0000, v52
	v_lshlrev_b32_e32 v52, 16, v53
	v_and_b32_e32 v53, 0xffff0000, v53
	v_pk_fma_f32 v[66:67], v[58:59], v[58:59], v[72:73] op_sel_hi:[1,1,0]
	v_pk_add_f32 v[64:65], v[74:75], v[64:65]
	v_mul_f32_e32 v60, v50, v50
	v_pk_mul_f32 v[54:55], v[42:43], v[54:55] op_sel_hi:[0,1]
	v_pk_mul_f32 v[72:73], v[42:43], v[76:77] op_sel_hi:[0,1]
	v_pk_add_f32 v[64:65], v[64:65], v[64:65] op_sel_hi:[0,1]
	v_pk_fma_f32 v[70:71], v[50:51], v[50:51], v[60:61] op_sel_hi:[1,1,0]
	v_pk_fma_f32 v[68:69], v[20:21], v[72:73], v[68:69]
	v_pk_fma_f32 v[52:53], v[22:23], v[54:55], v[52:53]
	v_mul_f32_e32 v66, v68, v68
	v_mul_f32_e32 v70, v69, v69
	v_mul_f32_e32 v64, v52, v52
	v_mul_f32_e32 v60, v53, v53
	v_pk_add_f32 v[54:55], v[66:67], v[70:71]
	v_pk_add_f32 v[60:61], v[64:65], v[60:61]
	v_cvt_pk_bf16_f32 v66, v56, v57
	v_lshl_add_u64 v[64:65], v[44:45], 0, s[68:69]
	v_pk_add_f32 v[54:55], v[54:55], v[60:61]
	s_nop 0
	v_add_f32_e32 v42, v54, v55
	s_nop 1
	v_mov_b32_dpp v54, v42 quad_perm:[1,0,3,2] row_mask:0xf bank_mask:0xf
	s_waitcnt lgkmcnt(0)
	v_add_f32_e32 v42, v42, v54
	s_nop 1
	v_mov_b32_dpp v54, v42 quad_perm:[2,3,0,1] row_mask:0xf bank_mask:0xf
	s_waitcnt lgkmcnt(0)
	v_add_f32_e32 v42, v42, v54
	s_nop 1
	v_mov_b32_dpp v60, v42 row_half_mirror row_mask:0xf bank_mask:0xf
	v_lshl_add_u64 v[54:55], v[44:45], 0, s[62:63]
	s_waitcnt lgkmcnt(0)
	v_add_f32_e32 v42, v42, v60
	s_nop 1
	v_mov_b32_dpp v67, v42 row_mirror row_mask:0xf bank_mask:0xf
	v_lshl_add_u64 v[60:61], v[44:45], 0, s[64:65]
	v_lshl_add_u64 v[44:45], v[44:45], 0, s[70:71]
	s_waitcnt lgkmcnt(0)
	v_add_f32_e32 v42, v42, v67
	v_mov_b32_e32 v70, v42
	s_nop 1
	v_permlane16_swap_b32 v42, v70
	v_cvt_pk_bf16_f32 v67, v46, v47
	s_waitcnt lgkmcnt(0)
	v_add_f32_e32 v42, v42, v70
	global_store_dwordx2 v[54:55], v[66:67], off sc0 sc1
	s_nop 1
	v_mov_b32_e32 v66, v42
	s_nop 1
	v_permlane32_swap_b32 v42, v66
	v_cvt_pk_bf16_f32 v54, v62, v63
	v_cvt_pk_bf16_f32 v55, v48, v49
	s_waitcnt lgkmcnt(0)
	v_add_f32_e32 v42, v42, v66
	global_store_dwordx2 v[60:61], v[54:55], off sc0 sc1
	s_nop 1
	v_cvt_pk_bf16_f32 v54, v58, v59
	v_fmamk_f32 v42, v42, 0x3a800000, v146
	v_cvt_pk_bf16_f32 v55, v50, v51
	v_cmp_gt_f32_e32 vcc, s97, v42
	global_store_dwordx2 v[64:65], v[54:55], off sc0 sc1
	s_nop 1
	v_mul_f32_e32 v54, 0x4b800000, v42
	s_nop 0
	v_cndmask_b32_e32 v42, v42, v54, vcc
	v_rsq_f32_e32 v42, v42
	v_cvt_pk_bf16_f32 v54, v68, v69
	v_cvt_pk_bf16_f32 v55, v52, v53
	s_nop 0
	global_store_dwordx2 v[44:45], v[54:55], off sc0 sc1
	s_nop 1
	v_mul_f32_e32 v44, 0x45800000, v42
	v_cndmask_b32_e32 v42, v42, v44, vcc
	v_pk_mul_f32 v[54:55], v[56:57], v[42:43] op_sel_hi:[1,0]
	v_pk_mul_f32 v[46:47], v[46:47], v[42:43] op_sel_hi:[1,0]
	v_pk_mul_f32 v[54:55], v[24:25], v[54:55]
	v_pk_mul_f32 v[46:47], v[26:27], v[46:47]
	v_cvt_pk_bf16_f32 v54, v54, v55
	v_pk_mul_f32 v[48:49], v[48:49], v[42:43] op_sel_hi:[1,0]
	v_cvt_pk_bf16_f32 v55, v46, v47
	v_pk_mul_f32 v[46:47], v[62:63], v[42:43] op_sel_hi:[1,0]
	v_lshl_add_u64 v[44:45], v[36:37], 0, s[6:7]
	v_pk_mul_f32 v[46:47], v[8:9], v[46:47]
	global_store_dwordx2 v[44:45], v[54:55], off sc0 sc1
	s_nop 1
	v_pk_mul_f32 v[48:49], v[10:11], v[48:49]
	v_cvt_pk_bf16_f32 v46, v46, v47
	s_and_b64 vcc, exec, s[0:1]
	v_cvt_pk_bf16_f32 v47, v48, v49
	v_lshl_add_u64 v[48:49], v[44:45], 0, s[72:73]
	global_store_dwordx2 v[48:49], v[46:47], off sc0 sc1
	s_nop 1
	v_pk_mul_f32 v[46:47], v[58:59], v[42:43] op_sel_hi:[1,0]
	v_pk_mul_f32 v[48:49], v[50:51], v[42:43] op_sel_hi:[1,0]
	v_pk_mul_f32 v[46:47], v[12:13], v[46:47]
	v_pk_mul_f32 v[48:49], v[14:15], v[48:49]
	v_cvt_pk_bf16_f32 v46, v46, v47
	s_nop 0
	v_cvt_pk_bf16_f32 v47, v48, v49
	v_lshl_add_u64 v[48:49], v[44:45], 0, s[74:75]
	global_store_dwordx2 v[48:49], v[46:47], off sc0 sc1
	s_nop 1
	v_pk_mul_f32 v[46:47], v[68:69], v[42:43] op_sel_hi:[1,0]
	v_pk_mul_f32 v[48:49], v[52:53], v[42:43] op_sel_hi:[1,0]
	v_pk_mul_f32 v[46:47], v[28:29], v[46:47]
	v_pk_mul_f32 v[48:49], v[30:31], v[48:49]
	v_cvt_pk_bf16_f32 v46, v46, v47
	v_lshl_add_u64 v[44:45], v[44:45], 0, s[78:79]
	v_cvt_pk_bf16_f32 v47, v48, v49
	s_nop 0
	global_store_dwordx2 v[44:45], v[46:47], off sc0 sc1
	s_nop 1
	s_cbranch_vccnz .LBB0_1432
	s_add_i32 s56, s80, 0xffffbf82
	s_mov_b64 s[8:9], 0
	s_mov_b64 s[6:7], s[56:57]

.LBB0_1439:
	s_or_b64 exec, exec, s[10:11]
	s_lshl_b64 s[6:7], s[6:7], 12
	s_add_u32 s6, s8, s6
	s_addc_u32 s7, s9, s7
	v_lshl_add_u64 v[44:45], v[32:33], 3, s[6:7]
	s_lshl_b64 s[6:7], s[56:57], 11
	v_lshl_add_u64 v[54:55], v[38:39], 0, s[6:7]
	global_load_dwordx2 v[46:47], v[44:45], off offset:2048
	global_load_dwordx2 v[48:49], v[44:45], off offset:2560
	global_load_dwordx2 v[50:51], v[44:45], off offset:3072
	global_load_dwordx2 v[52:53], v[44:45], off offset:3584
	global_load_dwordx2 v[56:57], v[54:55], off
	global_load_dwordx2 v[58:59], v[54:55], off offset:512
	global_load_dwordx2 v[60:61], v[54:55], off offset:1024
	s_nop 0
	global_load_dwordx2 v[54:55], v[54:55], off offset:1536
	s_waitcnt vmcnt(8)
	s_nop 1
	v_mov_b32_dpp v62, v42 quad_perm:[1,0,3,2] row_mask:0xf bank_mask:0xf
	s_waitcnt lgkmcnt(0)
	v_add_f32_e32 v42, v42, v62
	s_nop 1
	v_mov_b32_dpp v62, v42 quad_perm:[2,3,0,1] row_mask:0xf bank_mask:0xf
	s_waitcnt lgkmcnt(0)
	v_add_f32_e32 v42, v42, v62
	s_nop 1
	v_mov_b32_dpp v62, v42 row_half_mirror row_mask:0xf bank_mask:0xf
	s_waitcnt lgkmcnt(0)
	v_add_f32_e32 v42, v42, v62
	s_nop 1
	v_mov_b32_dpp v62, v42 row_mirror row_mask:0xf bank_mask:0xf
	s_waitcnt lgkmcnt(0)
	v_add_f32_e32 v42, v42, v62
	v_mov_b32_e32 v62, v42
	s_nop 1
	v_permlane16_swap_b32 v42, v62
	s_waitcnt lgkmcnt(0)
	v_add_f32_e32 v42, v42, v62
	v_mov_b32_e32 v62, v42
	s_nop 1
	v_permlane32_swap_b32 v42, v62
	s_waitcnt lgkmcnt(0)
	v_add_f32_e32 v42, v42, v62
	v_fmamk_f32 v42, v42, 0x3a800000, v146
	v_mul_f32_e32 v62, 0x4b800000, v42
	v_cmp_gt_f32_e32 vcc, s97, v42
	s_waitcnt vmcnt(7)
	v_and_b32_e32 v63, 0xffff0000, v46
	v_cndmask_b32_e32 v42, v42, v62, vcc
	v_rsq_f32_e32 v42, v42
	s_waitcnt vmcnt(3)
	v_lshlrev_b32_e32 v70, 16, v56
	v_and_b32_e32 v71, 0xffff0000, v56
	v_lshlrev_b32_e32 v56, 16, v57
	v_mul_f32_e32 v62, 0x45800000, v42
	v_cndmask_b32_e32 v42, v42, v62, vcc
	v_and_b32_e32 v57, 0xffff0000, v57
	s_waitcnt vmcnt(2)
	v_lshlrev_b32_e32 v72, 16, v58
	v_and_b32_e32 v73, 0xffff0000, v58
	v_lshlrev_b32_e32 v58, 16, v59
	v_and_b32_e32 v59, 0xffff0000, v59
	v_lshlrev_b32_e32 v62, 16, v46
	v_lshlrev_b32_e32 v46, 16, v47
	v_and_b32_e32 v47, 0xffff0000, v47
	v_lshlrev_b32_e32 v64, 16, v48
	v_and_b32_e32 v65, 0xffff0000, v48
	v_lshlrev_b32_e32 v48, 16, v49
	v_and_b32_e32 v49, 0xffff0000, v49
	s_waitcnt vmcnt(1)
	v_lshlrev_b32_e32 v74, 16, v60
	v_and_b32_e32 v75, 0xffff0000, v60
	v_lshlrev_b32_e32 v60, 16, v61
	v_and_b32_e32 v61, 0xffff0000, v61
	v_pk_mul_f32 v[70:71], v[42:43], v[70:71] op_sel_hi:[0,1]
	v_pk_mul_f32 v[56:57], v[42:43], v[56:57] op_sel_hi:[0,1]
	v_pk_mul_f32 v[58:59], v[42:43], v[58:59] op_sel_hi:[0,1]
	v_pk_mul_f32 v[72:73], v[42:43], v[72:73] op_sel_hi:[0,1]
	v_lshlrev_b32_e32 v66, 16, v50
	v_and_b32_e32 v67, 0xffff0000, v50
	v_lshlrev_b32_e32 v50, 16, v51
	v_and_b32_e32 v51, 0xffff0000, v51
	v_pk_mul_f32 v[60:61], v[42:43], v[60:61] op_sel_hi:[0,1]
	v_pk_mul_f32 v[74:75], v[42:43], v[74:75] op_sel_hi:[0,1]
	v_pk_fma_f32 v[46:47], v[2:3], v[56:57], v[46:47]
	v_pk_fma_f32 v[56:57], v[0:1], v[70:71], v[62:63]
	v_pk_fma_f32 v[62:63], v[4:5], v[72:73], v[64:65]
	v_pk_fma_f32 v[48:49], v[6:7], v[58:59], v[48:49]
	v_pk_fma_f32 v[58:59], v[16:17], v[74:75], v[66:67]
	v_pk_fma_f32 v[50:51], v[18:19], v[60:61], v[50:51]
	v_pk_mul_f32 v[60:61], v[46:47], v[46:47]
	v_pk_mul_f32 v[64:65], v[56:57], v[56:57]
	v_pk_mul_f32 v[66:67], v[48:49], v[48:49]
	v_pk_mul_f32 v[70:71], v[62:63], v[62:63]
	v_pk_mov_b32 v[74:75], v[64:65], v[60:61] op_sel:[1,0]
	v_mov_b32_e32 v65, v61
	v_pk_mov_b32 v[60:61], v[70:71], v[66:67] op_sel:[1,0]
	v_mov_b32_e32 v71, v67
	v_pk_add_f32 v[60:61], v[60:61], v[70:71]
	s_waitcnt vmcnt(0)
	v_lshlrev_b32_e32 v76, 16, v54
	v_and_b32_e32 v77, 0xffff0000, v54
	v_lshlrev_b32_e32 v54, 16, v55
	v_and_b32_e32 v55, 0xffff0000, v55
	v_mul_f32_e32 v72, v58, v58
	v_pk_add_f32 v[60:61], v[60:61], v[60:61] op_sel_hi:[0,1]
	v_lshlrev_b32_e32 v68, 16, v52
	v_and_b32_e32 v69, 0xffff0000, v52
	v_lshlrev_b32_e32 v52, 16, v53
	v_and_b32_e32 v53, 0xffff0000, v53
	v_pk_fma_f32 v[66:67], v[58:59], v[58:59], v[72:73] op_sel_hi:[1,1,0]
	v_pk_add_f32 v[64:65], v[74:75], v[64:65]
	v_mul_f32_e32 v60, v50, v50
	v_pk_mul_f32 v[54:55], v[42:43], v[54:55] op_sel_hi:[0,1]
	v_pk_mul_f32 v[72:73], v[42:43], v[76:77] op_sel_hi:[0,1]
	v_pk_add_f32 v[64:65], v[64:65], v[64:65] op_sel_hi:[0,1]
	v_pk_fma_f32 v[70:71], v[50:51], v[50:51], v[60:61] op_sel_hi:[1,1,0]
	v_pk_fma_f32 v[68:69], v[20:21], v[72:73], v[68:69]
	v_pk_fma_f32 v[52:53], v[22:23], v[54:55], v[52:53]
	v_mul_f32_e32 v66, v68, v68
	v_mul_f32_e32 v70, v69, v69
	v_mul_f32_e32 v64, v52, v52
	v_mul_f32_e32 v60, v53, v53
	v_pk_add_f32 v[54:55], v[66:67], v[70:71]
	v_pk_add_f32 v[60:61], v[64:65], v[60:61]
	v_cvt_pk_bf16_f32 v66, v56, v57
	v_lshl_add_u64 v[64:65], v[44:45], 0, s[68:69]
	v_pk_add_f32 v[54:55], v[54:55], v[60:61]
	s_nop 0
	v_add_f32_e32 v42, v54, v55
	s_nop 1
	v_mov_b32_dpp v54, v42 quad_perm:[1,0,3,2] row_mask:0xf bank_mask:0xf
	s_waitcnt lgkmcnt(0)
	v_add_f32_e32 v42, v42, v54
	s_nop 1
	v_mov_b32_dpp v54, v42 quad_perm:[2,3,0,1] row_mask:0xf bank_mask:0xf
	s_waitcnt lgkmcnt(0)
	v_add_f32_e32 v42, v42, v54
	s_nop 1
	v_mov_b32_dpp v60, v42 row_half_mirror row_mask:0xf bank_mask:0xf
	v_lshl_add_u64 v[54:55], v[44:45], 0, s[62:63]
	s_waitcnt lgkmcnt(0)
	v_add_f32_e32 v42, v42, v60
	s_nop 1
	v_mov_b32_dpp v67, v42 row_mirror row_mask:0xf bank_mask:0xf
	v_lshl_add_u64 v[60:61], v[44:45], 0, s[64:65]
	v_lshl_add_u64 v[44:45], v[44:45], 0, s[70:71]
	s_waitcnt lgkmcnt(0)
	v_add_f32_e32 v42, v42, v67
	v_mov_b32_e32 v70, v42
	s_nop 1
	v_permlane16_swap_b32 v42, v70
	v_cvt_pk_bf16_f32 v67, v46, v47
	s_waitcnt lgkmcnt(0)
	v_add_f32_e32 v42, v42, v70
	global_store_dwordx2 v[54:55], v[66:67], off sc0 sc1
	s_nop 1
	v_mov_b32_e32 v66, v42
	s_nop 1
	v_permlane32_swap_b32 v42, v66
	v_cvt_pk_bf16_f32 v54, v62, v63
	v_cvt_pk_bf16_f32 v55, v48, v49
	s_waitcnt lgkmcnt(0)
	v_add_f32_e32 v42, v42, v66
	global_store_dwordx2 v[60:61], v[54:55], off sc0 sc1
	s_nop 1
	v_cvt_pk_bf16_f32 v54, v58, v59
	v_fmamk_f32 v42, v42, 0x3a800000, v146
	v_cvt_pk_bf16_f32 v55, v50, v51
	v_cmp_gt_f32_e32 vcc, s97, v42
	global_store_dwordx2 v[64:65], v[54:55], off sc0 sc1
	s_nop 1
	v_mul_f32_e32 v54, 0x4b800000, v42
	s_nop 0
	v_cndmask_b32_e32 v42, v42, v54, vcc
	v_rsq_f32_e32 v42, v42
	v_cvt_pk_bf16_f32 v54, v68, v69
	v_cvt_pk_bf16_f32 v55, v52, v53
	s_nop 0
	global_store_dwordx2 v[44:45], v[54:55], off sc0 sc1
	s_nop 1
	v_mul_f32_e32 v44, 0x45800000, v42
	v_cndmask_b32_e32 v42, v42, v44, vcc
	v_pk_mul_f32 v[54:55], v[56:57], v[42:43] op_sel_hi:[1,0]
	v_pk_mul_f32 v[46:47], v[46:47], v[42:43] op_sel_hi:[1,0]
	v_pk_mul_f32 v[54:55], v[24:25], v[54:55]
	v_pk_mul_f32 v[46:47], v[26:27], v[46:47]
	v_cvt_pk_bf16_f32 v54, v54, v55
	v_pk_mul_f32 v[48:49], v[48:49], v[42:43] op_sel_hi:[1,0]
	v_cvt_pk_bf16_f32 v55, v46, v47
	v_pk_mul_f32 v[46:47], v[62:63], v[42:43] op_sel_hi:[1,0]
	v_lshl_add_u64 v[44:45], v[36:37], 0, s[6:7]
	v_pk_mul_f32 v[46:47], v[8:9], v[46:47]
	global_store_dwordx2 v[44:45], v[54:55], off sc0 sc1
	s_nop 1
	v_pk_mul_f32 v[48:49], v[10:11], v[48:49]
	v_cvt_pk_bf16_f32 v46, v46, v47
	s_and_b64 vcc, exec, s[0:1]
	v_cvt_pk_bf16_f32 v47, v48, v49
	v_lshl_add_u64 v[48:49], v[44:45], 0, s[72:73]
	global_store_dwordx2 v[48:49], v[46:47], off sc0 sc1
	s_nop 1
	v_pk_mul_f32 v[46:47], v[58:59], v[42:43] op_sel_hi:[1,0]
	v_pk_mul_f32 v[48:49], v[50:51], v[42:43] op_sel_hi:[1,0]
	v_pk_mul_f32 v[46:47], v[12:13], v[46:47]
	v_pk_mul_f32 v[48:49], v[14:15], v[48:49]
	v_cvt_pk_bf16_f32 v46, v46, v47
	s_mov_b64 s[6:7], -1
	v_cvt_pk_bf16_f32 v47, v48, v49
	v_lshl_add_u64 v[48:49], v[44:45], 0, s[74:75]
	global_store_dwordx2 v[48:49], v[46:47], off sc0 sc1
	s_nop 1
	v_pk_mul_f32 v[46:47], v[68:69], v[42:43] op_sel_hi:[1,0]
	v_pk_mul_f32 v[48:49], v[52:53], v[42:43] op_sel_hi:[1,0]
	v_pk_mul_f32 v[46:47], v[28:29], v[46:47]
	v_pk_mul_f32 v[48:49], v[30:31], v[48:49]
	v_cvt_pk_bf16_f32 v46, v46, v47
	v_lshl_add_u64 v[44:45], v[44:45], 0, s[78:79]
	v_cvt_pk_bf16_f32 v47, v48, v49
	s_nop 0
	global_store_dwordx2 v[44:45], v[46:47], off sc0 sc1
	s_nop 1
	s_cbranch_vccnz .LBB0_1441
	s_add_i32 s56, s80, 0xffffbf83
	s_mov_b64 s[6:7], 0
	s_mov_b64 s[0:1], s[56:57]

.LBB0_1964:
	s_or_b64 exec, exec, s[10:11]
	s_lshl_b64 s[0:1], s[0:1], 12
	s_add_u32 s0, s6, s0
	s_addc_u32 s1, s7, s1
	v_lshl_add_u64 v[44:45], v[32:33], 3, s[0:1]
	s_lshl_b64 s[0:1], s[14:15], 11
	v_lshl_add_u64 v[54:55], v[38:39], 0, s[0:1]
	global_load_dwordx2 v[46:47], v[44:45], off offset:2048
	global_load_dwordx2 v[48:49], v[44:45], off offset:2560
	global_load_dwordx2 v[50:51], v[44:45], off offset:3072
	global_load_dwordx2 v[52:53], v[44:45], off offset:3584
	global_load_dwordx2 v[56:57], v[54:55], off
	global_load_dwordx2 v[58:59], v[54:55], off offset:512
	global_load_dwordx2 v[60:61], v[54:55], off offset:1024
	s_nop 0
	global_load_dwordx2 v[54:55], v[54:55], off offset:1536
	s_waitcnt vmcnt(8)
	s_nop 1
	v_mov_b32_dpp v62, v42 quad_perm:[1,0,3,2] row_mask:0xf bank_mask:0xf
	s_waitcnt lgkmcnt(0)
	v_add_f32_e32 v42, v42, v62
	s_nop 1
	v_mov_b32_dpp v62, v42 quad_perm:[2,3,0,1] row_mask:0xf bank_mask:0xf
	s_waitcnt lgkmcnt(0)
	v_add_f32_e32 v42, v42, v62
	s_nop 1
	v_mov_b32_dpp v62, v42 row_half_mirror row_mask:0xf bank_mask:0xf
	s_waitcnt lgkmcnt(0)
	v_add_f32_e32 v42, v42, v62
	s_nop 1
	v_mov_b32_dpp v62, v42 row_mirror row_mask:0xf bank_mask:0xf
	s_waitcnt lgkmcnt(0)
	v_add_f32_e32 v42, v42, v62
	v_mov_b32_e32 v62, v42
	s_nop 1
	v_permlane16_swap_b32 v42, v62
	s_waitcnt lgkmcnt(0)
	v_add_f32_e32 v42, v42, v62
	v_mov_b32_e32 v62, v42
	s_nop 1
	v_permlane32_swap_b32 v42, v62
	s_waitcnt lgkmcnt(0)
	v_add_f32_e32 v42, v42, v62
	v_fmamk_f32 v42, v42, 0x3a800000, v90
	v_mul_f32_e32 v62, 0x4b800000, v42
	v_cmp_gt_f32_e32 vcc, s91, v42
	s_waitcnt vmcnt(7)
	v_and_b32_e32 v63, 0xffff0000, v46
	v_cndmask_b32_e32 v42, v42, v62, vcc
	v_rsq_f32_e32 v42, v42
	s_waitcnt vmcnt(3)
	v_lshlrev_b32_e32 v70, 16, v56
	v_and_b32_e32 v71, 0xffff0000, v56
	v_lshlrev_b32_e32 v56, 16, v57
	v_mul_f32_e32 v62, 0x45800000, v42
	v_cndmask_b32_e32 v42, v42, v62, vcc
	v_and_b32_e32 v57, 0xffff0000, v57
	s_waitcnt vmcnt(2)
	v_lshlrev_b32_e32 v72, 16, v58
	v_and_b32_e32 v73, 0xffff0000, v58
	v_lshlrev_b32_e32 v58, 16, v59
	v_and_b32_e32 v59, 0xffff0000, v59
	v_lshlrev_b32_e32 v62, 16, v46
	v_lshlrev_b32_e32 v46, 16, v47
	v_and_b32_e32 v47, 0xffff0000, v47
	v_lshlrev_b32_e32 v64, 16, v48
	v_and_b32_e32 v65, 0xffff0000, v48
	v_lshlrev_b32_e32 v48, 16, v49
	v_and_b32_e32 v49, 0xffff0000, v49
	s_waitcnt vmcnt(1)
	v_lshlrev_b32_e32 v74, 16, v60
	v_and_b32_e32 v75, 0xffff0000, v60
	v_lshlrev_b32_e32 v60, 16, v61
	v_and_b32_e32 v61, 0xffff0000, v61
	v_pk_mul_f32 v[70:71], v[42:43], v[70:71] op_sel_hi:[0,1]
	v_pk_mul_f32 v[56:57], v[42:43], v[56:57] op_sel_hi:[0,1]
	v_pk_mul_f32 v[58:59], v[42:43], v[58:59] op_sel_hi:[0,1]
	v_pk_mul_f32 v[72:73], v[42:43], v[72:73] op_sel_hi:[0,1]
	v_lshlrev_b32_e32 v66, 16, v50
	v_and_b32_e32 v67, 0xffff0000, v50
	v_lshlrev_b32_e32 v50, 16, v51
	v_and_b32_e32 v51, 0xffff0000, v51
	v_pk_mul_f32 v[60:61], v[42:43], v[60:61] op_sel_hi:[0,1]
	v_pk_mul_f32 v[74:75], v[42:43], v[74:75] op_sel_hi:[0,1]
	v_pk_fma_f32 v[46:47], v[2:3], v[56:57], v[46:47]
	v_pk_fma_f32 v[56:57], v[0:1], v[70:71], v[62:63]
	v_pk_fma_f32 v[62:63], v[8:9], v[72:73], v[64:65]
	v_pk_fma_f32 v[48:49], v[10:11], v[58:59], v[48:49]
	v_pk_fma_f32 v[58:59], v[12:13], v[74:75], v[66:67]
	v_pk_fma_f32 v[50:51], v[14:15], v[60:61], v[50:51]
	v_pk_mul_f32 v[60:61], v[46:47], v[46:47]
	v_pk_mul_f32 v[64:65], v[56:57], v[56:57]
	v_pk_mul_f32 v[66:67], v[48:49], v[48:49]
	v_pk_mul_f32 v[70:71], v[62:63], v[62:63]
	v_pk_mov_b32 v[74:75], v[64:65], v[60:61] op_sel:[1,0]
	v_mov_b32_e32 v65, v61
	v_pk_mov_b32 v[60:61], v[70:71], v[66:67] op_sel:[1,0]
	v_mov_b32_e32 v71, v67
	v_pk_add_f32 v[60:61], v[60:61], v[70:71]
	s_waitcnt vmcnt(0)
	v_lshlrev_b32_e32 v76, 16, v54
	v_and_b32_e32 v77, 0xffff0000, v54
	v_lshlrev_b32_e32 v54, 16, v55
	v_and_b32_e32 v55, 0xffff0000, v55
	v_mul_f32_e32 v72, v58, v58
	v_pk_add_f32 v[60:61], v[60:61], v[60:61] op_sel_hi:[0,1]
	v_lshlrev_b32_e32 v68, 16, v52
	v_and_b32_e32 v69, 0xffff0000, v52
	v_lshlrev_b32_e32 v52, 16, v53
	v_and_b32_e32 v53, 0xffff0000, v53
	v_pk_fma_f32 v[66:67], v[58:59], v[58:59], v[72:73] op_sel_hi:[1,1,0]
	v_pk_add_f32 v[64:65], v[74:75], v[64:65]
	v_mul_f32_e32 v60, v50, v50
	v_pk_mul_f32 v[54:55], v[42:43], v[54:55] op_sel_hi:[0,1]
	v_pk_mul_f32 v[72:73], v[42:43], v[76:77] op_sel_hi:[0,1]
	v_pk_add_f32 v[64:65], v[64:65], v[64:65] op_sel_hi:[0,1]
	v_pk_fma_f32 v[70:71], v[50:51], v[50:51], v[60:61] op_sel_hi:[1,1,0]
	v_pk_fma_f32 v[68:69], v[24:25], v[72:73], v[68:69]
	v_pk_fma_f32 v[52:53], v[26:27], v[54:55], v[52:53]
	v_mul_f32_e32 v66, v68, v68
	v_mul_f32_e32 v70, v69, v69
	v_mul_f32_e32 v64, v52, v52
	v_mul_f32_e32 v60, v53, v53
	v_pk_add_f32 v[54:55], v[66:67], v[70:71]
	v_pk_add_f32 v[60:61], v[64:65], v[60:61]
	v_cvt_pk_bf16_f32 v66, v56, v57
	v_lshl_add_u64 v[64:65], v[44:45], 0, s[54:55]
	v_pk_add_f32 v[54:55], v[54:55], v[60:61]
	s_nop 0
	v_add_f32_e32 v42, v54, v55
	s_nop 1
	v_mov_b32_dpp v54, v42 quad_perm:[1,0,3,2] row_mask:0xf bank_mask:0xf
	s_waitcnt lgkmcnt(0)
	v_add_f32_e32 v42, v42, v54
	s_nop 1
	v_mov_b32_dpp v54, v42 quad_perm:[2,3,0,1] row_mask:0xf bank_mask:0xf
	s_waitcnt lgkmcnt(0)
	v_add_f32_e32 v42, v42, v54
	s_nop 1
	v_mov_b32_dpp v60, v42 row_half_mirror row_mask:0xf bank_mask:0xf
	v_lshl_add_u64 v[54:55], v[44:45], 0, s[40:41]
	s_waitcnt lgkmcnt(0)
	v_add_f32_e32 v42, v42, v60
	s_nop 1
	v_mov_b32_dpp v67, v42 row_mirror row_mask:0xf bank_mask:0xf
	v_lshl_add_u64 v[60:61], v[44:45], 0, s[52:53]
	v_lshl_add_u64 v[44:45], v[44:45], 0, s[56:57]
	s_waitcnt lgkmcnt(0)
	v_add_f32_e32 v42, v42, v67
	v_mov_b32_e32 v70, v42
	s_nop 1
	v_permlane16_swap_b32 v42, v70
	v_cvt_pk_bf16_f32 v67, v46, v47
	s_waitcnt lgkmcnt(0)
	v_add_f32_e32 v42, v42, v70
	global_store_dwordx2 v[54:55], v[66:67], off sc0 sc1
	s_nop 1
	v_mov_b32_e32 v66, v42
	s_nop 1
	v_permlane32_swap_b32 v42, v66
	v_cvt_pk_bf16_f32 v54, v62, v63
	v_cvt_pk_bf16_f32 v55, v48, v49
	s_waitcnt lgkmcnt(0)
	v_add_f32_e32 v42, v42, v66
	global_store_dwordx2 v[60:61], v[54:55], off sc0 sc1
	s_nop 1
	v_cvt_pk_bf16_f32 v54, v58, v59
	v_fmamk_f32 v42, v42, 0x3a800000, v90
	v_cvt_pk_bf16_f32 v55, v50, v51
	v_cmp_gt_f32_e32 vcc, s91, v42
	global_store_dwordx2 v[64:65], v[54:55], off sc0 sc1
	s_nop 1
	v_mul_f32_e32 v54, 0x4b800000, v42
	s_nop 0
	v_cndmask_b32_e32 v42, v42, v54, vcc
	v_rsq_f32_e32 v42, v42
	v_cvt_pk_bf16_f32 v54, v68, v69
	v_cvt_pk_bf16_f32 v55, v52, v53
	s_nop 0
	global_store_dwordx2 v[44:45], v[54:55], off sc0 sc1
	s_nop 1
	v_mul_f32_e32 v44, 0x45800000, v42
	v_cndmask_b32_e32 v42, v42, v44, vcc
	v_pk_mul_f32 v[54:55], v[56:57], v[42:43] op_sel_hi:[1,0]
	v_pk_mul_f32 v[46:47], v[46:47], v[42:43] op_sel_hi:[1,0]
	v_pk_mul_f32 v[54:55], v[4:5], v[54:55]
	v_pk_mul_f32 v[46:47], v[6:7], v[46:47]
	v_cvt_pk_bf16_f32 v54, v54, v55
	v_pk_mul_f32 v[48:49], v[48:49], v[42:43] op_sel_hi:[1,0]
	v_cvt_pk_bf16_f32 v55, v46, v47
	v_pk_mul_f32 v[46:47], v[62:63], v[42:43] op_sel_hi:[1,0]
	v_lshl_add_u64 v[44:45], v[36:37], 0, s[0:1]
	v_pk_mul_f32 v[46:47], v[16:17], v[46:47]
	global_store_dwordx2 v[44:45], v[54:55], off sc0 sc1
	s_nop 1
	v_pk_mul_f32 v[48:49], v[18:19], v[48:49]
	v_cvt_pk_bf16_f32 v46, v46, v47
	s_nop 0
	v_cvt_pk_bf16_f32 v47, v48, v49
	v_lshl_add_u64 v[48:49], v[44:45], 0, s[58:59]
	global_store_dwordx2 v[48:49], v[46:47], off sc0 sc1
	s_nop 1
	v_pk_mul_f32 v[46:47], v[58:59], v[42:43] op_sel_hi:[1,0]
	v_pk_mul_f32 v[48:49], v[50:51], v[42:43] op_sel_hi:[1,0]
	v_pk_mul_f32 v[46:47], v[20:21], v[46:47]
	v_pk_mul_f32 v[48:49], v[22:23], v[48:49]
	v_cvt_pk_bf16_f32 v46, v46, v47
	s_nop 0
	v_cvt_pk_bf16_f32 v47, v48, v49
	v_lshl_add_u64 v[48:49], v[44:45], 0, s[60:61]
	global_store_dwordx2 v[48:49], v[46:47], off sc0 sc1
	s_nop 1
	v_pk_mul_f32 v[46:47], v[68:69], v[42:43] op_sel_hi:[1,0]
	v_pk_mul_f32 v[48:49], v[52:53], v[42:43] op_sel_hi:[1,0]
	v_pk_mul_f32 v[46:47], v[28:29], v[46:47]
	v_pk_mul_f32 v[48:49], v[30:31], v[48:49]
	v_cvt_pk_bf16_f32 v46, v46, v47
	v_lshl_add_u64 v[44:45], v[44:45], 0, s[62:63]
	v_cvt_pk_bf16_f32 v47, v48, v49
	s_nop 0
	global_store_dwordx2 v[44:45], v[46:47], off sc0 sc1
	s_nop 1

.LBB0_2008:
	global_load_dwordx2 v[68:69], v[50:51], off offset:2048
	global_load_dwordx2 v[78:79], v[52:53], off offset:2048
	global_load_dwordx2 v[80:81], v[54:55], off offset:2048
	global_load_dwordx2 v[82:83], v[56:57], off offset:2048
	global_load_dwordx2 v[84:85], v[50:51], off offset:2560
	global_load_dwordx2 v[86:87], v[52:53], off offset:2560
	global_load_dwordx2 v[88:89], v[54:55], off offset:2560
	global_load_dwordx2 v[92:93], v[56:57], off offset:2560
	global_load_dwordx2 v[76:77], v[50:51], off offset:3072
	global_load_dwordx2 v[72:73], v[52:53], off offset:3072
	global_load_dwordx2 v[70:71], v[54:55], off offset:3072
	global_load_dwordx2 v[74:75], v[56:57], off offset:3072
	global_load_dwordx2 v[64:65], v[50:51], off offset:3584
	global_load_dwordx2 v[62:63], v[52:53], off offset:3584
	global_load_dwordx2 v[60:61], v[54:55], off offset:3584
	global_load_dwordx2 v[66:67], v[56:57], off offset:3584
	s_lshl_b64 s[6:7], s[6:7], 12
	s_add_u32 s6, s10, s6
	s_addc_u32 s7, s11, s7
	v_lshl_add_u64 v[50:51], v[32:33], 3, s[6:7]
	global_load_dwordx2 v[58:59], v[50:51], off offset:2048
	global_load_dwordx2 v[56:57], v[50:51], off offset:2560
	global_load_dwordx2 v[54:55], v[50:51], off offset:3072
	global_load_dwordx2 v[52:53], v[50:51], off offset:3584
	s_mov_b64 s[6:7], 0x3800800
	s_add_u32 s66, s66, 0x1000
	s_addc_u32 s67, s67, 0
	s_add_i32 s12, s12, 2
	s_add_u32 s0, s0, 2
	s_addc_u32 s1, s1, 0
	s_add_i32 s3, s3, 2
	s_cmpk_lg_i32 s66, 0x2000
	s_waitcnt vmcnt(19)
	v_lshlrev_b32_e32 v94, 16, v68
	v_and_b32_e32 v95, 0xffff0000, v68
	v_lshlrev_b32_e32 v68, 16, v69
	v_and_b32_e32 v69, 0xffff0000, v69
	s_waitcnt vmcnt(18)
	v_lshlrev_b32_e32 v96, 16, v78
	v_and_b32_e32 v97, 0xffff0000, v78
	v_lshlrev_b32_e32 v78, 16, v79
	v_and_b32_e32 v79, 0xffff0000, v79
	s_waitcnt vmcnt(11)
	v_lshlrev_b32_e32 v110, 16, v76
	v_and_b32_e32 v111, 0xffff0000, v76
	v_lshlrev_b32_e32 v76, 16, v77
	v_and_b32_e32 v77, 0xffff0000, v77
	s_waitcnt vmcnt(10)
	v_lshlrev_b32_e32 v112, 16, v72
	v_and_b32_e32 v113, 0xffff0000, v72
	v_pk_add_f32 v[76:77], v[76:77], 0 op_sel_hi:[1,0]
	v_lshlrev_b32_e32 v72, 16, v73
	v_and_b32_e32 v73, 0xffff0000, v73
	s_waitcnt vmcnt(9)
	v_lshlrev_b32_e32 v114, 16, v70
	v_and_b32_e32 v115, 0xffff0000, v70
	v_pk_add_f32 v[72:73], v[76:77], v[72:73]
	v_lshlrev_b32_e32 v70, 16, v71
	v_and_b32_e32 v71, 0xffff0000, v71
	v_lshlrev_b32_e32 v102, 16, v84
	v_and_b32_e32 v103, 0xffff0000, v84
	v_lshlrev_b32_e32 v84, 16, v85
	v_and_b32_e32 v85, 0xffff0000, v85
	v_pk_add_f32 v[94:95], v[94:95], 0 op_sel_hi:[1,0]
	v_pk_add_f32 v[68:69], v[68:69], 0 op_sel_hi:[1,0]
	v_pk_add_f32 v[70:71], v[72:73], v[70:71]
	s_waitcnt vmcnt(8)
	v_lshlrev_b32_e32 v72, 16, v75
	v_and_b32_e32 v73, 0xffff0000, v75
	v_lshlrev_b32_e32 v98, 16, v80
	v_and_b32_e32 v99, 0xffff0000, v80
	v_lshlrev_b32_e32 v80, 16, v81
	v_and_b32_e32 v81, 0xffff0000, v81
	v_lshlrev_b32_e32 v104, 16, v86
	v_and_b32_e32 v105, 0xffff0000, v86
	v_lshlrev_b32_e32 v86, 16, v87
	v_and_b32_e32 v87, 0xffff0000, v87
	v_pk_add_f32 v[102:103], v[102:103], 0 op_sel_hi:[1,0]
	v_pk_add_f32 v[84:85], v[84:85], 0 op_sel_hi:[1,0]
	v_pk_add_f32 v[110:111], v[110:111], 0 op_sel_hi:[1,0]
	v_pk_add_f32 v[94:95], v[94:95], v[96:97]
	v_pk_add_f32 v[68:69], v[68:69], v[78:79]
	v_pk_add_f32 v[72:73], v[70:71], v[72:73]
	s_waitcnt vmcnt(7)
	v_lshlrev_b32_e32 v70, 16, v64
	v_and_b32_e32 v71, 0xffff0000, v64
	v_lshlrev_b32_e32 v64, 16, v65
	v_and_b32_e32 v65, 0xffff0000, v65
	v_lshlrev_b32_e32 v100, 16, v82
	v_and_b32_e32 v101, 0xffff0000, v82
	v_lshlrev_b32_e32 v82, 16, v83
	v_and_b32_e32 v83, 0xffff0000, v83
	v_lshlrev_b32_e32 v106, 16, v88
	v_and_b32_e32 v107, 0xffff0000, v88
	v_lshlrev_b32_e32 v88, 16, v89
	v_and_b32_e32 v89, 0xffff0000, v89
	v_lshlrev_b32_e32 v116, 16, v74
	v_and_b32_e32 v117, 0xffff0000, v74
	v_pk_add_f32 v[78:79], v[102:103], v[104:105]
	v_pk_add_f32 v[84:85], v[84:85], v[86:87]
	v_pk_add_f32 v[86:87], v[110:111], v[112:113]
	v_pk_add_f32 v[94:95], v[94:95], v[98:99]
	v_pk_add_f32 v[68:69], v[68:69], v[80:81]
	v_pk_add_f32 v[70:71], v[70:71], 0 op_sel_hi:[1,0]
	s_waitcnt vmcnt(6)
	v_lshlrev_b32_e32 v74, 16, v62
	v_and_b32_e32 v75, 0xffff0000, v62
	v_pk_add_f32 v[64:65], v[64:65], 0 op_sel_hi:[1,0]
	v_lshlrev_b32_e32 v62, 16, v63
	v_and_b32_e32 v63, 0xffff0000, v63
	v_lshlrev_b32_e32 v108, 16, v92
	v_and_b32_e32 v109, 0xffff0000, v92
	v_lshlrev_b32_e32 v92, 16, v93
	v_and_b32_e32 v93, 0xffff0000, v93
	v_pk_add_f32 v[78:79], v[78:79], v[106:107]
	v_pk_add_f32 v[80:81], v[84:85], v[88:89]
	v_pk_add_f32 v[84:85], v[86:87], v[114:115]
	v_pk_add_f32 v[86:87], v[94:95], v[100:101]
	v_pk_add_f32 v[82:83], v[68:69], v[82:83]
	v_pk_add_f32 v[70:71], v[70:71], v[74:75]
	s_waitcnt vmcnt(5)
	v_lshlrev_b32_e32 v74, 16, v60
	v_and_b32_e32 v75, 0xffff0000, v60
	v_pk_add_f32 v[62:63], v[64:65], v[62:63]
	v_lshlrev_b32_e32 v60, 16, v61
	v_and_b32_e32 v61, 0xffff0000, v61
	v_pk_add_f32 v[78:79], v[78:79], v[108:109]
	v_pk_add_f32 v[80:81], v[80:81], v[92:93]
	v_pk_add_f32 v[60:61], v[62:63], v[60:61]
	s_waitcnt vmcnt(4)
	v_lshlrev_b32_e32 v62, 16, v67
	v_and_b32_e32 v63, 0xffff0000, v67
	v_mov_b32_e32 v64, v87
	v_mov_b32_e32 v65, v83
	v_pk_add_f32 v[68:69], v[84:85], v[116:117]
	v_pk_add_f32 v[70:71], v[70:71], v[74:75]
	v_lshlrev_b32_e32 v74, 16, v66
	v_and_b32_e32 v75, 0xffff0000, v66
	v_pk_add_f32 v[60:61], v[60:61], v[62:63]
	v_mov_b32_e32 v62, v86
	v_mov_b32_e32 v63, v82
	v_pk_mul_f32 v[64:65], v[64:65], v[64:65]
	v_mov_b32_e32 v66, v79
	v_mov_b32_e32 v67, v81
	v_pk_fma_f32 v[62:63], v[62:63], v[62:63], v[64:65]
	v_mov_b32_e32 v64, v78
	v_mov_b32_e32 v65, v80
	v_pk_mul_f32 v[66:67], v[66:67], v[66:67]
	v_mul_f32_e32 v42, v69, v69
	v_pk_add_f32 v[70:71], v[70:71], v[74:75]
	v_pk_fma_f32 v[64:65], v[64:65], v[64:65], v[66:67]
	v_pk_fma_f32 v[66:67], v[68:69], v[68:69], v[42:43] op_sel_hi:[1,1,0]
	v_mul_f32_e32 v42, v73, v73
	v_pk_add_f32 v[62:63], v[62:63], v[62:63] op_sel:[0,1] op_sel_hi:[1,0]
	v_pk_add_f32 v[64:65], v[64:65], v[64:65] op_sel:[0,1] op_sel_hi:[1,0]
	v_pk_fma_f32 v[74:75], v[72:73], v[72:73], v[42:43] op_sel_hi:[1,1,0]
	v_pk_mul_f32 v[76:77], v[70:71], v[70:71]
	v_pk_mul_f32 v[84:85], v[60:61], v[60:61]
	v_mov_b32_e32 v63, v76
	v_mov_b32_e32 v65, v77
	v_mov_b32_e32 v67, v84
	v_mov_b32_e32 v75, v85
	v_pk_add_f32 v[62:63], v[62:63], v[64:65]
	v_pk_add_f32 v[64:65], v[66:67], v[74:75]
	s_waitcnt vmcnt(1)
	v_lshlrev_b32_e32 v66, 16, v54
	v_pk_add_f32 v[62:63], v[62:63], v[64:65]
	v_lshlrev_b32_e32 v64, 16, v56
	v_add_f32_e32 v42, v62, v63
	s_nop 1
	v_mov_b32_dpp v62, v42 quad_perm:[1,0,3,2] row_mask:0xf bank_mask:0xf
	s_waitcnt vmcnt(0)
	v_lshlrev_b32_e32 v74, 16, v52
	s_waitcnt lgkmcnt(0)
	v_add_f32_e32 v42, v42, v62
	s_nop 1
	v_mov_b32_dpp v62, v42 quad_perm:[2,3,0,1] row_mask:0xf bank_mask:0xf
	s_waitcnt lgkmcnt(0)
	v_add_f32_e32 v42, v42, v62
	s_nop 1
	v_mov_b32_dpp v63, v42 row_half_mirror row_mask:0xf bank_mask:0xf
	v_lshlrev_b32_e32 v62, 16, v58
	s_waitcnt lgkmcnt(0)
	v_add_f32_e32 v42, v42, v63
	s_nop 1
	v_mov_b32_dpp v65, v42 row_mirror row_mask:0xf bank_mask:0xf
	v_and_b32_e32 v63, 0xffff0000, v58
	v_lshlrev_b32_e32 v58, 16, v59
	v_and_b32_e32 v59, 0xffff0000, v59
	s_waitcnt lgkmcnt(0)
	v_add_f32_e32 v42, v42, v65
	v_mov_b32_e32 v67, v42
	s_nop 1
	v_permlane16_swap_b32 v42, v67
	v_and_b32_e32 v65, 0xffff0000, v56
	v_lshlrev_b32_e32 v56, 16, v57
	v_and_b32_e32 v57, 0xffff0000, v57
	s_waitcnt lgkmcnt(0)
	v_add_f32_e32 v42, v42, v67
	v_mov_b32_e32 v75, v42
	s_nop 1
	v_permlane32_swap_b32 v42, v75
	v_and_b32_e32 v67, 0xffff0000, v54
	v_lshlrev_b32_e32 v54, 16, v55
	v_and_b32_e32 v55, 0xffff0000, v55
	s_waitcnt lgkmcnt(0)
	v_add_f32_e32 v42, v42, v75
	v_fmamk_f32 v42, v42, 0x3a800000, v90
	v_mul_f32_e32 v75, 0x4b800000, v42
	v_cmp_gt_f32_e32 vcc, s91, v42
	s_nop 1
	v_cndmask_b32_e32 v42, v42, v75, vcc
	v_rsq_f32_e32 v42, v42
	v_and_b32_e32 v75, 0xffff0000, v52
	v_lshlrev_b32_e32 v52, 16, v53
	v_and_b32_e32 v53, 0xffff0000, v53
	v_mul_f32_e32 v76, 0x45800000, v42
	v_cndmask_b32_e32 v42, v42, v76, vcc
	v_pk_mul_f32 v[76:77], v[86:87], v[42:43] op_sel_hi:[1,0]
	v_pk_mul_f32 v[82:83], v[82:83], v[42:43] op_sel_hi:[1,0]
	v_pk_fma_f32 v[62:63], v[0:1], v[76:77], v[62:63]
	v_pk_fma_f32 v[58:59], v[2:3], v[82:83], v[58:59]
	v_pk_mul_f32 v[80:81], v[80:81], v[42:43] op_sel_hi:[1,0]
	v_pk_mul_f32 v[78:79], v[78:79], v[42:43] op_sel_hi:[1,0]
	v_pk_mul_f32 v[68:69], v[68:69], v[42:43] op_sel_hi:[1,0]
	v_pk_mul_f32 v[76:77], v[58:59], v[58:59]
	v_pk_mul_f32 v[82:83], v[62:63], v[62:63]
	v_pk_fma_f32 v[64:65], v[8:9], v[78:79], v[64:65]
	v_pk_fma_f32 v[56:57], v[10:11], v[80:81], v[56:57]
	v_pk_fma_f32 v[66:67], v[12:13], v[68:69], v[66:67]
	v_pk_mov_b32 v[84:85], v[82:83], v[76:77] op_sel:[1,0]
	v_mov_b32_e32 v83, v77
	v_pk_mul_f32 v[78:79], v[56:57], v[56:57]
	v_pk_mul_f32 v[80:81], v[64:65], v[64:65]
	v_pk_mul_f32 v[72:73], v[72:73], v[42:43] op_sel_hi:[1,0]
	v_mul_f32_e32 v68, v66, v66
	v_pk_add_f32 v[76:77], v[84:85], v[82:83]
	v_pk_mov_b32 v[82:83], v[80:81], v[78:79] op_sel:[1,0]
	v_mov_b32_e32 v81, v79
	v_pk_fma_f32 v[54:55], v[14:15], v[72:73], v[54:55]
	v_pk_fma_f32 v[68:69], v[66:67], v[66:67], v[68:69] op_sel_hi:[1,1,0]
	v_pk_add_f32 v[78:79], v[82:83], v[80:81]
	v_mul_f32_e32 v68, v54, v54
	v_pk_mul_f32 v[60:61], v[60:61], v[42:43] op_sel_hi:[1,0]
	v_pk_mul_f32 v[70:71], v[70:71], v[42:43] op_sel_hi:[1,0]
	v_pk_add_f32 v[76:77], v[76:77], v[76:77] op_sel_hi:[0,1]
	v_pk_add_f32 v[78:79], v[78:79], v[78:79] op_sel_hi:[0,1]
	v_pk_fma_f32 v[72:73], v[54:55], v[54:55], v[68:69] op_sel_hi:[1,1,0]
	v_pk_fma_f32 v[70:71], v[24:25], v[70:71], v[74:75]
	v_pk_fma_f32 v[52:53], v[26:27], v[60:61], v[52:53]
	v_mul_f32_e32 v68, v70, v70
	v_mul_f32_e32 v72, v71, v71
	v_mul_f32_e32 v76, v52, v52
	v_mul_f32_e32 v78, v53, v53
	v_pk_add_f32 v[60:61], v[68:69], v[72:73]
	v_pk_add_f32 v[68:69], v[76:77], v[78:79]
	v_cvt_pk_bf16_f32 v74, v62, v63
	v_lshl_add_u64 v[72:73], v[50:51], 0, s[54:55]
	v_pk_add_f32 v[60:61], v[60:61], v[68:69]
	s_nop 0
	v_add_f32_e32 v42, v60, v61
	s_nop 1
	v_mov_b32_dpp v60, v42 quad_perm:[1,0,3,2] row_mask:0xf bank_mask:0xf
	s_waitcnt lgkmcnt(0)
	v_add_f32_e32 v42, v42, v60
	s_nop 1
	v_mov_b32_dpp v60, v42 quad_perm:[2,3,0,1] row_mask:0xf bank_mask:0xf
	s_waitcnt lgkmcnt(0)
	v_add_f32_e32 v42, v42, v60
	s_nop 1
	v_mov_b32_dpp v68, v42 row_half_mirror row_mask:0xf bank_mask:0xf
	v_lshl_add_u64 v[60:61], v[50:51], 0, s[40:41]
	s_waitcnt lgkmcnt(0)
	v_add_f32_e32 v42, v42, v68
	s_nop 1
	v_mov_b32_dpp v75, v42 row_mirror row_mask:0xf bank_mask:0xf
	v_lshl_add_u64 v[68:69], v[50:51], 0, s[52:53]
	v_lshl_add_u64 v[50:51], v[50:51], 0, s[56:57]
	s_waitcnt lgkmcnt(0)
	v_add_f32_e32 v42, v42, v75
	v_mov_b32_e32 v76, v42
	s_nop 1
	v_permlane16_swap_b32 v42, v76
	v_cvt_pk_bf16_f32 v75, v58, v59
	s_waitcnt lgkmcnt(0)
	v_add_f32_e32 v42, v42, v76
	global_store_dwordx2 v[60:61], v[74:75], off sc0 sc1
	s_nop 1
	v_mov_b32_e32 v74, v42
	s_nop 1
	v_permlane32_swap_b32 v42, v74
	v_cvt_pk_bf16_f32 v60, v64, v65
	v_cvt_pk_bf16_f32 v61, v56, v57
	s_waitcnt lgkmcnt(0)
	v_add_f32_e32 v42, v42, v74
	global_store_dwordx2 v[68:69], v[60:61], off sc0 sc1
	s_nop 1
	v_cvt_pk_bf16_f32 v60, v66, v67
	v_fmamk_f32 v42, v42, 0x3a800000, v90
	v_cvt_pk_bf16_f32 v61, v54, v55
	v_cmp_gt_f32_e32 vcc, s91, v42
	global_store_dwordx2 v[72:73], v[60:61], off sc0 sc1
	s_nop 1
	v_mul_f32_e32 v60, 0x4b800000, v42
	s_nop 0
	v_cndmask_b32_e32 v42, v42, v60, vcc
	v_rsq_f32_e32 v42, v42
	v_cvt_pk_bf16_f32 v60, v70, v71
	v_cvt_pk_bf16_f32 v61, v52, v53
	s_nop 0
	global_store_dwordx2 v[50:51], v[60:61], off sc0 sc1
	s_nop 1
	v_mul_f32_e32 v50, 0x45800000, v42
	v_cndmask_b32_e32 v42, v42, v50, vcc
	v_pk_mul_f32 v[60:61], v[62:63], v[42:43] op_sel_hi:[1,0]
	v_lshl_add_u64 v[50:51], v[48:49], 0, s[6:7]
	v_pk_mul_f32 v[58:59], v[58:59], v[42:43] op_sel_hi:[1,0]
	v_pk_mul_f32 v[60:61], v[4:5], v[60:61]
	v_pk_mul_f32 v[58:59], v[6:7], v[58:59]
	v_cvt_pk_bf16_f32 v60, v60, v61
	v_pk_mul_f32 v[56:57], v[56:57], v[42:43] op_sel_hi:[1,0]
	v_cvt_pk_bf16_f32 v61, v58, v59
	s_mov_b64 s[6:7], 0x3800a00
	global_store_dwordx2 v[50:51], v[60:61], off sc0 sc1
	s_nop 1
	v_pk_mul_f32 v[50:51], v[64:65], v[42:43] op_sel_hi:[1,0]
	v_pk_mul_f32 v[56:57], v[18:19], v[56:57]
	v_pk_mul_f32 v[50:51], v[16:17], v[50:51]
	v_pk_mul_f32 v[54:55], v[54:55], v[42:43] op_sel_hi:[1,0]
	v_cvt_pk_bf16_f32 v50, v50, v51
	v_cvt_pk_bf16_f32 v51, v56, v57
	v_lshl_add_u64 v[56:57], v[48:49], 0, s[6:7]
	global_store_dwordx2 v[56:57], v[50:51], off sc0 sc1
	s_nop 1
	v_pk_mul_f32 v[50:51], v[66:67], v[42:43] op_sel_hi:[1,0]
	v_pk_mul_f32 v[54:55], v[22:23], v[54:55]
	v_pk_mul_f32 v[50:51], v[20:21], v[50:51]
	s_mov_b64 s[6:7], 0x3800c00
	v_cvt_pk_bf16_f32 v50, v50, v51
	v_cvt_pk_bf16_f32 v51, v54, v55
	v_lshl_add_u64 v[54:55], v[48:49], 0, s[6:7]
	global_store_dwordx2 v[54:55], v[50:51], off sc0 sc1
	s_nop 1
	v_pk_mul_f32 v[50:51], v[70:71], v[42:43] op_sel_hi:[1,0]
	v_pk_mul_f32 v[52:53], v[52:53], v[42:43] op_sel_hi:[1,0]
	v_pk_mul_f32 v[50:51], v[28:29], v[50:51]
	s_mov_b64 s[6:7], 0x3800e00
	v_pk_mul_f32 v[52:53], v[30:31], v[52:53]
	v_cvt_pk_bf16_f32 v50, v50, v51
	v_lshl_add_u64 v[48:49], v[48:49], 0, s[6:7]
	v_cvt_pk_bf16_f32 v51, v52, v53
	s_nop 0
	global_store_dwordx2 v[48:49], v[50:51], off sc0 sc1
	s_nop 1
	s_cbranch_scc0 .LBB0_2023

.LBB0_2016:
	v_lshl_add_u64 v[48:49], v[46:47], 0, s[66:67]
	s_mov_b32 s14, 0xda00000
	v_add_co_u32_e32 v50, vcc, s14, v48
	s_mov_b32 s14, 0xdb80000
	s_nop 0
	v_addc_co_u32_e32 v51, vcc, 0, v49, vcc
	v_add_co_u32_e32 v52, vcc, s14, v48
	s_mov_b32 s14, 0xdd00000
	s_nop 0
	v_addc_co_u32_e32 v53, vcc, 0, v49, vcc
	global_load_dwordx2 v[66:67], v[50:51], off
	global_load_dwordx2 v[76:77], v[52:53], off
	v_add_co_u32_e32 v54, vcc, s14, v48
	s_mov_b32 s14, 0xde80000
	s_nop 0
	v_addc_co_u32_e32 v55, vcc, 0, v49, vcc
	global_load_dwordx2 v[78:79], v[54:55], off
	v_add_co_u32_e32 v56, vcc, s14, v48
	s_lshl_b64 s[6:7], s[6:7], 12
	s_nop 0
	v_addc_co_u32_e32 v57, vcc, 0, v49, vcc
	global_load_dwordx2 v[88:89], v[56:57], off
	global_load_dwordx2 v[92:93], v[50:51], off offset:512
	global_load_dwordx2 v[94:95], v[52:53], off offset:512
	global_load_dwordx2 v[96:97], v[54:55], off offset:512
	global_load_dwordx2 v[98:99], v[56:57], off offset:512
	global_load_dwordx2 v[86:87], v[50:51], off offset:1024
	global_load_dwordx2 v[82:83], v[52:53], off offset:1024
	global_load_dwordx2 v[80:81], v[54:55], off offset:1024
	global_load_dwordx2 v[84:85], v[56:57], off offset:1024
	global_load_dwordx2 v[72:73], v[50:51], off offset:1536
	global_load_dwordx2 v[70:71], v[52:53], off offset:1536
	global_load_dwordx2 v[68:69], v[54:55], off offset:1536
	global_load_dwordx2 v[74:75], v[56:57], off offset:1536
	s_add_u32 s6, s10, s6
	s_addc_u32 s7, s11, s7
	v_lshl_add_u64 v[48:49], v[32:33], 3, s[6:7]
	global_load_dwordx2 v[64:65], v[48:49], off offset:2048
	global_load_dwordx2 v[62:63], v[48:49], off offset:2560
	global_load_dwordx2 v[60:61], v[48:49], off offset:3072
	global_load_dwordx2 v[58:59], v[48:49], off offset:3584
	s_mov_b64 s[6:7], 0x3800000
	s_add_i32 s17, s17, 1
	s_cmpk_lt_u32 s17, 0x4080
	s_mov_b64 s[10:11], -1
	s_waitcnt vmcnt(19)
	v_lshlrev_b32_e32 v100, 16, v66
	v_and_b32_e32 v101, 0xffff0000, v66
	v_lshlrev_b32_e32 v66, 16, v67
	v_and_b32_e32 v67, 0xffff0000, v67
	s_waitcnt vmcnt(18)
	v_lshlrev_b32_e32 v102, 16, v76
	v_and_b32_e32 v103, 0xffff0000, v76
	v_lshlrev_b32_e32 v76, 16, v77
	v_and_b32_e32 v77, 0xffff0000, v77
	v_pk_add_f32 v[66:67], v[66:67], 0 op_sel_hi:[1,0]
	s_waitcnt vmcnt(17)
	v_lshlrev_b32_e32 v104, 16, v78
	v_and_b32_e32 v105, 0xffff0000, v78
	v_lshlrev_b32_e32 v78, 16, v79
	v_and_b32_e32 v79, 0xffff0000, v79
	s_waitcnt vmcnt(15)
	v_lshlrev_b32_e32 v108, 16, v92
	v_and_b32_e32 v109, 0xffff0000, v92
	v_lshlrev_b32_e32 v92, 16, v93
	v_and_b32_e32 v93, 0xffff0000, v93
	v_pk_add_f32 v[66:67], v[66:67], v[76:77]
	v_lshlrev_b32_e32 v106, 16, v88
	v_and_b32_e32 v107, 0xffff0000, v88
	v_lshlrev_b32_e32 v88, 16, v89
	v_and_b32_e32 v89, 0xffff0000, v89
	s_waitcnt vmcnt(14)
	v_lshlrev_b32_e32 v110, 16, v94
	v_and_b32_e32 v111, 0xffff0000, v94
	v_lshlrev_b32_e32 v94, 16, v95
	v_and_b32_e32 v95, 0xffff0000, v95
	v_pk_add_f32 v[92:93], v[92:93], 0 op_sel_hi:[1,0]
	v_pk_add_f32 v[66:67], v[66:67], v[78:79]
	v_pk_add_f32 v[100:101], v[100:101], 0 op_sel_hi:[1,0]
	v_pk_add_f32 v[92:93], v[92:93], v[94:95]
	v_pk_add_f32 v[78:79], v[66:67], v[88:89]
	s_waitcnt vmcnt(13)
	v_lshlrev_b32_e32 v88, 16, v97
	v_and_b32_e32 v89, 0xffff0000, v97
	v_pk_add_f32 v[108:109], v[108:109], 0 op_sel_hi:[1,0]
	v_pk_add_f32 v[100:101], v[100:101], v[102:103]
	v_pk_add_f32 v[88:89], v[92:93], v[88:89]
	s_waitcnt vmcnt(12)
	v_lshlrev_b32_e32 v92, 16, v99
	v_and_b32_e32 v93, 0xffff0000, v99
	v_lshlrev_b32_e32 v112, 16, v96
	v_and_b32_e32 v113, 0xffff0000, v96
	v_pk_add_f32 v[76:77], v[108:109], v[110:111]
	v_pk_add_f32 v[94:95], v[100:101], v[104:105]
	v_pk_add_f32 v[92:93], v[88:89], v[92:93]
	s_waitcnt vmcnt(11)
	v_lshlrev_b32_e32 v88, 16, v86
	v_and_b32_e32 v89, 0xffff0000, v86
	v_lshlrev_b32_e32 v86, 16, v87
	v_and_b32_e32 v87, 0xffff0000, v87
	v_pk_add_f32 v[100:101], v[76:77], v[112:113]
	v_pk_add_f32 v[76:77], v[94:95], v[106:107]
	v_pk_add_f32 v[88:89], v[88:89], 0 op_sel_hi:[1,0]
	s_waitcnt vmcnt(10)
	v_lshlrev_b32_e32 v94, 16, v82
	v_and_b32_e32 v95, 0xffff0000, v82
	v_pk_add_f32 v[86:87], v[86:87], 0 op_sel_hi:[1,0]
	v_lshlrev_b32_e32 v82, 16, v83
	v_and_b32_e32 v83, 0xffff0000, v83
	v_pk_add_f32 v[88:89], v[88:89], v[94:95]
	s_waitcnt vmcnt(9)
	v_lshlrev_b32_e32 v94, 16, v80
	v_and_b32_e32 v95, 0xffff0000, v80
	v_pk_add_f32 v[82:83], v[86:87], v[82:83]
	v_lshlrev_b32_e32 v80, 16, v81
	v_and_b32_e32 v81, 0xffff0000, v81
	v_pk_add_f32 v[80:81], v[82:83], v[80:81]
	s_waitcnt vmcnt(8)
	v_lshlrev_b32_e32 v82, 16, v85
	v_and_b32_e32 v83, 0xffff0000, v85
	v_pk_add_f32 v[82:83], v[80:81], v[82:83]
	s_waitcnt vmcnt(7)
	v_lshlrev_b32_e32 v80, 16, v72
	v_and_b32_e32 v81, 0xffff0000, v72
	v_lshlrev_b32_e32 v72, 16, v73
	v_and_b32_e32 v73, 0xffff0000, v73
	v_pk_add_f32 v[88:89], v[88:89], v[94:95]
	v_lshlrev_b32_e32 v94, 16, v84
	v_and_b32_e32 v95, 0xffff0000, v84
	v_pk_add_f32 v[80:81], v[80:81], 0 op_sel_hi:[1,0]
	s_waitcnt vmcnt(6)
	v_lshlrev_b32_e32 v84, 16, v70
	v_and_b32_e32 v85, 0xffff0000, v70
	v_pk_add_f32 v[72:73], v[72:73], 0 op_sel_hi:[1,0]
	v_lshlrev_b32_e32 v70, 16, v71
	v_and_b32_e32 v71, 0xffff0000, v71
	v_lshlrev_b32_e32 v114, 16, v98
	v_and_b32_e32 v115, 0xffff0000, v98
	v_pk_add_f32 v[80:81], v[80:81], v[84:85]
	s_waitcnt vmcnt(5)
	v_lshlrev_b32_e32 v84, 16, v68
	v_and_b32_e32 v85, 0xffff0000, v68
	v_pk_add_f32 v[70:71], v[72:73], v[70:71]
	v_lshlrev_b32_e32 v68, 16, v69
	v_and_b32_e32 v69, 0xffff0000, v69
	v_pk_add_f32 v[66:67], v[100:101], v[114:115]
	v_pk_add_f32 v[68:69], v[70:71], v[68:69]
	s_waitcnt vmcnt(4)
	v_lshlrev_b32_e32 v70, 16, v75
	v_and_b32_e32 v71, 0xffff0000, v75
	v_mov_b32_e32 v72, v77
	v_mov_b32_e32 v73, v79
	v_pk_add_f32 v[88:89], v[88:89], v[94:95]
	v_pk_add_f32 v[80:81], v[80:81], v[84:85]
	v_lshlrev_b32_e32 v84, 16, v74
	v_and_b32_e32 v85, 0xffff0000, v74
	v_pk_add_f32 v[68:69], v[68:69], v[70:71]
	v_mov_b32_e32 v70, v76
	v_mov_b32_e32 v71, v78
	v_pk_mul_f32 v[72:73], v[72:73], v[72:73]
	v_mov_b32_e32 v74, v67
	v_mov_b32_e32 v75, v93
	v_pk_fma_f32 v[70:71], v[70:71], v[70:71], v[72:73]
	v_mov_b32_e32 v72, v66
	v_mov_b32_e32 v73, v92
	v_pk_mul_f32 v[74:75], v[74:75], v[74:75]
	v_mul_f32_e32 v42, v89, v89
	v_pk_add_f32 v[80:81], v[80:81], v[84:85]
	v_pk_fma_f32 v[72:73], v[72:73], v[72:73], v[74:75]
	v_pk_fma_f32 v[74:75], v[88:89], v[88:89], v[42:43] op_sel_hi:[1,1,0]
	v_mul_f32_e32 v42, v83, v83
	v_pk_add_f32 v[70:71], v[70:71], v[70:71] op_sel:[0,1] op_sel_hi:[1,0]
	v_pk_add_f32 v[72:73], v[72:73], v[72:73] op_sel:[0,1] op_sel_hi:[1,0]
	v_pk_fma_f32 v[84:85], v[82:83], v[82:83], v[42:43] op_sel_hi:[1,1,0]
	v_pk_mul_f32 v[86:87], v[80:81], v[80:81]
	v_pk_mul_f32 v[94:95], v[68:69], v[68:69]
	v_mov_b32_e32 v71, v86
	v_mov_b32_e32 v73, v87
	v_mov_b32_e32 v75, v94
	v_mov_b32_e32 v85, v95
	v_pk_add_f32 v[70:71], v[70:71], v[72:73]
	v_pk_add_f32 v[72:73], v[74:75], v[84:85]
	s_waitcnt vmcnt(1)
	v_lshlrev_b32_e32 v74, 16, v60
	v_pk_add_f32 v[70:71], v[70:71], v[72:73]
	v_lshlrev_b32_e32 v72, 16, v62
	v_add_f32_e32 v42, v70, v71
	s_nop 1
	v_mov_b32_dpp v70, v42 quad_perm:[1,0,3,2] row_mask:0xf bank_mask:0xf
	s_waitcnt vmcnt(0)
	v_lshlrev_b32_e32 v84, 16, v58
	s_waitcnt lgkmcnt(0)
	v_add_f32_e32 v42, v42, v70
	s_nop 1
	v_mov_b32_dpp v70, v42 quad_perm:[2,3,0,1] row_mask:0xf bank_mask:0xf
	s_waitcnt lgkmcnt(0)
	v_add_f32_e32 v42, v42, v70
	s_nop 1
	v_mov_b32_dpp v71, v42 row_half_mirror row_mask:0xf bank_mask:0xf
	v_lshlrev_b32_e32 v70, 16, v64
	s_waitcnt lgkmcnt(0)
	v_add_f32_e32 v42, v42, v71
	s_nop 1
	v_mov_b32_dpp v73, v42 row_mirror row_mask:0xf bank_mask:0xf
	v_and_b32_e32 v71, 0xffff0000, v64
	v_lshlrev_b32_e32 v64, 16, v65
	v_and_b32_e32 v65, 0xffff0000, v65
	s_waitcnt lgkmcnt(0)
	v_add_f32_e32 v42, v42, v73
	v_mov_b32_e32 v75, v42
	s_nop 1
	v_permlane16_swap_b32 v42, v75
	v_and_b32_e32 v73, 0xffff0000, v62
	v_lshlrev_b32_e32 v62, 16, v63
	v_and_b32_e32 v63, 0xffff0000, v63
	s_waitcnt lgkmcnt(0)
	v_add_f32_e32 v42, v42, v75
	v_mov_b32_e32 v85, v42
	s_nop 1
	v_permlane32_swap_b32 v42, v85
	v_and_b32_e32 v75, 0xffff0000, v60
	v_lshlrev_b32_e32 v60, 16, v61
	v_and_b32_e32 v61, 0xffff0000, v61
	s_waitcnt lgkmcnt(0)
	v_add_f32_e32 v42, v42, v85
	v_fmamk_f32 v42, v42, 0x3a800000, v90
	v_mul_f32_e32 v85, 0x4b800000, v42
	v_cmp_gt_f32_e32 vcc, s91, v42
	s_nop 1
	v_cndmask_b32_e32 v42, v42, v85, vcc
	v_rsq_f32_e32 v42, v42
	v_and_b32_e32 v85, 0xffff0000, v58
	v_lshlrev_b32_e32 v58, 16, v59
	v_and_b32_e32 v59, 0xffff0000, v59
	v_mul_f32_e32 v86, 0x45800000, v42
	v_cndmask_b32_e32 v42, v42, v86, vcc
	v_pk_mul_f32 v[76:77], v[76:77], v[42:43] op_sel_hi:[1,0]
	v_pk_mul_f32 v[78:79], v[78:79], v[42:43] op_sel_hi:[1,0]
	v_pk_fma_f32 v[70:71], v[0:1], v[76:77], v[70:71]
	v_pk_fma_f32 v[64:65], v[2:3], v[78:79], v[64:65]
	v_pk_mul_f32 v[78:79], v[70:71], v[70:71]
	v_pk_mul_f32 v[76:77], v[64:65], v[64:65]
	v_pk_mul_f32 v[66:67], v[66:67], v[42:43] op_sel_hi:[1,0]
	v_pk_mov_b32 v[86:87], v[78:79], v[76:77] op_sel:[1,0]
	v_mov_b32_e32 v79, v77
	v_pk_add_f32 v[76:77], v[86:87], v[78:79]
	v_pk_mul_f32 v[78:79], v[92:93], v[42:43] op_sel_hi:[1,0]
	v_pk_fma_f32 v[66:67], v[8:9], v[66:67], v[72:73]
	v_pk_fma_f32 v[62:63], v[10:11], v[78:79], v[62:63]
	v_pk_mul_f32 v[78:79], v[66:67], v[66:67]
	v_pk_mul_f32 v[72:73], v[62:63], v[62:63]
	v_pk_mul_f32 v[68:69], v[68:69], v[42:43] op_sel_hi:[1,0]
	v_pk_mov_b32 v[86:87], v[78:79], v[72:73] op_sel:[1,0]
	v_mov_b32_e32 v79, v73
	v_pk_add_f32 v[72:73], v[86:87], v[78:79]
	v_pk_mul_f32 v[78:79], v[82:83], v[42:43] op_sel_hi:[1,0]
	v_pk_mul_f32 v[82:83], v[88:89], v[42:43] op_sel_hi:[1,0]
	v_pk_add_f32 v[72:73], v[72:73], v[72:73] op_sel_hi:[0,1]
	v_pk_fma_f32 v[74:75], v[12:13], v[82:83], v[74:75]
	v_pk_fma_f32 v[60:61], v[14:15], v[78:79], v[60:61]
	v_mul_f32_e32 v72, v74, v74
	v_pk_fma_f32 v[78:79], v[74:75], v[74:75], v[72:73] op_sel_hi:[1,1,0]
	v_mul_f32_e32 v72, v60, v60
	v_pk_mul_f32 v[80:81], v[80:81], v[42:43] op_sel_hi:[1,0]
	v_pk_add_f32 v[76:77], v[76:77], v[76:77] op_sel_hi:[0,1]
	v_pk_fma_f32 v[82:83], v[60:61], v[60:61], v[72:73] op_sel_hi:[1,1,0]
	v_pk_fma_f32 v[80:81], v[24:25], v[80:81], v[84:85]
	v_pk_fma_f32 v[58:59], v[26:27], v[68:69], v[58:59]
	v_mul_f32_e32 v78, v80, v80
	v_mul_f32_e32 v82, v81, v81
	v_mul_f32_e32 v76, v58, v58
	v_mul_f32_e32 v72, v59, v59
	v_pk_add_f32 v[68:69], v[78:79], v[82:83]
	v_pk_add_f32 v[72:73], v[76:77], v[72:73]
	v_cvt_pk_bf16_f32 v78, v70, v71
	v_lshl_add_u64 v[76:77], v[48:49], 0, s[54:55]
	v_pk_add_f32 v[68:69], v[68:69], v[72:73]
	s_nop 0
	v_add_f32_e32 v42, v68, v69
	s_nop 1
	v_mov_b32_dpp v68, v42 quad_perm:[1,0,3,2] row_mask:0xf bank_mask:0xf
	s_waitcnt lgkmcnt(0)
	v_add_f32_e32 v42, v42, v68
	s_nop 1
	v_mov_b32_dpp v68, v42 quad_perm:[2,3,0,1] row_mask:0xf bank_mask:0xf
	s_waitcnt lgkmcnt(0)
	v_add_f32_e32 v42, v42, v68
	s_nop 1
	v_mov_b32_dpp v72, v42 row_half_mirror row_mask:0xf bank_mask:0xf
	v_lshl_add_u64 v[68:69], v[48:49], 0, s[40:41]
	s_waitcnt lgkmcnt(0)
	v_add_f32_e32 v42, v42, v72
	s_nop 1
	v_mov_b32_dpp v79, v42 row_mirror row_mask:0xf bank_mask:0xf
	v_lshl_add_u64 v[72:73], v[48:49], 0, s[52:53]
	v_lshl_add_u64 v[48:49], v[48:49], 0, s[56:57]
	s_waitcnt lgkmcnt(0)
	v_add_f32_e32 v42, v42, v79
	v_mov_b32_e32 v82, v42
	s_nop 1
	v_permlane16_swap_b32 v42, v82
	v_cvt_pk_bf16_f32 v79, v64, v65
	s_waitcnt lgkmcnt(0)
	v_add_f32_e32 v42, v42, v82
	global_store_dwordx2 v[68:69], v[78:79], off sc0 sc1
	s_nop 1
	v_mov_b32_e32 v78, v42
	s_nop 1
	v_permlane32_swap_b32 v42, v78
	v_cvt_pk_bf16_f32 v68, v66, v67
	v_cvt_pk_bf16_f32 v69, v62, v63
	s_waitcnt lgkmcnt(0)
	v_add_f32_e32 v42, v42, v78
	global_store_dwordx2 v[72:73], v[68:69], off sc0 sc1
	s_nop 1
	v_cvt_pk_bf16_f32 v68, v74, v75
	v_fmamk_f32 v42, v42, 0x3a800000, v90
	v_cvt_pk_bf16_f32 v69, v60, v61
	v_cmp_gt_f32_e32 vcc, s91, v42
	global_store_dwordx2 v[76:77], v[68:69], off sc0 sc1
	s_nop 1
	v_mul_f32_e32 v68, 0x4b800000, v42
	s_nop 0
	v_cndmask_b32_e32 v42, v42, v68, vcc
	v_rsq_f32_e32 v42, v42
	v_cvt_pk_bf16_f32 v68, v80, v81
	v_cvt_pk_bf16_f32 v69, v58, v59
	s_nop 0
	global_store_dwordx2 v[48:49], v[68:69], off sc0 sc1
	s_nop 1
	v_mul_f32_e32 v48, 0x45800000, v42
	v_cndmask_b32_e32 v42, v42, v48, vcc
	v_pk_mul_f32 v[70:71], v[70:71], v[42:43] op_sel_hi:[1,0]
	v_pk_mul_f32 v[64:65], v[64:65], v[42:43] op_sel_hi:[1,0]
	v_pk_mul_f32 v[70:71], v[4:5], v[70:71]
	v_pk_mul_f32 v[64:65], v[6:7], v[64:65]
	v_lshl_add_u64 v[48:49], v[44:45], 0, s[66:67]
	v_cvt_pk_bf16_f32 v70, v70, v71
	v_cvt_pk_bf16_f32 v71, v64, v65
	v_pk_mul_f32 v[64:65], v[66:67], v[42:43] op_sel_hi:[1,0]
	v_pk_mul_f32 v[62:63], v[62:63], v[42:43] op_sel_hi:[1,0]
	v_lshl_add_u64 v[68:69], v[48:49], 0, s[6:7]
	v_pk_mul_f32 v[62:63], v[18:19], v[62:63]
	v_pk_mul_f32 v[64:65], v[16:17], v[64:65]
	s_mov_b64 s[6:7], 0x3800200
	global_store_dwordx2 v[68:69], v[70:71], off sc0 sc1
	s_nop 1
	v_cvt_pk_bf16_f32 v64, v64, v65
	v_cvt_pk_bf16_f32 v65, v62, v63
	v_lshl_add_u64 v[62:63], v[48:49], 0, s[6:7]
	global_store_dwordx2 v[62:63], v[64:65], off sc0 sc1
	s_nop 1
	v_pk_mul_f32 v[62:63], v[74:75], v[42:43] op_sel_hi:[1,0]
	v_pk_mul_f32 v[60:61], v[60:61], v[42:43] op_sel_hi:[1,0]
	v_pk_mul_f32 v[62:63], v[20:21], v[62:63]
	v_pk_mul_f32 v[60:61], v[22:23], v[60:61]
	s_mov_b64 s[6:7], 0x3800400
	v_cvt_pk_bf16_f32 v62, v62, v63
	v_cvt_pk_bf16_f32 v63, v60, v61
	v_lshl_add_u64 v[60:61], v[48:49], 0, s[6:7]
	global_store_dwordx2 v[60:61], v[62:63], off sc0 sc1
	s_nop 1
	v_pk_mul_f32 v[60:61], v[80:81], v[42:43] op_sel_hi:[1,0]
	v_pk_mul_f32 v[58:59], v[58:59], v[42:43] op_sel_hi:[1,0]
	v_pk_mul_f32 v[60:61], v[28:29], v[60:61]
	v_pk_mul_f32 v[58:59], v[30:31], v[58:59]
	s_mov_b64 s[6:7], 0x3800600
	v_cvt_pk_bf16_f32 v60, v60, v61
	v_cvt_pk_bf16_f32 v61, v58, v59
	v_lshl_add_u64 v[58:59], v[48:49], 0, s[6:7]
	global_store_dwordx2 v[58:59], v[60:61], off sc0 sc1
	s_nop 1
	s_cbranch_scc1 .LBB0_2018
	s_add_u32 s6, s16, s0
	s_addc_u32 s7, 0, s1
	s_add_u32 s6, s6, 1
	s_addc_u32 s7, s7, 0
	s_mov_b64 s[10:11], 0

.LBB0_2034:
	s_or_b64 exec, exec, s[38:39]
	s_lshl_b64 s[0:1], s[0:1], 12
	s_add_u32 s0, s10, s0
	s_addc_u32 s1, s11, s1
	v_lshl_add_u64 v[44:45], v[32:33], 3, s[0:1]
	s_lshl_b64 s[0:1], s[64:65], 11
	v_lshl_add_u64 v[54:55], v[38:39], 0, s[0:1]
	global_load_dwordx2 v[46:47], v[44:45], off offset:2048
	global_load_dwordx2 v[48:49], v[44:45], off offset:2560
	global_load_dwordx2 v[50:51], v[44:45], off offset:3072
	global_load_dwordx2 v[52:53], v[44:45], off offset:3584
	global_load_dwordx2 v[56:57], v[54:55], off
	global_load_dwordx2 v[58:59], v[54:55], off offset:512
	global_load_dwordx2 v[60:61], v[54:55], off offset:1024
	s_nop 0
	global_load_dwordx2 v[54:55], v[54:55], off offset:1536
	s_waitcnt vmcnt(8)
	s_nop 1
	v_mov_b32_dpp v62, v42 quad_perm:[1,0,3,2] row_mask:0xf bank_mask:0xf
	s_mov_b64 s[10:11], -1
	s_waitcnt lgkmcnt(0)
	v_add_f32_e32 v42, v42, v62
	s_nop 1
	v_mov_b32_dpp v62, v42 quad_perm:[2,3,0,1] row_mask:0xf bank_mask:0xf
	s_waitcnt lgkmcnt(0)
	v_add_f32_e32 v42, v42, v62
	s_nop 1
	v_mov_b32_dpp v62, v42 row_half_mirror row_mask:0xf bank_mask:0xf
	s_waitcnt lgkmcnt(0)
	v_add_f32_e32 v42, v42, v62
	s_nop 1
	v_mov_b32_dpp v62, v42 row_mirror row_mask:0xf bank_mask:0xf
	s_waitcnt lgkmcnt(0)
	v_add_f32_e32 v42, v42, v62
	v_mov_b32_e32 v62, v42
	s_nop 1
	v_permlane16_swap_b32 v42, v62
	s_waitcnt lgkmcnt(0)
	v_add_f32_e32 v42, v42, v62
	v_mov_b32_e32 v62, v42
	s_nop 1
	v_permlane32_swap_b32 v42, v62
	s_waitcnt lgkmcnt(0)
	v_add_f32_e32 v42, v42, v62
	v_fmamk_f32 v42, v42, 0x3a800000, v90
	v_mul_f32_e32 v62, 0x4b800000, v42
	v_cmp_gt_f32_e32 vcc, s91, v42
	s_waitcnt vmcnt(7)
	v_and_b32_e32 v63, 0xffff0000, v46
	v_cndmask_b32_e32 v42, v42, v62, vcc
	v_rsq_f32_e32 v42, v42
	s_waitcnt vmcnt(3)
	v_lshlrev_b32_e32 v70, 16, v56
	v_and_b32_e32 v71, 0xffff0000, v56
	v_lshlrev_b32_e32 v56, 16, v57
	v_mul_f32_e32 v62, 0x45800000, v42
	v_cndmask_b32_e32 v42, v42, v62, vcc
	v_and_b32_e32 v57, 0xffff0000, v57
	s_waitcnt vmcnt(2)
	v_lshlrev_b32_e32 v72, 16, v58
	v_and_b32_e32 v73, 0xffff0000, v58
	v_lshlrev_b32_e32 v58, 16, v59
	v_and_b32_e32 v59, 0xffff0000, v59
	v_lshlrev_b32_e32 v62, 16, v46
	v_lshlrev_b32_e32 v46, 16, v47
	v_and_b32_e32 v47, 0xffff0000, v47
	v_lshlrev_b32_e32 v64, 16, v48
	v_and_b32_e32 v65, 0xffff0000, v48
	v_lshlrev_b32_e32 v48, 16, v49
	v_and_b32_e32 v49, 0xffff0000, v49
	s_waitcnt vmcnt(1)
	v_lshlrev_b32_e32 v74, 16, v60
	v_and_b32_e32 v75, 0xffff0000, v60
	v_lshlrev_b32_e32 v60, 16, v61
	v_and_b32_e32 v61, 0xffff0000, v61
	v_pk_mul_f32 v[70:71], v[42:43], v[70:71] op_sel_hi:[0,1]
	v_pk_mul_f32 v[56:57], v[42:43], v[56:57] op_sel_hi:[0,1]
	v_pk_mul_f32 v[58:59], v[42:43], v[58:59] op_sel_hi:[0,1]
	v_pk_mul_f32 v[72:73], v[42:43], v[72:73] op_sel_hi:[0,1]
	v_lshlrev_b32_e32 v66, 16, v50
	v_and_b32_e32 v67, 0xffff0000, v50
	v_lshlrev_b32_e32 v50, 16, v51
	v_and_b32_e32 v51, 0xffff0000, v51
	v_pk_mul_f32 v[60:61], v[42:43], v[60:61] op_sel_hi:[0,1]
	v_pk_mul_f32 v[74:75], v[42:43], v[74:75] op_sel_hi:[0,1]
	v_pk_fma_f32 v[46:47], v[2:3], v[56:57], v[46:47]
	v_pk_fma_f32 v[56:57], v[0:1], v[70:71], v[62:63]
	v_pk_fma_f32 v[62:63], v[8:9], v[72:73], v[64:65]
	v_pk_fma_f32 v[48:49], v[10:11], v[58:59], v[48:49]
	v_pk_fma_f32 v[58:59], v[12:13], v[74:75], v[66:67]
	v_pk_fma_f32 v[50:51], v[14:15], v[60:61], v[50:51]
	v_pk_mul_f32 v[60:61], v[46:47], v[46:47]
	v_pk_mul_f32 v[64:65], v[56:57], v[56:57]
	v_pk_mul_f32 v[66:67], v[48:49], v[48:49]
	v_pk_mul_f32 v[70:71], v[62:63], v[62:63]
	v_pk_mov_b32 v[74:75], v[64:65], v[60:61] op_sel:[1,0]
	v_mov_b32_e32 v65, v61
	v_pk_mov_b32 v[60:61], v[70:71], v[66:67] op_sel:[1,0]
	v_mov_b32_e32 v71, v67
	v_pk_add_f32 v[60:61], v[60:61], v[70:71]
	s_waitcnt vmcnt(0)
	v_lshlrev_b32_e32 v76, 16, v54
	v_and_b32_e32 v77, 0xffff0000, v54
	v_lshlrev_b32_e32 v54, 16, v55
	v_and_b32_e32 v55, 0xffff0000, v55
	v_mul_f32_e32 v72, v58, v58
	v_pk_add_f32 v[60:61], v[60:61], v[60:61] op_sel_hi:[0,1]
	v_lshlrev_b32_e32 v68, 16, v52
	v_and_b32_e32 v69, 0xffff0000, v52
	v_lshlrev_b32_e32 v52, 16, v53
	v_and_b32_e32 v53, 0xffff0000, v53
	v_pk_fma_f32 v[66:67], v[58:59], v[58:59], v[72:73] op_sel_hi:[1,1,0]
	v_pk_add_f32 v[64:65], v[74:75], v[64:65]
	v_mul_f32_e32 v60, v50, v50
	v_pk_mul_f32 v[54:55], v[42:43], v[54:55] op_sel_hi:[0,1]
	v_pk_mul_f32 v[72:73], v[42:43], v[76:77] op_sel_hi:[0,1]
	v_pk_add_f32 v[64:65], v[64:65], v[64:65] op_sel_hi:[0,1]
	v_pk_fma_f32 v[70:71], v[50:51], v[50:51], v[60:61] op_sel_hi:[1,1,0]
	v_pk_fma_f32 v[68:69], v[24:25], v[72:73], v[68:69]
	v_pk_fma_f32 v[52:53], v[26:27], v[54:55], v[52:53]
	v_mul_f32_e32 v66, v68, v68
	v_mul_f32_e32 v70, v69, v69
	v_mul_f32_e32 v64, v52, v52
	v_mul_f32_e32 v60, v53, v53
	v_pk_add_f32 v[54:55], v[66:67], v[70:71]
	v_pk_add_f32 v[60:61], v[64:65], v[60:61]
	v_cvt_pk_bf16_f32 v66, v56, v57
	v_lshl_add_u64 v[64:65], v[44:45], 0, s[54:55]
	v_pk_add_f32 v[54:55], v[54:55], v[60:61]
	s_nop 0
	v_add_f32_e32 v42, v54, v55
	s_nop 1
	v_mov_b32_dpp v54, v42 quad_perm:[1,0,3,2] row_mask:0xf bank_mask:0xf
	s_waitcnt lgkmcnt(0)
	v_add_f32_e32 v42, v42, v54
	s_nop 1
	v_mov_b32_dpp v54, v42 quad_perm:[2,3,0,1] row_mask:0xf bank_mask:0xf
	s_waitcnt lgkmcnt(0)
	v_add_f32_e32 v42, v42, v54
	s_nop 1
	v_mov_b32_dpp v60, v42 row_half_mirror row_mask:0xf bank_mask:0xf
	v_lshl_add_u64 v[54:55], v[44:45], 0, s[40:41]
	s_waitcnt lgkmcnt(0)
	v_add_f32_e32 v42, v42, v60
	s_nop 1
	v_mov_b32_dpp v67, v42 row_mirror row_mask:0xf bank_mask:0xf
	v_lshl_add_u64 v[60:61], v[44:45], 0, s[52:53]
	v_lshl_add_u64 v[44:45], v[44:45], 0, s[56:57]
	s_waitcnt lgkmcnt(0)
	v_add_f32_e32 v42, v42, v67
	v_mov_b32_e32 v70, v42
	s_nop 1
	v_permlane16_swap_b32 v42, v70
	v_cvt_pk_bf16_f32 v67, v46, v47
	s_waitcnt lgkmcnt(0)
	v_add_f32_e32 v42, v42, v70
	global_store_dwordx2 v[54:55], v[66:67], off sc0 sc1
	s_nop 1
	v_mov_b32_e32 v66, v42
	s_nop 1
	v_permlane32_swap_b32 v42, v66
	v_cvt_pk_bf16_f32 v54, v62, v63
	v_cvt_pk_bf16_f32 v55, v48, v49
	s_waitcnt lgkmcnt(0)
	v_add_f32_e32 v42, v42, v66
	global_store_dwordx2 v[60:61], v[54:55], off sc0 sc1
	s_nop 1
	v_cvt_pk_bf16_f32 v54, v58, v59
	v_fmamk_f32 v42, v42, 0x3a800000, v90
	v_cvt_pk_bf16_f32 v55, v50, v51
	v_cmp_gt_f32_e32 vcc, s91, v42
	global_store_dwordx2 v[64:65], v[54:55], off sc0 sc1
	s_nop 1
	v_mul_f32_e32 v54, 0x4b800000, v42
	s_nop 0
	v_cndmask_b32_e32 v42, v42, v54, vcc
	v_rsq_f32_e32 v42, v42
	v_cvt_pk_bf16_f32 v54, v68, v69
	v_cvt_pk_bf16_f32 v55, v52, v53
	s_nop 0
	global_store_dwordx2 v[44:45], v[54:55], off sc0 sc1
	s_nop 1
	v_mul_f32_e32 v44, 0x45800000, v42
	v_cndmask_b32_e32 v42, v42, v44, vcc
	v_pk_mul_f32 v[54:55], v[56:57], v[42:43] op_sel_hi:[1,0]
	v_pk_mul_f32 v[46:47], v[46:47], v[42:43] op_sel_hi:[1,0]
	v_pk_mul_f32 v[54:55], v[4:5], v[54:55]
	v_pk_mul_f32 v[46:47], v[6:7], v[46:47]
	v_cvt_pk_bf16_f32 v54, v54, v55
	v_pk_mul_f32 v[48:49], v[48:49], v[42:43] op_sel_hi:[1,0]
	v_cvt_pk_bf16_f32 v55, v46, v47
	v_pk_mul_f32 v[46:47], v[62:63], v[42:43] op_sel_hi:[1,0]
	v_lshl_add_u64 v[44:45], v[36:37], 0, s[0:1]
	v_pk_mul_f32 v[46:47], v[16:17], v[46:47]
	global_store_dwordx2 v[44:45], v[54:55], off sc0 sc1
	s_nop 1
	v_pk_mul_f32 v[48:49], v[18:19], v[48:49]
	v_cvt_pk_bf16_f32 v46, v46, v47
	s_andn2_b64 vcc, exec, s[6:7]
	v_cvt_pk_bf16_f32 v47, v48, v49
	v_lshl_add_u64 v[48:49], v[44:45], 0, s[58:59]
	global_store_dwordx2 v[48:49], v[46:47], off sc0 sc1
	s_nop 1
	v_pk_mul_f32 v[46:47], v[58:59], v[42:43] op_sel_hi:[1,0]
	v_pk_mul_f32 v[48:49], v[50:51], v[42:43] op_sel_hi:[1,0]
	v_pk_mul_f32 v[46:47], v[20:21], v[46:47]
	v_pk_mul_f32 v[48:49], v[22:23], v[48:49]
	v_cvt_pk_bf16_f32 v46, v46, v47
	s_nop 0
	v_cvt_pk_bf16_f32 v47, v48, v49
	v_lshl_add_u64 v[48:49], v[44:45], 0, s[60:61]
	global_store_dwordx2 v[48:49], v[46:47], off sc0 sc1
	s_nop 1
	v_pk_mul_f32 v[46:47], v[68:69], v[42:43] op_sel_hi:[1,0]
	v_pk_mul_f32 v[48:49], v[52:53], v[42:43] op_sel_hi:[1,0]
	v_pk_mul_f32 v[46:47], v[28:29], v[46:47]
	v_pk_mul_f32 v[48:49], v[30:31], v[48:49]
	v_cvt_pk_bf16_f32 v46, v46, v47
	v_lshl_add_u64 v[44:45], v[44:45], 0, s[62:63]
	v_cvt_pk_bf16_f32 v47, v48, v49
	v_cndmask_b32_e64 v42, 0, 1, s[6:7]
	global_store_dwordx2 v[44:45], v[46:47], off sc0 sc1
	s_nop 1
	v_cmp_ne_u32_e64 s[0:1], 1, v42
	s_cbranch_vccnz .LBB0_2036
	s_add_i32 s14, s64, 0xffffbf81
	s_mov_b64 s[10:11], 0
	s_mov_b64 s[6:7], s[14:15]

.LBB0_2043:
	s_or_b64 exec, exec, s[38:39]
	s_lshl_b64 s[6:7], s[6:7], 12
	s_add_u32 s6, s10, s6
	s_addc_u32 s7, s11, s7
	v_lshl_add_u64 v[44:45], v[32:33], 3, s[6:7]
	s_lshl_b64 s[6:7], s[14:15], 11
	v_lshl_add_u64 v[54:55], v[38:39], 0, s[6:7]
	global_load_dwordx2 v[46:47], v[44:45], off offset:2048
	global_load_dwordx2 v[48:49], v[44:45], off offset:2560
	global_load_dwordx2 v[50:51], v[44:45], off offset:3072
	global_load_dwordx2 v[52:53], v[44:45], off offset:3584
	global_load_dwordx2 v[56:57], v[54:55], off
	global_load_dwordx2 v[58:59], v[54:55], off offset:512
	global_load_dwordx2 v[60:61], v[54:55], off offset:1024
	s_nop 0
	global_load_dwordx2 v[54:55], v[54:55], off offset:1536
	s_waitcnt vmcnt(8)
	s_nop 1
	v_mov_b32_dpp v62, v42 quad_perm:[1,0,3,2] row_mask:0xf bank_mask:0xf
	s_mov_b64 s[10:11], -1
	s_waitcnt lgkmcnt(0)
	v_add_f32_e32 v42, v42, v62
	s_nop 1
	v_mov_b32_dpp v62, v42 quad_perm:[2,3,0,1] row_mask:0xf bank_mask:0xf
	s_waitcnt lgkmcnt(0)
	v_add_f32_e32 v42, v42, v62
	s_nop 1
	v_mov_b32_dpp v62, v42 row_half_mirror row_mask:0xf bank_mask:0xf
	s_waitcnt lgkmcnt(0)
	v_add_f32_e32 v42, v42, v62
	s_nop 1
	v_mov_b32_dpp v62, v42 row_mirror row_mask:0xf bank_mask:0xf
	s_waitcnt lgkmcnt(0)
	v_add_f32_e32 v42, v42, v62
	v_mov_b32_e32 v62, v42
	s_nop 1
	v_permlane16_swap_b32 v42, v62
	s_waitcnt lgkmcnt(0)
	v_add_f32_e32 v42, v42, v62
	v_mov_b32_e32 v62, v42
	s_nop 1
	v_permlane32_swap_b32 v42, v62
	s_waitcnt lgkmcnt(0)
	v_add_f32_e32 v42, v42, v62
	v_fmamk_f32 v42, v42, 0x3a800000, v90
	v_mul_f32_e32 v62, 0x4b800000, v42
	v_cmp_gt_f32_e32 vcc, s91, v42
	s_waitcnt vmcnt(7)
	v_and_b32_e32 v63, 0xffff0000, v46
	v_cndmask_b32_e32 v42, v42, v62, vcc
	v_rsq_f32_e32 v42, v42
	s_waitcnt vmcnt(3)
	v_lshlrev_b32_e32 v70, 16, v56
	v_and_b32_e32 v71, 0xffff0000, v56
	v_lshlrev_b32_e32 v56, 16, v57
	v_mul_f32_e32 v62, 0x45800000, v42
	v_cndmask_b32_e32 v42, v42, v62, vcc
	v_and_b32_e32 v57, 0xffff0000, v57
	s_waitcnt vmcnt(2)
	v_lshlrev_b32_e32 v72, 16, v58
	v_and_b32_e32 v73, 0xffff0000, v58
	v_lshlrev_b32_e32 v58, 16, v59
	v_and_b32_e32 v59, 0xffff0000, v59
	v_lshlrev_b32_e32 v62, 16, v46
	v_lshlrev_b32_e32 v46, 16, v47
	v_and_b32_e32 v47, 0xffff0000, v47
	v_lshlrev_b32_e32 v64, 16, v48
	v_and_b32_e32 v65, 0xffff0000, v48
	v_lshlrev_b32_e32 v48, 16, v49
	v_and_b32_e32 v49, 0xffff0000, v49
	s_waitcnt vmcnt(1)
	v_lshlrev_b32_e32 v74, 16, v60
	v_and_b32_e32 v75, 0xffff0000, v60
	v_lshlrev_b32_e32 v60, 16, v61
	v_and_b32_e32 v61, 0xffff0000, v61
	v_pk_mul_f32 v[70:71], v[42:43], v[70:71] op_sel_hi:[0,1]
	v_pk_mul_f32 v[56:57], v[42:43], v[56:57] op_sel_hi:[0,1]
	v_pk_mul_f32 v[58:59], v[42:43], v[58:59] op_sel_hi:[0,1]
	v_pk_mul_f32 v[72:73], v[42:43], v[72:73] op_sel_hi:[0,1]
	v_lshlrev_b32_e32 v66, 16, v50
	v_and_b32_e32 v67, 0xffff0000, v50
	v_lshlrev_b32_e32 v50, 16, v51
	v_and_b32_e32 v51, 0xffff0000, v51
	v_pk_mul_f32 v[60:61], v[42:43], v[60:61] op_sel_hi:[0,1]
	v_pk_mul_f32 v[74:75], v[42:43], v[74:75] op_sel_hi:[0,1]
	v_pk_fma_f32 v[46:47], v[2:3], v[56:57], v[46:47]
	v_pk_fma_f32 v[56:57], v[0:1], v[70:71], v[62:63]
	v_pk_fma_f32 v[62:63], v[8:9], v[72:73], v[64:65]
	v_pk_fma_f32 v[48:49], v[10:11], v[58:59], v[48:49]
	v_pk_fma_f32 v[58:59], v[12:13], v[74:75], v[66:67]
	v_pk_fma_f32 v[50:51], v[14:15], v[60:61], v[50:51]
	v_pk_mul_f32 v[60:61], v[46:47], v[46:47]
	v_pk_mul_f32 v[64:65], v[56:57], v[56:57]
	v_pk_mul_f32 v[66:67], v[48:49], v[48:49]
	v_pk_mul_f32 v[70:71], v[62:63], v[62:63]
	v_pk_mov_b32 v[74:75], v[64:65], v[60:61] op_sel:[1,0]
	v_mov_b32_e32 v65, v61
	v_pk_mov_b32 v[60:61], v[70:71], v[66:67] op_sel:[1,0]
	v_mov_b32_e32 v71, v67
	v_pk_add_f32 v[60:61], v[60:61], v[70:71]
	s_waitcnt vmcnt(0)
	v_lshlrev_b32_e32 v76, 16, v54
	v_and_b32_e32 v77, 0xffff0000, v54
	v_lshlrev_b32_e32 v54, 16, v55
	v_and_b32_e32 v55, 0xffff0000, v55
	v_mul_f32_e32 v72, v58, v58
	v_pk_add_f32 v[60:61], v[60:61], v[60:61] op_sel_hi:[0,1]
	v_lshlrev_b32_e32 v68, 16, v52
	v_and_b32_e32 v69, 0xffff0000, v52
	v_lshlrev_b32_e32 v52, 16, v53
	v_and_b32_e32 v53, 0xffff0000, v53
	v_pk_fma_f32 v[66:67], v[58:59], v[58:59], v[72:73] op_sel_hi:[1,1,0]
	v_pk_add_f32 v[64:65], v[74:75], v[64:65]
	v_mul_f32_e32 v60, v50, v50
	v_pk_mul_f32 v[54:55], v[42:43], v[54:55] op_sel_hi:[0,1]
	v_pk_mul_f32 v[72:73], v[42:43], v[76:77] op_sel_hi:[0,1]
	v_pk_add_f32 v[64:65], v[64:65], v[64:65] op_sel_hi:[0,1]
	v_pk_fma_f32 v[70:71], v[50:51], v[50:51], v[60:61] op_sel_hi:[1,1,0]
	v_pk_fma_f32 v[68:69], v[24:25], v[72:73], v[68:69]
	v_pk_fma_f32 v[52:53], v[26:27], v[54:55], v[52:53]
	v_mul_f32_e32 v66, v68, v68
	v_mul_f32_e32 v70, v69, v69
	v_mul_f32_e32 v64, v52, v52
	v_mul_f32_e32 v60, v53, v53
	v_pk_add_f32 v[54:55], v[66:67], v[70:71]
	v_pk_add_f32 v[60:61], v[64:65], v[60:61]
	v_cvt_pk_bf16_f32 v66, v56, v57
	v_lshl_add_u64 v[64:65], v[44:45], 0, s[54:55]
	v_pk_add_f32 v[54:55], v[54:55], v[60:61]
	s_nop 0
	v_add_f32_e32 v42, v54, v55
	s_nop 1
	v_mov_b32_dpp v54, v42 quad_perm:[1,0,3,2] row_mask:0xf bank_mask:0xf
	s_waitcnt lgkmcnt(0)
	v_add_f32_e32 v42, v42, v54
	s_nop 1
	v_mov_b32_dpp v54, v42 quad_perm:[2,3,0,1] row_mask:0xf bank_mask:0xf
	s_waitcnt lgkmcnt(0)
	v_add_f32_e32 v42, v42, v54
	s_nop 1
	v_mov_b32_dpp v60, v42 row_half_mirror row_mask:0xf bank_mask:0xf
	v_lshl_add_u64 v[54:55], v[44:45], 0, s[40:41]
	s_waitcnt lgkmcnt(0)
	v_add_f32_e32 v42, v42, v60
	s_nop 1
	v_mov_b32_dpp v67, v42 row_mirror row_mask:0xf bank_mask:0xf
	v_lshl_add_u64 v[60:61], v[44:45], 0, s[52:53]
	v_lshl_add_u64 v[44:45], v[44:45], 0, s[56:57]
	s_waitcnt lgkmcnt(0)
	v_add_f32_e32 v42, v42, v67
	v_mov_b32_e32 v70, v42
	s_nop 1
	v_permlane16_swap_b32 v42, v70
	v_cvt_pk_bf16_f32 v67, v46, v47
	s_waitcnt lgkmcnt(0)
	v_add_f32_e32 v42, v42, v70
	global_store_dwordx2 v[54:55], v[66:67], off sc0 sc1
	s_nop 1
	v_mov_b32_e32 v66, v42
	s_nop 1
	v_permlane32_swap_b32 v42, v66
	v_cvt_pk_bf16_f32 v54, v62, v63
	v_cvt_pk_bf16_f32 v55, v48, v49
	s_waitcnt lgkmcnt(0)
	v_add_f32_e32 v42, v42, v66
	global_store_dwordx2 v[60:61], v[54:55], off sc0 sc1
	s_nop 1
	v_cvt_pk_bf16_f32 v54, v58, v59
	v_fmamk_f32 v42, v42, 0x3a800000, v90
	v_cvt_pk_bf16_f32 v55, v50, v51
	v_cmp_gt_f32_e32 vcc, s91, v42
	global_store_dwordx2 v[64:65], v[54:55], off sc0 sc1
	s_nop 1
	v_mul_f32_e32 v54, 0x4b800000, v42
	s_nop 0
	v_cndmask_b32_e32 v42, v42, v54, vcc
	v_rsq_f32_e32 v42, v42
	v_cvt_pk_bf16_f32 v54, v68, v69
	v_cvt_pk_bf16_f32 v55, v52, v53
	s_nop 0
	global_store_dwordx2 v[44:45], v[54:55], off sc0 sc1
	s_nop 1
	v_mul_f32_e32 v44, 0x45800000, v42
	v_cndmask_b32_e32 v42, v42, v44, vcc
	v_pk_mul_f32 v[54:55], v[56:57], v[42:43] op_sel_hi:[1,0]
	v_pk_mul_f32 v[46:47], v[46:47], v[42:43] op_sel_hi:[1,0]
	v_pk_mul_f32 v[54:55], v[4:5], v[54:55]
	v_pk_mul_f32 v[46:47], v[6:7], v[46:47]
	v_cvt_pk_bf16_f32 v54, v54, v55
	v_pk_mul_f32 v[48:49], v[48:49], v[42:43] op_sel_hi:[1,0]
	v_cvt_pk_bf16_f32 v55, v46, v47
	v_pk_mul_f32 v[46:47], v[62:63], v[42:43] op_sel_hi:[1,0]
	v_lshl_add_u64 v[44:45], v[36:37], 0, s[6:7]
	v_pk_mul_f32 v[46:47], v[16:17], v[46:47]
	global_store_dwordx2 v[44:45], v[54:55], off sc0 sc1
	s_nop 1
	v_pk_mul_f32 v[48:49], v[18:19], v[48:49]
	v_cvt_pk_bf16_f32 v46, v46, v47
	s_and_b64 vcc, exec, s[0:1]
	v_cvt_pk_bf16_f32 v47, v48, v49
	v_lshl_add_u64 v[48:49], v[44:45], 0, s[58:59]
	global_store_dwordx2 v[48:49], v[46:47], off sc0 sc1
	s_nop 1
	v_pk_mul_f32 v[46:47], v[58:59], v[42:43] op_sel_hi:[1,0]
	v_pk_mul_f32 v[48:49], v[50:51], v[42:43] op_sel_hi:[1,0]
	v_pk_mul_f32 v[46:47], v[20:21], v[46:47]
	v_pk_mul_f32 v[48:49], v[22:23], v[48:49]
	v_cvt_pk_bf16_f32 v46, v46, v47
	s_nop 0
	v_cvt_pk_bf16_f32 v47, v48, v49
	v_lshl_add_u64 v[48:49], v[44:45], 0, s[60:61]
	global_store_dwordx2 v[48:49], v[46:47], off sc0 sc1
	s_nop 1
	v_pk_mul_f32 v[46:47], v[68:69], v[42:43] op_sel_hi:[1,0]
	v_pk_mul_f32 v[48:49], v[52:53], v[42:43] op_sel_hi:[1,0]
	v_pk_mul_f32 v[46:47], v[28:29], v[46:47]
	v_pk_mul_f32 v[48:49], v[30:31], v[48:49]
	v_cvt_pk_bf16_f32 v46, v46, v47
	v_lshl_add_u64 v[44:45], v[44:45], 0, s[62:63]
	v_cvt_pk_bf16_f32 v47, v48, v49
	s_nop 0
	global_store_dwordx2 v[44:45], v[46:47], off sc0 sc1
	s_nop 1
	s_cbranch_vccnz .LBB0_2045
	s_add_i32 s14, s64, 0xffffbf82
	s_mov_b64 s[10:11], 0
	s_mov_b64 s[6:7], s[14:15]

.LBB0_2052:
	s_or_b64 exec, exec, s[38:39]
	s_lshl_b64 s[6:7], s[6:7], 12
	s_add_u32 s6, s10, s6
	s_addc_u32 s7, s11, s7
	v_lshl_add_u64 v[44:45], v[32:33], 3, s[6:7]
	s_lshl_b64 s[6:7], s[14:15], 11
	v_lshl_add_u64 v[54:55], v[38:39], 0, s[6:7]
	global_load_dwordx2 v[46:47], v[44:45], off offset:2048
	global_load_dwordx2 v[48:49], v[44:45], off offset:2560
	global_load_dwordx2 v[50:51], v[44:45], off offset:3072
	global_load_dwordx2 v[52:53], v[44:45], off offset:3584
	global_load_dwordx2 v[56:57], v[54:55], off
	global_load_dwordx2 v[58:59], v[54:55], off offset:512
	global_load_dwordx2 v[60:61], v[54:55], off offset:1024
	s_nop 0
	global_load_dwordx2 v[54:55], v[54:55], off offset:1536
	s_waitcnt vmcnt(8)
	s_nop 1
	v_mov_b32_dpp v62, v42 quad_perm:[1,0,3,2] row_mask:0xf bank_mask:0xf
	s_waitcnt lgkmcnt(0)
	v_add_f32_e32 v42, v42, v62
	s_nop 1
	v_mov_b32_dpp v62, v42 quad_perm:[2,3,0,1] row_mask:0xf bank_mask:0xf
	s_waitcnt lgkmcnt(0)
	v_add_f32_e32 v42, v42, v62
	s_nop 1
	v_mov_b32_dpp v62, v42 row_half_mirror row_mask:0xf bank_mask:0xf
	s_waitcnt lgkmcnt(0)
	v_add_f32_e32 v42, v42, v62
	s_nop 1
	v_mov_b32_dpp v62, v42 row_mirror row_mask:0xf bank_mask:0xf
	s_waitcnt lgkmcnt(0)
	v_add_f32_e32 v42, v42, v62
	v_mov_b32_e32 v62, v42
	s_nop 1
	v_permlane16_swap_b32 v42, v62
	s_waitcnt lgkmcnt(0)
	v_add_f32_e32 v42, v42, v62
	v_mov_b32_e32 v62, v42
	s_nop 1
	v_permlane32_swap_b32 v42, v62
	s_waitcnt lgkmcnt(0)
	v_add_f32_e32 v42, v42, v62
	v_fmamk_f32 v42, v42, 0x3a800000, v90
	v_mul_f32_e32 v62, 0x4b800000, v42
	v_cmp_gt_f32_e32 vcc, s91, v42
	s_waitcnt vmcnt(7)
	v_and_b32_e32 v63, 0xffff0000, v46
	v_cndmask_b32_e32 v42, v42, v62, vcc
	v_rsq_f32_e32 v42, v42
	s_waitcnt vmcnt(3)
	v_lshlrev_b32_e32 v70, 16, v56
	v_and_b32_e32 v71, 0xffff0000, v56
	v_lshlrev_b32_e32 v56, 16, v57
	v_mul_f32_e32 v62, 0x45800000, v42
	v_cndmask_b32_e32 v42, v42, v62, vcc
	v_and_b32_e32 v57, 0xffff0000, v57
	s_waitcnt vmcnt(2)
	v_lshlrev_b32_e32 v72, 16, v58
	v_and_b32_e32 v73, 0xffff0000, v58
	v_lshlrev_b32_e32 v58, 16, v59
	v_and_b32_e32 v59, 0xffff0000, v59
	v_lshlrev_b32_e32 v62, 16, v46
	v_lshlrev_b32_e32 v46, 16, v47
	v_and_b32_e32 v47, 0xffff0000, v47
	v_lshlrev_b32_e32 v64, 16, v48
	v_and_b32_e32 v65, 0xffff0000, v48
	v_lshlrev_b32_e32 v48, 16, v49
	v_and_b32_e32 v49, 0xffff0000, v49
	s_waitcnt vmcnt(1)
	v_lshlrev_b32_e32 v74, 16, v60
	v_and_b32_e32 v75, 0xffff0000, v60
	v_lshlrev_b32_e32 v60, 16, v61
	v_and_b32_e32 v61, 0xffff0000, v61
	v_pk_mul_f32 v[70:71], v[42:43], v[70:71] op_sel_hi:[0,1]
	v_pk_mul_f32 v[56:57], v[42:43], v[56:57] op_sel_hi:[0,1]
	v_pk_mul_f32 v[58:59], v[42:43], v[58:59] op_sel_hi:[0,1]
	v_pk_mul_f32 v[72:73], v[42:43], v[72:73] op_sel_hi:[0,1]
	v_lshlrev_b32_e32 v66, 16, v50
	v_and_b32_e32 v67, 0xffff0000, v50
	v_lshlrev_b32_e32 v50, 16, v51
	v_and_b32_e32 v51, 0xffff0000, v51
	v_pk_mul_f32 v[60:61], v[42:43], v[60:61] op_sel_hi:[0,1]
	v_pk_mul_f32 v[74:75], v[42:43], v[74:75] op_sel_hi:[0,1]
	v_pk_fma_f32 v[46:47], v[2:3], v[56:57], v[46:47]
	v_pk_fma_f32 v[56:57], v[0:1], v[70:71], v[62:63]
	v_pk_fma_f32 v[62:63], v[8:9], v[72:73], v[64:65]
	v_pk_fma_f32 v[48:49], v[10:11], v[58:59], v[48:49]
	v_pk_fma_f32 v[58:59], v[12:13], v[74:75], v[66:67]
	v_pk_fma_f32 v[50:51], v[14:15], v[60:61], v[50:51]
	v_pk_mul_f32 v[60:61], v[46:47], v[46:47]
	v_pk_mul_f32 v[64:65], v[56:57], v[56:57]
	v_pk_mul_f32 v[66:67], v[48:49], v[48:49]
	v_pk_mul_f32 v[70:71], v[62:63], v[62:63]
	v_pk_mov_b32 v[74:75], v[64:65], v[60:61] op_sel:[1,0]
	v_mov_b32_e32 v65, v61
	v_pk_mov_b32 v[60:61], v[70:71], v[66:67] op_sel:[1,0]
	v_mov_b32_e32 v71, v67
	v_pk_add_f32 v[60:61], v[60:61], v[70:71]
	s_waitcnt vmcnt(0)
	v_lshlrev_b32_e32 v76, 16, v54
	v_and_b32_e32 v77, 0xffff0000, v54
	v_lshlrev_b32_e32 v54, 16, v55
	v_and_b32_e32 v55, 0xffff0000, v55
	v_mul_f32_e32 v72, v58, v58
	v_pk_add_f32 v[60:61], v[60:61], v[60:61] op_sel_hi:[0,1]
	v_lshlrev_b32_e32 v68, 16, v52
	v_and_b32_e32 v69, 0xffff0000, v52
	v_lshlrev_b32_e32 v52, 16, v53
	v_and_b32_e32 v53, 0xffff0000, v53
	v_pk_fma_f32 v[66:67], v[58:59], v[58:59], v[72:73] op_sel_hi:[1,1,0]
	v_pk_add_f32 v[64:65], v[74:75], v[64:65]
	v_mul_f32_e32 v60, v50, v50
	v_pk_mul_f32 v[54:55], v[42:43], v[54:55] op_sel_hi:[0,1]
	v_pk_mul_f32 v[72:73], v[42:43], v[76:77] op_sel_hi:[0,1]
	v_pk_add_f32 v[64:65], v[64:65], v[64:65] op_sel_hi:[0,1]
	v_pk_fma_f32 v[70:71], v[50:51], v[50:51], v[60:61] op_sel_hi:[1,1,0]
	v_pk_fma_f32 v[68:69], v[24:25], v[72:73], v[68:69]
	v_pk_fma_f32 v[52:53], v[26:27], v[54:55], v[52:53]
	v_mul_f32_e32 v66, v68, v68
	v_mul_f32_e32 v70, v69, v69
	v_mul_f32_e32 v64, v52, v52
	v_mul_f32_e32 v60, v53, v53
	v_pk_add_f32 v[54:55], v[66:67], v[70:71]
	v_pk_add_f32 v[60:61], v[64:65], v[60:61]
	v_cvt_pk_bf16_f32 v66, v56, v57
	v_lshl_add_u64 v[64:65], v[44:45], 0, s[54:55]
	v_pk_add_f32 v[54:55], v[54:55], v[60:61]
	s_nop 0
	v_add_f32_e32 v42, v54, v55
	s_nop 1
	v_mov_b32_dpp v54, v42 quad_perm:[1,0,3,2] row_mask:0xf bank_mask:0xf
	s_waitcnt lgkmcnt(0)
	v_add_f32_e32 v42, v42, v54
	s_nop 1
	v_mov_b32_dpp v54, v42 quad_perm:[2,3,0,1] row_mask:0xf bank_mask:0xf
	s_waitcnt lgkmcnt(0)
	v_add_f32_e32 v42, v42, v54
	s_nop 1
	v_mov_b32_dpp v60, v42 row_half_mirror row_mask:0xf bank_mask:0xf
	v_lshl_add_u64 v[54:55], v[44:45], 0, s[40:41]
	s_waitcnt lgkmcnt(0)
	v_add_f32_e32 v42, v42, v60
	s_nop 1
	v_mov_b32_dpp v67, v42 row_mirror row_mask:0xf bank_mask:0xf
	v_lshl_add_u64 v[60:61], v[44:45], 0, s[52:53]
	v_lshl_add_u64 v[44:45], v[44:45], 0, s[56:57]
	s_waitcnt lgkmcnt(0)
	v_add_f32_e32 v42, v42, v67
	v_mov_b32_e32 v70, v42
	s_nop 1
	v_permlane16_swap_b32 v42, v70
	v_cvt_pk_bf16_f32 v67, v46, v47
	s_waitcnt lgkmcnt(0)
	v_add_f32_e32 v42, v42, v70
	global_store_dwordx2 v[54:55], v[66:67], off sc0 sc1
	s_nop 1
	v_mov_b32_e32 v66, v42
	s_nop 1
	v_permlane32_swap_b32 v42, v66
	v_cvt_pk_bf16_f32 v54, v62, v63
	v_cvt_pk_bf16_f32 v55, v48, v49
	s_waitcnt lgkmcnt(0)
	v_add_f32_e32 v42, v42, v66
	global_store_dwordx2 v[60:61], v[54:55], off sc0 sc1
	s_nop 1
	v_cvt_pk_bf16_f32 v54, v58, v59
	v_fmamk_f32 v42, v42, 0x3a800000, v90
	v_cvt_pk_bf16_f32 v55, v50, v51
	v_cmp_gt_f32_e32 vcc, s91, v42
	global_store_dwordx2 v[64:65], v[54:55], off sc0 sc1
	s_nop 1
	v_mul_f32_e32 v54, 0x4b800000, v42
	s_nop 0
	v_cndmask_b32_e32 v42, v42, v54, vcc
	v_rsq_f32_e32 v42, v42
	v_cvt_pk_bf16_f32 v54, v68, v69
	v_cvt_pk_bf16_f32 v55, v52, v53
	s_nop 0
	global_store_dwordx2 v[44:45], v[54:55], off sc0 sc1
	s_nop 1
	v_mul_f32_e32 v44, 0x45800000, v42
	v_cndmask_b32_e32 v42, v42, v44, vcc
	v_pk_mul_f32 v[54:55], v[56:57], v[42:43] op_sel_hi:[1,0]
	v_pk_mul_f32 v[46:47], v[46:47], v[42:43] op_sel_hi:[1,0]
	v_pk_mul_f32 v[54:55], v[4:5], v[54:55]
	v_pk_mul_f32 v[46:47], v[6:7], v[46:47]
	v_cvt_pk_bf16_f32 v54, v54, v55
	v_pk_mul_f32 v[48:49], v[48:49], v[42:43] op_sel_hi:[1,0]
	v_cvt_pk_bf16_f32 v55, v46, v47
	v_pk_mul_f32 v[46:47], v[62:63], v[42:43] op_sel_hi:[1,0]
	v_lshl_add_u64 v[44:45], v[36:37], 0, s[6:7]
	v_pk_mul_f32 v[46:47], v[16:17], v[46:47]
	global_store_dwordx2 v[44:45], v[54:55], off sc0 sc1
	s_nop 1
	v_pk_mul_f32 v[48:49], v[18:19], v[48:49]
	v_cvt_pk_bf16_f32 v46, v46, v47
	s_and_b64 vcc, exec, s[0:1]
	v_cvt_pk_bf16_f32 v47, v48, v49
	v_lshl_add_u64 v[48:49], v[44:45], 0, s[58:59]
	global_store_dwordx2 v[48:49], v[46:47], off sc0 sc1
	s_nop 1
	v_pk_mul_f32 v[46:47], v[58:59], v[42:43] op_sel_hi:[1,0]
	v_pk_mul_f32 v[48:49], v[50:51], v[42:43] op_sel_hi:[1,0]
	v_pk_mul_f32 v[46:47], v[20:21], v[46:47]
	v_pk_mul_f32 v[48:49], v[22:23], v[48:49]
	v_cvt_pk_bf16_f32 v46, v46, v47
	s_mov_b64 s[6:7], -1
	v_cvt_pk_bf16_f32 v47, v48, v49
	v_lshl_add_u64 v[48:49], v[44:45], 0, s[60:61]
	global_store_dwordx2 v[48:49], v[46:47], off sc0 sc1
	s_nop 1
	v_pk_mul_f32 v[46:47], v[68:69], v[42:43] op_sel_hi:[1,0]
	v_pk_mul_f32 v[48:49], v[52:53], v[42:43] op_sel_hi:[1,0]
	v_pk_mul_f32 v[46:47], v[28:29], v[46:47]
	v_pk_mul_f32 v[48:49], v[30:31], v[48:49]
	v_cvt_pk_bf16_f32 v46, v46, v47
	v_lshl_add_u64 v[44:45], v[44:45], 0, s[62:63]
	v_cvt_pk_bf16_f32 v47, v48, v49
	s_nop 0
	global_store_dwordx2 v[44:45], v[46:47], off sc0 sc1
	s_nop 1
	s_cbranch_vccnz .LBB0_2054
	s_add_i32 s14, s64, 0xffffbf83
	s_mov_b64 s[6:7], 0
	s_mov_b64 s[0:1], s[14:15]

.LBB0_2392:
	s_or_b64 exec, exec, s[16:17]
	s_lshl_b64 s[4:5], s[4:5], 12
	s_add_u32 s4, s8, s4
	s_addc_u32 s5, s9, s5
	v_lshl_add_u64 v[24:25], v[152:153], 3, s[4:5]
	s_lshl_b64 s[4:5], s[2:3], 11
	global_load_dwordx2 v[26:27], v[24:25], off offset:2048
	global_load_dwordx2 v[28:29], v[24:25], off offset:2560
	global_load_dwordx2 v[30:31], v[24:25], off offset:3072
	global_load_dwordx2 v[32:33], v[24:25], off offset:3584
	v_lshl_add_u64 v[24:25], v[18:19], 0, s[4:5]
	global_load_dwordx2 v[34:35], v[24:25], off
	global_load_dwordx2 v[36:37], v[24:25], off offset:512
	global_load_dwordx2 v[38:39], v[24:25], off offset:1024
	global_load_dwordx2 v[40:41], v[24:25], off offset:1536
	s_waitcnt vmcnt(8)
	s_nop 1
	v_mov_b32_dpp v24, v22 quad_perm:[1,0,3,2] row_mask:0xf bank_mask:0xf
	s_lshl_b64 s[4:5], s[12:13], 12
	s_add_u32 s4, s14, s4
	s_addc_u32 s5, s15, s5
	v_lshl_add_u64 v[42:43], v[152:153], 4, s[4:5]
	s_waitcnt lgkmcnt(0)
	v_add_f32_e32 v22, v22, v24
	s_nop 1
	v_mov_b32_dpp v24, v22 quad_perm:[2,3,0,1] row_mask:0xf bank_mask:0xf
	s_waitcnt lgkmcnt(0)
	v_add_f32_e32 v22, v22, v24
	s_nop 1
	v_mov_b32_dpp v24, v22 row_half_mirror row_mask:0xf bank_mask:0xf
	s_waitcnt lgkmcnt(0)
	v_add_f32_e32 v22, v22, v24
	s_nop 1
	v_mov_b32_dpp v24, v22 row_mirror row_mask:0xf bank_mask:0xf
	s_waitcnt lgkmcnt(0)
	v_add_f32_e32 v22, v22, v24
	v_mov_b32_e32 v24, v22
	s_nop 1
	v_permlane16_swap_b32 v22, v24
	s_waitcnt lgkmcnt(0)
	v_add_f32_e32 v22, v22, v24
	v_mov_b32_e32 v24, v22
	s_nop 1
	v_permlane32_swap_b32 v22, v24
	s_waitcnt lgkmcnt(0)
	v_add_f32_e32 v22, v22, v24
	v_fmamk_f32 v22, v22, 0x3a800000, v122
	v_mul_f32_e32 v24, 0x4b800000, v22
	v_cmp_gt_f32_e32 vcc, s67, v22
	s_waitcnt vmcnt(7)
	v_and_b32_e32 v25, 0xffff0000, v26
	v_cndmask_b32_e32 v22, v22, v24, vcc
	v_rsq_f32_e32 v22, v22
	s_waitcnt vmcnt(5)
	v_lshlrev_b32_e32 v46, 16, v30
	v_and_b32_e32 v47, 0xffff0000, v30
	v_lshlrev_b32_e32 v48, 16, v31
	v_mul_f32_e32 v24, 0x45800000, v22
	v_cndmask_b32_e32 v22, v22, v24, vcc
	v_and_b32_e32 v49, 0xffff0000, v31
	s_waitcnt vmcnt(4)
	v_lshlrev_b32_e32 v50, 16, v32
	v_and_b32_e32 v51, 0xffff0000, v32
	v_lshlrev_b32_e32 v52, 16, v33
	v_and_b32_e32 v53, 0xffff0000, v33
	s_waitcnt vmcnt(3)
	v_lshlrev_b32_e32 v30, 16, v34
	v_and_b32_e32 v31, 0xffff0000, v34
	v_lshlrev_b32_e32 v32, 16, v35
	v_and_b32_e32 v33, 0xffff0000, v35
	v_lshlrev_b32_e32 v24, 16, v26
	v_lshlrev_b32_e32 v26, 16, v27
	v_and_b32_e32 v27, 0xffff0000, v27
	s_waitcnt vmcnt(2)
	v_lshlrev_b32_e32 v34, 16, v36
	v_and_b32_e32 v35, 0xffff0000, v36
	v_lshlrev_b32_e32 v36, 16, v37
	v_and_b32_e32 v37, 0xffff0000, v37
	s_waitcnt vmcnt(1)
	v_lshlrev_b32_e32 v54, 16, v38
	v_and_b32_e32 v55, 0xffff0000, v38
	v_lshlrev_b32_e32 v38, 16, v39
	v_and_b32_e32 v39, 0xffff0000, v39
	s_waitcnt vmcnt(0)
	v_lshlrev_b32_e32 v56, 16, v40
	v_and_b32_e32 v57, 0xffff0000, v40
	v_lshlrev_b32_e32 v40, 16, v41
	v_and_b32_e32 v41, 0xffff0000, v41
	v_pk_mul_f32 v[30:31], v[22:23], v[30:31] op_sel_hi:[0,1]
	v_pk_mul_f32 v[32:33], v[22:23], v[32:33] op_sel_hi:[0,1]
	v_lshlrev_b32_e32 v44, 16, v28
	v_and_b32_e32 v45, 0xffff0000, v28
	v_lshlrev_b32_e32 v28, 16, v29
	v_and_b32_e32 v29, 0xffff0000, v29
	v_pk_mul_f32 v[34:35], v[22:23], v[34:35] op_sel_hi:[0,1]
	v_pk_mul_f32 v[36:37], v[22:23], v[36:37] op_sel_hi:[0,1]
	v_pk_mul_f32 v[54:55], v[22:23], v[54:55] op_sel_hi:[0,1]
	v_pk_mul_f32 v[38:39], v[22:23], v[38:39] op_sel_hi:[0,1]
	v_pk_mul_f32 v[56:57], v[22:23], v[56:57] op_sel_hi:[0,1]
	v_pk_mul_f32 v[40:41], v[22:23], v[40:41] op_sel_hi:[0,1]
	v_pk_fma_f32 v[26:27], v[10:11], v[32:33], v[26:27]
	v_pk_fma_f32 v[24:25], v[8:9], v[30:31], v[24:25]
	v_pk_fma_f32 v[30:31], v[2:3], v[36:37], v[28:29]
	v_pk_fma_f32 v[28:29], v[0:1], v[34:35], v[44:45]
	v_pk_fma_f32 v[34:35], v[6:7], v[38:39], v[48:49]
	v_pk_fma_f32 v[32:33], v[4:5], v[54:55], v[46:47]
	v_pk_fma_f32 v[38:39], v[14:15], v[40:41], v[52:53]
	v_pk_fma_f32 v[36:37], v[12:13], v[56:57], v[50:51]
	global_store_dwordx4 v[42:43], v[24:27], off
	global_store_dwordx4 v[42:43], v[28:31], off offset:1024
	global_store_dwordx4 v[42:43], v[32:35], off offset:2048
	global_store_dwordx4 v[42:43], v[36:39], off offset:3072

.LBB0_2432:
	global_load_dwordx2 v[50:51], v[26:27], off offset:2048
	global_load_dwordx2 v[52:53], v[26:27], off offset:2560
	global_load_dwordx2 v[54:55], v[26:27], off offset:3072
	global_load_dwordx2 v[56:57], v[26:27], off offset:3584
	global_load_dwordx2 v[68:69], v[28:29], off offset:2048
	global_load_dwordx2 v[76:77], v[28:29], off offset:2560
	global_load_dwordx2 v[80:81], v[28:29], off offset:3072
	global_load_dwordx2 v[82:83], v[28:29], off offset:3584
	global_load_dwordx2 v[92:93], v[30:31], off offset:2048
	global_load_dwordx2 v[102:103], v[30:31], off offset:2560
	global_load_dwordx2 v[104:105], v[30:31], off offset:3072
	global_load_dwordx2 v[106:107], v[30:31], off offset:3584
	global_load_dwordx2 v[108:109], v[32:33], off offset:2048
	global_load_dwordx2 v[84:85], v[32:33], off offset:2560
	global_load_dwordx2 v[58:59], v[32:33], off offset:3072
	global_load_dwordx2 v[48:49], v[32:33], off offset:3584
	global_load_dwordx2 v[110:111], v[34:35], off offset:2048
	global_load_dwordx2 v[90:91], v[34:35], off offset:2560
	global_load_dwordx2 v[60:61], v[34:35], off offset:3072
	s_nop 0
	global_load_dwordx2 v[34:35], v[34:35], off offset:3584
	s_nop 0
	global_load_dwordx2 v[112:113], v[36:37], off offset:2048
	global_load_dwordx2 v[94:95], v[36:37], off offset:2560
	global_load_dwordx2 v[62:63], v[36:37], off offset:3072
	s_nop 0
	global_load_dwordx2 v[36:37], v[36:37], off offset:3584
	s_nop 0
	global_load_dwordx2 v[114:115], v[38:39], off offset:2048
	global_load_dwordx2 v[96:97], v[38:39], off offset:2560
	global_load_dwordx2 v[64:65], v[38:39], off offset:3072
	s_nop 0
	global_load_dwordx2 v[38:39], v[38:39], off offset:3584
	s_nop 0
	global_load_dwordx2 v[116:117], v[40:41], off offset:2048
	global_load_dwordx2 v[98:99], v[40:41], off offset:2560
	global_load_dwordx2 v[66:67], v[40:41], off offset:3072
	s_nop 0
	global_load_dwordx2 v[40:41], v[40:41], off offset:3584
	s_nop 0
	global_load_dwordx2 v[118:119], v[42:43], off offset:2048
	global_load_dwordx2 v[100:101], v[42:43], off offset:2560
	global_load_dwordx2 v[70:71], v[42:43], off offset:3072
	s_nop 0
	global_load_dwordx2 v[42:43], v[42:43], off offset:3584
	s_nop 0
	global_load_dwordx2 v[120:121], v[44:45], off offset:2048
	global_load_dwordx2 v[126:127], v[44:45], off offset:2560
	global_load_dwordx2 v[72:73], v[44:45], off offset:3072
	s_nop 0
	global_load_dwordx2 v[44:45], v[44:45], off offset:3584
	s_nop 0
	global_load_dwordx2 v[128:129], v[46:47], off offset:2048
	global_load_dwordx2 v[130:131], v[46:47], off offset:2560
	global_load_dwordx2 v[74:75], v[46:47], off offset:3072
	s_nop 0
	global_load_dwordx2 v[46:47], v[46:47], off offset:3584
	s_lshl_b64 s[16:17], s[16:17], 12
	s_add_u32 s14, s14, s16
	s_addc_u32 s15, s15, s17
	s_lshl_b64 s[16:17], s[20:21], 12
	s_add_u32 s16, s24, s16
	s_addc_u32 s17, s25, s17
	v_lshl_add_u64 v[26:27], v[152:153], 3, s[16:17]
	global_load_dwordx2 v[32:33], v[26:27], off offset:2048
	global_load_dwordx2 v[30:31], v[26:27], off offset:2560
	global_load_dwordx2 v[28:29], v[26:27], off offset:3072
	s_nop 0
	global_load_dwordx2 v[26:27], v[26:27], off offset:3584
	s_add_u32 s12, s12, 0x1000
	s_addc_u32 s13, s13, 0
	s_add_i32 s28, s28, 2
	s_add_u32 s4, s4, 2
	s_addc_u32 s5, s5, 0
	s_add_i32 s9, s9, 2
	s_cmpk_eq_i32 s12, 0x2000
	s_waitcnt vmcnt(38)
	v_lshlrev_b32_e32 v158, 16, v102
	s_waitcnt vmcnt(37)
	v_lshlrev_b32_e32 v160, 16, v104
	v_and_b32_e32 v161, 0xffff0000, v104
	v_and_b32_e32 v159, 0xffff0000, v102
	v_lshlrev_b32_e32 v102, 16, v103
	v_and_b32_e32 v103, 0xffff0000, v103
	v_lshlrev_b32_e32 v132, 16, v50
	v_and_b32_e32 v133, 0xffff0000, v50
	v_lshlrev_b32_e32 v134, 16, v51
	v_and_b32_e32 v135, 0xffff0000, v51
	v_lshlrev_b32_e32 v50, 16, v68
	v_and_b32_e32 v51, 0xffff0000, v68
	v_lshlrev_b32_e32 v142, 16, v76
	v_and_b32_e32 v143, 0xffff0000, v76
	v_lshlrev_b32_e32 v144, 16, v77
	v_and_b32_e32 v145, 0xffff0000, v77
	v_lshlrev_b32_e32 v76, 16, v92
	v_and_b32_e32 v77, 0xffff0000, v92
	v_lshlrev_b32_e32 v156, 16, v93
	v_and_b32_e32 v157, 0xffff0000, v93
	v_lshlrev_b32_e32 v92, 16, v105
	v_and_b32_e32 v93, 0xffff0000, v105
	v_pk_add_f32 v[104:105], v[132:133], 0 op_sel_hi:[1,0]
	v_lshlrev_b32_e32 v140, 16, v54
	v_pk_add_f32 v[50:51], v[104:105], v[50:51]
	v_and_b32_e32 v141, 0xffff0000, v54
	v_pk_add_f32 v[50:51], v[50:51], v[76:77]
	s_waitcnt vmcnt(35)
	v_lshlrev_b32_e32 v76, 16, v108
	v_and_b32_e32 v77, 0xffff0000, v108
	v_pk_add_f32 v[50:51], v[50:51], v[76:77]
	s_waitcnt vmcnt(31)
	v_lshlrev_b32_e32 v76, 16, v110
	v_and_b32_e32 v77, 0xffff0000, v110
	v_pk_add_f32 v[50:51], v[50:51], v[76:77]
	s_waitcnt vmcnt(27)
	v_lshlrev_b32_e32 v76, 16, v112
	v_and_b32_e32 v77, 0xffff0000, v112
	v_pk_add_f32 v[50:51], v[50:51], v[76:77]
	s_waitcnt vmcnt(23)
	v_lshlrev_b32_e32 v76, 16, v114
	v_and_b32_e32 v77, 0xffff0000, v114
	v_pk_add_f32 v[50:51], v[50:51], v[76:77]
	s_waitcnt vmcnt(19)
	v_lshlrev_b32_e32 v76, 16, v116
	v_and_b32_e32 v77, 0xffff0000, v116
	v_pk_add_f32 v[50:51], v[50:51], v[76:77]
	s_waitcnt vmcnt(15)
	v_lshlrev_b32_e32 v76, 16, v118
	v_and_b32_e32 v77, 0xffff0000, v118
	v_pk_add_f32 v[50:51], v[50:51], v[76:77]
	s_waitcnt vmcnt(11)
	v_lshlrev_b32_e32 v76, 16, v120
	v_and_b32_e32 v77, 0xffff0000, v120
	v_pk_add_f32 v[50:51], v[50:51], v[76:77]
	s_waitcnt vmcnt(7)
	v_lshlrev_b32_e32 v76, 16, v128
	v_and_b32_e32 v77, 0xffff0000, v128
	v_lshlrev_b32_e32 v86, 16, v55
	v_and_b32_e32 v87, 0xffff0000, v55
	v_lshlrev_b32_e32 v54, 16, v69
	v_and_b32_e32 v55, 0xffff0000, v69
	v_pk_add_f32 v[50:51], v[50:51], v[76:77]
	v_pk_add_f32 v[76:77], v[134:135], 0 op_sel_hi:[1,0]
	v_lshlrev_b32_e32 v136, 16, v52
	v_pk_add_f32 v[54:55], v[76:77], v[54:55]
	v_lshlrev_b32_e32 v76, 16, v109
	v_pk_add_f32 v[54:55], v[54:55], v[156:157]
	v_and_b32_e32 v77, 0xffff0000, v109
	v_pk_add_f32 v[54:55], v[54:55], v[76:77]
	v_lshlrev_b32_e32 v76, 16, v111
	v_and_b32_e32 v77, 0xffff0000, v111
	v_pk_add_f32 v[54:55], v[54:55], v[76:77]
	v_lshlrev_b32_e32 v76, 16, v113
	v_and_b32_e32 v77, 0xffff0000, v113
	v_pk_add_f32 v[54:55], v[54:55], v[76:77]
	v_lshlrev_b32_e32 v76, 16, v115
	v_and_b32_e32 v77, 0xffff0000, v115
	v_pk_add_f32 v[54:55], v[54:55], v[76:77]
	v_lshlrev_b32_e32 v76, 16, v117
	v_and_b32_e32 v77, 0xffff0000, v117
	v_pk_add_f32 v[54:55], v[54:55], v[76:77]
	v_lshlrev_b32_e32 v76, 16, v119
	v_and_b32_e32 v77, 0xffff0000, v119
	v_pk_add_f32 v[54:55], v[54:55], v[76:77]
	v_lshlrev_b32_e32 v76, 16, v121
	v_and_b32_e32 v77, 0xffff0000, v121
	v_and_b32_e32 v137, 0xffff0000, v52
	v_pk_add_f32 v[54:55], v[54:55], v[76:77]
	v_lshlrev_b32_e32 v76, 16, v129
	v_and_b32_e32 v77, 0xffff0000, v129
	v_pk_add_f32 v[54:55], v[54:55], v[76:77]
	v_pk_add_f32 v[76:77], v[136:137], 0 op_sel_hi:[1,0]
	v_lshlrev_b32_e32 v104, 16, v84
	v_pk_add_f32 v[76:77], v[76:77], v[142:143]
	v_and_b32_e32 v105, 0xffff0000, v84
	v_pk_add_f32 v[76:77], v[76:77], v[158:159]
	v_lshlrev_b32_e32 v138, 16, v53
	v_pk_add_f32 v[76:77], v[76:77], v[104:105]
	v_lshlrev_b32_e32 v104, 16, v90
	v_and_b32_e32 v105, 0xffff0000, v90
	v_pk_add_f32 v[76:77], v[76:77], v[104:105]
	v_lshlrev_b32_e32 v104, 16, v94
	v_and_b32_e32 v105, 0xffff0000, v94
	v_pk_add_f32 v[76:77], v[76:77], v[104:105]
	v_lshlrev_b32_e32 v104, 16, v96
	v_and_b32_e32 v105, 0xffff0000, v96
	v_pk_add_f32 v[76:77], v[76:77], v[104:105]
	v_lshlrev_b32_e32 v104, 16, v98
	v_and_b32_e32 v105, 0xffff0000, v98
	v_pk_add_f32 v[76:77], v[76:77], v[104:105]
	v_lshlrev_b32_e32 v104, 16, v100
	v_and_b32_e32 v105, 0xffff0000, v100
	v_pk_add_f32 v[76:77], v[76:77], v[104:105]
	v_lshlrev_b32_e32 v104, 16, v126
	v_and_b32_e32 v105, 0xffff0000, v126
	v_and_b32_e32 v139, 0xffff0000, v53
	v_pk_add_f32 v[76:77], v[76:77], v[104:105]
	s_waitcnt vmcnt(6)
	v_lshlrev_b32_e32 v104, 16, v130
	v_and_b32_e32 v105, 0xffff0000, v130
	v_pk_add_f32 v[76:77], v[76:77], v[104:105]
	v_pk_add_f32 v[104:105], v[138:139], 0 op_sel_hi:[1,0]
	v_lshlrev_b32_e32 v84, 16, v85
	v_pk_add_f32 v[104:105], v[104:105], v[144:145]
	v_and_b32_e32 v85, 0xffff0000, v85
	v_pk_add_f32 v[102:103], v[104:105], v[102:103]
	v_lshlrev_b32_e32 v90, 16, v91
	v_pk_add_f32 v[84:85], v[102:103], v[84:85]
	v_and_b32_e32 v91, 0xffff0000, v91
	v_pk_add_f32 v[84:85], v[84:85], v[90:91]
	v_lshlrev_b32_e32 v90, 16, v95
	v_and_b32_e32 v91, 0xffff0000, v95
	v_pk_add_f32 v[84:85], v[84:85], v[90:91]
	v_lshlrev_b32_e32 v90, 16, v97
	v_and_b32_e32 v91, 0xffff0000, v97
	v_pk_add_f32 v[84:85], v[84:85], v[90:91]
	v_lshlrev_b32_e32 v90, 16, v99
	v_and_b32_e32 v91, 0xffff0000, v99
	v_pk_add_f32 v[84:85], v[84:85], v[90:91]
	v_lshlrev_b32_e32 v90, 16, v101
	v_and_b32_e32 v91, 0xffff0000, v101
	v_pk_add_f32 v[84:85], v[84:85], v[90:91]
	v_lshlrev_b32_e32 v90, 16, v127
	v_and_b32_e32 v91, 0xffff0000, v127
	v_pk_add_f32 v[84:85], v[84:85], v[90:91]
	v_lshlrev_b32_e32 v90, 16, v131
	v_and_b32_e32 v91, 0xffff0000, v131
	v_lshlrev_b32_e32 v146, 16, v80
	v_and_b32_e32 v147, 0xffff0000, v80
	v_lshlrev_b32_e32 v88, 16, v81
	v_and_b32_e32 v89, 0xffff0000, v81
	v_pk_add_f32 v[84:85], v[84:85], v[90:91]
	v_pk_add_f32 v[90:91], v[140:141], 0 op_sel_hi:[1,0]
	v_pk_add_f32 v[86:87], v[86:87], 0 op_sel_hi:[1,0]
	v_pk_add_f32 v[90:91], v[90:91], v[146:147]
	v_pk_add_f32 v[86:87], v[86:87], v[88:89]
	v_pk_add_f32 v[90:91], v[90:91], v[160:161]
	v_lshlrev_b32_e32 v94, 16, v58
	v_and_b32_e32 v95, 0xffff0000, v58
	v_pk_add_f32 v[86:87], v[86:87], v[92:93]
	v_lshlrev_b32_e32 v58, 16, v59
	v_and_b32_e32 v59, 0xffff0000, v59
	v_pk_add_f32 v[90:91], v[90:91], v[94:95]
	v_lshlrev_b32_e32 v94, 16, v60
	v_and_b32_e32 v95, 0xffff0000, v60
	v_pk_add_f32 v[58:59], v[86:87], v[58:59]
	v_lshlrev_b32_e32 v60, 16, v61
	v_and_b32_e32 v61, 0xffff0000, v61
	v_pk_add_f32 v[58:59], v[58:59], v[60:61]
	v_lshlrev_b32_e32 v60, 16, v63
	v_and_b32_e32 v61, 0xffff0000, v63
	v_pk_add_f32 v[58:59], v[58:59], v[60:61]
	v_lshlrev_b32_e32 v60, 16, v65
	v_and_b32_e32 v61, 0xffff0000, v65
	v_pk_add_f32 v[58:59], v[58:59], v[60:61]
	v_lshlrev_b32_e32 v60, 16, v67
	v_and_b32_e32 v61, 0xffff0000, v67
	v_pk_add_f32 v[58:59], v[58:59], v[60:61]
	v_lshlrev_b32_e32 v60, 16, v71
	v_and_b32_e32 v61, 0xffff0000, v71
	v_pk_add_f32 v[58:59], v[58:59], v[60:61]
	v_lshlrev_b32_e32 v60, 16, v73
	v_and_b32_e32 v61, 0xffff0000, v73
	v_lshlrev_b32_e32 v78, 16, v56
	v_and_b32_e32 v79, 0xffff0000, v56
	v_lshlrev_b32_e32 v52, 16, v57
	v_and_b32_e32 v53, 0xffff0000, v57
	v_pk_add_f32 v[58:59], v[58:59], v[60:61]
	s_waitcnt vmcnt(5)
	v_lshlrev_b32_e32 v60, 16, v75
	v_and_b32_e32 v61, 0xffff0000, v75
	v_lshlrev_b32_e32 v80, 16, v82
	v_and_b32_e32 v81, 0xffff0000, v82
	v_lshlrev_b32_e32 v56, 16, v83
	v_and_b32_e32 v57, 0xffff0000, v83
	v_pk_add_f32 v[58:59], v[58:59], v[60:61]
	v_pk_add_f32 v[60:61], v[78:79], 0 op_sel_hi:[1,0]
	v_pk_add_f32 v[52:53], v[52:53], 0 op_sel_hi:[1,0]
	v_lshlrev_b32_e32 v82, 16, v106
	v_and_b32_e32 v83, 0xffff0000, v106
	v_lshlrev_b32_e32 v68, 16, v107
	v_and_b32_e32 v69, 0xffff0000, v107
	v_pk_add_f32 v[60:61], v[60:61], v[80:81]
	v_pk_add_f32 v[52:53], v[52:53], v[56:57]
	v_pk_add_f32 v[90:91], v[90:91], v[94:95]
	v_lshlrev_b32_e32 v94, 16, v62
	v_and_b32_e32 v95, 0xffff0000, v62
	v_pk_add_f32 v[60:61], v[60:61], v[82:83]
	v_lshlrev_b32_e32 v62, 16, v48
	v_and_b32_e32 v63, 0xffff0000, v48
	v_pk_add_f32 v[52:53], v[52:53], v[68:69]
	v_lshlrev_b32_e32 v48, 16, v49
	v_and_b32_e32 v49, 0xffff0000, v49
	v_pk_add_f32 v[60:61], v[60:61], v[62:63]
	v_lshlrev_b32_e32 v62, 16, v34
	v_and_b32_e32 v63, 0xffff0000, v34
	v_pk_add_f32 v[48:49], v[52:53], v[48:49]
	v_lshlrev_b32_e32 v34, 16, v35
	v_and_b32_e32 v35, 0xffff0000, v35
	v_pk_add_f32 v[60:61], v[60:61], v[62:63]
	v_lshlrev_b32_e32 v62, 16, v36
	v_and_b32_e32 v63, 0xffff0000, v36
	v_pk_add_f32 v[34:35], v[48:49], v[34:35]
	v_lshlrev_b32_e32 v36, 16, v37
	v_and_b32_e32 v37, 0xffff0000, v37
	v_pk_add_f32 v[90:91], v[90:91], v[94:95]
	v_lshlrev_b32_e32 v94, 16, v64
	v_and_b32_e32 v95, 0xffff0000, v64
	v_pk_add_f32 v[34:35], v[34:35], v[36:37]
	v_lshlrev_b32_e32 v36, 16, v39
	v_and_b32_e32 v37, 0xffff0000, v39
	v_pk_add_f32 v[90:91], v[90:91], v[94:95]
	v_lshlrev_b32_e32 v94, 16, v66
	v_and_b32_e32 v95, 0xffff0000, v66
	v_pk_add_f32 v[34:35], v[34:35], v[36:37]
	v_lshlrev_b32_e32 v36, 16, v41
	v_and_b32_e32 v37, 0xffff0000, v41
	v_pk_add_f32 v[90:91], v[90:91], v[94:95]
	v_lshlrev_b32_e32 v94, 16, v70
	v_and_b32_e32 v95, 0xffff0000, v70
	v_pk_add_f32 v[60:61], v[60:61], v[62:63]
	v_lshlrev_b32_e32 v62, 16, v38
	v_and_b32_e32 v63, 0xffff0000, v38
	v_pk_add_f32 v[34:35], v[34:35], v[36:37]
	v_lshlrev_b32_e32 v36, 16, v43
	v_and_b32_e32 v37, 0xffff0000, v43
	v_pk_add_f32 v[90:91], v[90:91], v[94:95]
	v_lshlrev_b32_e32 v94, 16, v72
	v_and_b32_e32 v95, 0xffff0000, v72
	v_pk_add_f32 v[60:61], v[60:61], v[62:63]
	v_lshlrev_b32_e32 v62, 16, v40
	v_and_b32_e32 v63, 0xffff0000, v40
	v_pk_add_f32 v[34:35], v[34:35], v[36:37]
	v_lshlrev_b32_e32 v36, 16, v45
	v_and_b32_e32 v37, 0xffff0000, v45
	v_pk_add_f32 v[90:91], v[90:91], v[94:95]
	v_lshlrev_b32_e32 v94, 16, v74
	v_and_b32_e32 v95, 0xffff0000, v74
	v_pk_add_f32 v[60:61], v[60:61], v[62:63]
	v_lshlrev_b32_e32 v62, 16, v42
	v_and_b32_e32 v63, 0xffff0000, v42
	v_pk_add_f32 v[34:35], v[34:35], v[36:37]
	s_waitcnt vmcnt(4)
	v_lshlrev_b32_e32 v36, 16, v47
	v_and_b32_e32 v37, 0xffff0000, v47
	v_mov_b32_e32 v38, v51
	v_mov_b32_e32 v39, v55
	v_pk_add_f32 v[90:91], v[90:91], v[94:95]
	v_pk_add_f32 v[60:61], v[60:61], v[62:63]
	v_lshlrev_b32_e32 v62, 16, v44
	v_and_b32_e32 v63, 0xffff0000, v44
	v_pk_add_f32 v[34:35], v[34:35], v[36:37]
	v_mov_b32_e32 v36, v50
	v_mov_b32_e32 v37, v54
	v_pk_mul_f32 v[38:39], v[38:39], v[38:39]
	v_mov_b32_e32 v40, v77
	v_mov_b32_e32 v41, v85
	v_pk_add_f32 v[60:61], v[60:61], v[62:63]
	v_lshlrev_b32_e32 v62, 16, v46
	v_and_b32_e32 v63, 0xffff0000, v46
	v_pk_fma_f32 v[36:37], v[36:37], v[36:37], v[38:39]
	v_mov_b32_e32 v38, v76
	v_mov_b32_e32 v39, v84
	v_pk_mul_f32 v[40:41], v[40:41], v[40:41]
	v_mul_f32_e32 v22, v91, v91
	v_pk_add_f32 v[60:61], v[60:61], v[62:63]
	v_pk_fma_f32 v[38:39], v[38:39], v[38:39], v[40:41]
	v_pk_fma_f32 v[40:41], v[90:91], v[90:91], v[22:23] op_sel_hi:[1,1,0]
	v_mul_f32_e32 v22, v59, v59
	v_pk_add_f32 v[36:37], v[36:37], v[36:37] op_sel:[0,1] op_sel_hi:[1,0]
	v_pk_add_f32 v[38:39], v[38:39], v[38:39] op_sel:[0,1] op_sel_hi:[1,0]
	v_pk_fma_f32 v[42:43], v[58:59], v[58:59], v[22:23] op_sel_hi:[1,1,0]
	v_pk_mul_f32 v[44:45], v[60:61], v[60:61]
	v_pk_mul_f32 v[46:47], v[34:35], v[34:35]
	v_mov_b32_e32 v37, v44
	v_mov_b32_e32 v39, v45
	v_mov_b32_e32 v41, v46
	v_mov_b32_e32 v43, v47
	v_pk_add_f32 v[36:37], v[36:37], v[38:39]
	v_pk_add_f32 v[38:39], v[40:41], v[42:43]
	s_waitcnt vmcnt(1)
	v_lshlrev_b32_e32 v42, 16, v28
	v_pk_add_f32 v[36:37], v[36:37], v[38:39]
	s_waitcnt vmcnt(0)
	v_lshlrev_b32_e32 v46, 16, v26
	v_add_f32_e32 v22, v36, v37
	s_nop 1
	v_mov_b32_dpp v36, v22 quad_perm:[1,0,3,2] row_mask:0xf bank_mask:0xf
	v_lshlrev_b32_e32 v38, 16, v32
	v_lshlrev_b32_e32 v44, 16, v29
	v_and_b32_e32 v45, 0xffff0000, v29
	v_lshlrev_b32_e32 v48, 16, v27
	s_waitcnt lgkmcnt(0)
	v_add_f32_e32 v22, v22, v36
	s_nop 1
	v_mov_b32_dpp v36, v22 quad_perm:[2,3,0,1] row_mask:0xf bank_mask:0xf
	v_and_b32_e32 v49, 0xffff0000, v27
	v_lshlrev_b32_e32 v40, 16, v30
	s_waitcnt lgkmcnt(0)
	v_add_f32_e32 v22, v22, v36
	s_nop 1
	v_mov_b32_dpp v39, v22 row_half_mirror row_mask:0xf bank_mask:0xf
	v_lshl_add_u64 v[36:37], v[152:153], 4, s[14:15]
	s_waitcnt lgkmcnt(0)
	v_add_f32_e32 v22, v22, v39
	s_nop 1
	v_mov_b32_dpp v41, v22 row_mirror row_mask:0xf bank_mask:0xf
	v_and_b32_e32 v39, 0xffff0000, v32
	v_lshlrev_b32_e32 v32, 16, v33
	v_and_b32_e32 v33, 0xffff0000, v33
	s_waitcnt lgkmcnt(0)
	v_add_f32_e32 v22, v22, v41
	v_mov_b32_e32 v43, v22
	s_nop 1
	v_permlane16_swap_b32 v22, v43
	v_and_b32_e32 v41, 0xffff0000, v30
	v_lshlrev_b32_e32 v30, 16, v31
	v_and_b32_e32 v31, 0xffff0000, v31
	s_waitcnt lgkmcnt(0)
	v_add_f32_e32 v22, v22, v43
	v_mov_b32_e32 v47, v22
	s_nop 1
	v_permlane32_swap_b32 v22, v47
	v_and_b32_e32 v43, 0xffff0000, v28
	s_waitcnt lgkmcnt(0)
	v_add_f32_e32 v22, v22, v47
	v_fmamk_f32 v22, v22, 0x3a800000, v122
	v_mul_f32_e32 v28, 0x4b800000, v22
	v_cmp_gt_f32_e32 vcc, s67, v22
	v_and_b32_e32 v47, 0xffff0000, v26
	s_nop 0
	v_cndmask_b32_e32 v22, v22, v28, vcc
	v_rsq_f32_e32 v22, v22
	s_nop 0
	v_mul_f32_e32 v26, 0x45800000, v22
	v_cndmask_b32_e32 v22, v22, v26, vcc
	v_pk_mul_f32 v[26:27], v[50:51], v[22:23] op_sel_hi:[1,0]
	v_pk_mul_f32 v[28:29], v[54:55], v[22:23] op_sel_hi:[1,0]
	v_pk_fma_f32 v[26:27], v[8:9], v[26:27], v[38:39]
	v_pk_fma_f32 v[28:29], v[10:11], v[28:29], v[32:33]
	global_store_dwordx4 v[36:37], v[26:29], off
	s_nop 1
	v_pk_mul_f32 v[26:27], v[76:77], v[22:23] op_sel_hi:[1,0]
	v_pk_mul_f32 v[28:29], v[84:85], v[22:23] op_sel_hi:[1,0]
	v_pk_fma_f32 v[26:27], v[0:1], v[26:27], v[40:41]
	v_pk_fma_f32 v[28:29], v[2:3], v[28:29], v[30:31]
	global_store_dwordx4 v[36:37], v[26:29], off offset:1024
	s_nop 1
	v_pk_mul_f32 v[26:27], v[90:91], v[22:23] op_sel_hi:[1,0]
	v_pk_mul_f32 v[28:29], v[58:59], v[22:23] op_sel_hi:[1,0]
	v_pk_fma_f32 v[26:27], v[4:5], v[26:27], v[42:43]
	v_pk_fma_f32 v[28:29], v[6:7], v[28:29], v[44:45]
	global_store_dwordx4 v[36:37], v[26:29], off offset:2048
	s_nop 1
	v_pk_mul_f32 v[26:27], v[60:61], v[22:23] op_sel_hi:[1,0]
	v_pk_mul_f32 v[28:29], v[34:35], v[22:23] op_sel_hi:[1,0]
	v_pk_fma_f32 v[26:27], v[12:13], v[26:27], v[46:47]
	v_pk_fma_f32 v[28:29], v[14:15], v[28:29], v[48:49]
	global_store_dwordx4 v[36:37], v[26:29], off offset:3072
	s_cbranch_scc1 .LBB0_2461

.LBB0_2447:
	s_lshl_b64 s[14:15], s[14:15], 12
	s_add_u32 s14, s16, s14
	s_mul_hi_u32 s2, s28, 0xfe03f81
	s_addc_u32 s15, s17, s15
	s_lshr_b32 s2, s2, 7
	s_lshl_b32 s16, s2, 11
	s_sub_i32 s16, s8, s16
	s_add_u32 s34, s16, 1
	s_lshl_b32 s16, s2, 4
	s_mulk_i32 s2, 0x810
	s_sub_i32 s16, s29, s16
	s_sub_i32 s2, s8, s2
	s_add_u32 s35, s16, 1
	s_add_u32 s26, s2, 1
	s_lshl_b64 s[16:17], s[20:21], 12
	s_add_u32 s16, s24, s16
	s_addc_u32 s17, s25, s17
	v_lshl_add_u64 v[26:27], v[152:153], 3, s[16:17]
	v_lshl_add_u64 v[46:47], v[24:25], 0, s[12:13]
	global_load_dwordx2 v[54:55], v[26:27], off offset:2048
	global_load_dwordx2 v[52:53], v[26:27], off offset:2560
	global_load_dwordx2 v[50:51], v[26:27], off offset:3072
	global_load_dwordx2 v[48:49], v[26:27], off offset:3584
	v_add_co_u32_e32 v26, vcc, s56, v46
	s_add_i32 s31, s31, 1
	s_nop 0
	v_addc_co_u32_e32 v27, vcc, 0, v47, vcc
	v_add_co_u32_e32 v28, vcc, s57, v46
	global_load_dwordx2 v[72:73], v[26:27], off
	global_load_dwordx2 v[74:75], v[26:27], off offset:512
	global_load_dwordx2 v[76:77], v[26:27], off offset:1024
	global_load_dwordx2 v[80:81], v[26:27], off offset:1536
	v_addc_co_u32_e32 v29, vcc, 0, v47, vcc
	v_add_co_u32_e32 v30, vcc, s58, v46
	global_load_dwordx2 v[90:91], v[28:29], off
	global_load_dwordx2 v[94:95], v[28:29], off offset:512
	global_load_dwordx2 v[102:103], v[28:29], off offset:1024
	global_load_dwordx2 v[104:105], v[28:29], off offset:1536
	v_addc_co_u32_e32 v31, vcc, 0, v47, vcc
	v_add_co_u32_e32 v32, vcc, s59, v46
	global_load_dwordx2 v[118:119], v[30:31], off
	global_load_dwordx2 v[126:127], v[30:31], off offset:512
	global_load_dwordx2 v[128:129], v[30:31], off offset:1024
	global_load_dwordx2 v[130:131], v[30:31], off offset:1536
	v_addc_co_u32_e32 v33, vcc, 0, v47, vcc
	v_add_co_u32_e32 v34, vcc, s60, v46
	global_load_dwordx2 v[132:133], v[32:33], off
	global_load_dwordx2 v[106:107], v[32:33], off offset:512
	global_load_dwordx2 v[78:79], v[32:33], off offset:1024
	global_load_dwordx2 v[56:57], v[32:33], off offset:1536
	v_addc_co_u32_e32 v35, vcc, 0, v47, vcc
	v_add_co_u32_e32 v36, vcc, s61, v46
	global_load_dwordx2 v[134:135], v[34:35], off
	global_load_dwordx2 v[112:113], v[34:35], off offset:512
	global_load_dwordx2 v[82:83], v[34:35], off offset:1024
	global_load_dwordx2 v[58:59], v[34:35], off offset:1536
	v_addc_co_u32_e32 v37, vcc, 0, v47, vcc
	v_add_co_u32_e32 v38, vcc, s62, v46
	global_load_dwordx2 v[136:137], v[36:37], off
	global_load_dwordx2 v[114:115], v[36:37], off offset:512
	global_load_dwordx2 v[84:85], v[36:37], off offset:1024
	global_load_dwordx2 v[60:61], v[36:37], off offset:1536
	v_addc_co_u32_e32 v39, vcc, 0, v47, vcc
	v_add_co_u32_e32 v40, vcc, s63, v46
	global_load_dwordx2 v[138:139], v[38:39], off
	global_load_dwordx2 v[116:117], v[38:39], off offset:512
	global_load_dwordx2 v[86:87], v[38:39], off offset:1024
	global_load_dwordx2 v[62:63], v[38:39], off offset:1536
	v_addc_co_u32_e32 v41, vcc, 0, v47, vcc
	v_add_co_u32_e32 v42, vcc, s64, v46
	global_load_dwordx2 v[140:141], v[40:41], off
	global_load_dwordx2 v[120:121], v[40:41], off offset:512
	global_load_dwordx2 v[88:89], v[40:41], off offset:1024
	global_load_dwordx2 v[64:65], v[40:41], off offset:1536
	v_addc_co_u32_e32 v43, vcc, 0, v47, vcc
	v_add_co_u32_e32 v44, vcc, s65, v46
	global_load_dwordx2 v[142:143], v[42:43], off
	s_nop 0
	v_addc_co_u32_e32 v45, vcc, 0, v47, vcc
	global_load_dwordx2 v[144:145], v[44:45], off
	v_add_co_u32_e32 v46, vcc, s66, v46
	s_cmpk_gt_u32 s31, 0x407f
	s_nop 0
	v_addc_co_u32_e32 v47, vcc, 0, v47, vcc
	global_load_dwordx2 v[146:147], v[46:47], off
	global_load_dwordx2 v[156:157], v[42:43], off offset:512
	global_load_dwordx2 v[98:99], v[42:43], off offset:1024
	global_load_dwordx2 v[70:71], v[42:43], off offset:1536
	global_load_dwordx2 v[158:159], v[44:45], off offset:512
	global_load_dwordx2 v[96:97], v[44:45], off offset:1024
	global_load_dwordx2 v[68:69], v[44:45], off offset:1536
	global_load_dwordx2 v[160:161], v[46:47], off offset:512
	global_load_dwordx2 v[92:93], v[46:47], off offset:1024
	global_load_dwordx2 v[66:67], v[46:47], off offset:1536
	s_cselect_b64 s[20:21], -1, 0
	s_cmpk_lt_u32 s31, 0x4080
	s_waitcnt vmcnt(43)
	v_lshlrev_b32_e32 v162, 16, v72
	v_and_b32_e32 v163, 0xffff0000, v72
	v_lshlrev_b32_e32 v164, 16, v73
	v_and_b32_e32 v165, 0xffff0000, v73
	s_waitcnt vmcnt(41)
	v_lshlrev_b32_e32 v170, 16, v76
	s_waitcnt vmcnt(39)
	v_lshlrev_b32_e32 v72, 16, v90
	v_and_b32_e32 v73, 0xffff0000, v90
	s_waitcnt vmcnt(38)
	v_lshlrev_b32_e32 v172, 16, v94
	v_and_b32_e32 v173, 0xffff0000, v94
	v_lshlrev_b32_e32 v174, 16, v95
	v_and_b32_e32 v175, 0xffff0000, v95
	s_waitcnt vmcnt(35)
	v_lshlrev_b32_e32 v94, 16, v118
	v_and_b32_e32 v95, 0xffff0000, v118
	v_lshlrev_b32_e32 v178, 16, v119
	v_and_b32_e32 v179, 0xffff0000, v119
	s_waitcnt vmcnt(33)
	v_lshlrev_b32_e32 v182, 16, v128
	v_and_b32_e32 v183, 0xffff0000, v128
	v_lshlrev_b32_e32 v118, 16, v129
	v_and_b32_e32 v119, 0xffff0000, v129
	v_pk_add_f32 v[128:129], v[162:163], 0 op_sel_hi:[1,0]
	v_and_b32_e32 v171, 0xffff0000, v76
	v_pk_add_f32 v[72:73], v[128:129], v[72:73]
	v_lshlrev_b32_e32 v108, 16, v77
	v_pk_add_f32 v[72:73], v[72:73], v[94:95]
	s_waitcnt vmcnt(31)
	v_lshlrev_b32_e32 v94, 16, v132
	v_and_b32_e32 v95, 0xffff0000, v132
	v_pk_add_f32 v[72:73], v[72:73], v[94:95]
	s_waitcnt vmcnt(27)
	v_lshlrev_b32_e32 v94, 16, v134
	v_and_b32_e32 v95, 0xffff0000, v134
	v_pk_add_f32 v[72:73], v[72:73], v[94:95]
	s_waitcnt vmcnt(23)
	v_lshlrev_b32_e32 v94, 16, v136
	v_and_b32_e32 v95, 0xffff0000, v136
	v_pk_add_f32 v[72:73], v[72:73], v[94:95]
	s_waitcnt vmcnt(19)
	v_lshlrev_b32_e32 v94, 16, v138
	v_and_b32_e32 v95, 0xffff0000, v138
	v_pk_add_f32 v[72:73], v[72:73], v[94:95]
	s_waitcnt vmcnt(15)
	v_lshlrev_b32_e32 v94, 16, v140
	v_and_b32_e32 v95, 0xffff0000, v140
	v_pk_add_f32 v[72:73], v[72:73], v[94:95]
	v_and_b32_e32 v109, 0xffff0000, v77
	v_lshlrev_b32_e32 v76, 16, v91
	v_and_b32_e32 v77, 0xffff0000, v91
	v_lshlrev_b32_e32 v166, 16, v74
	s_waitcnt vmcnt(11)
	v_lshlrev_b32_e32 v94, 16, v142
	v_and_b32_e32 v95, 0xffff0000, v142
	v_pk_add_f32 v[72:73], v[72:73], v[94:95]
	s_waitcnt vmcnt(10)
	v_lshlrev_b32_e32 v94, 16, v144
	v_and_b32_e32 v95, 0xffff0000, v144
	v_pk_add_f32 v[72:73], v[72:73], v[94:95]
	s_waitcnt vmcnt(9)
	v_lshlrev_b32_e32 v94, 16, v146
	v_and_b32_e32 v95, 0xffff0000, v146
	v_pk_add_f32 v[72:73], v[72:73], v[94:95]
	v_pk_add_f32 v[94:95], v[164:165], 0 op_sel_hi:[1,0]
	v_and_b32_e32 v167, 0xffff0000, v74
	v_pk_add_f32 v[76:77], v[94:95], v[76:77]
	v_lshlrev_b32_e32 v94, 16, v133
	v_pk_add_f32 v[76:77], v[76:77], v[178:179]
	v_and_b32_e32 v95, 0xffff0000, v133
	v_pk_add_f32 v[76:77], v[76:77], v[94:95]
	v_lshlrev_b32_e32 v94, 16, v135
	v_and_b32_e32 v95, 0xffff0000, v135
	v_pk_add_f32 v[76:77], v[76:77], v[94:95]
	v_lshlrev_b32_e32 v94, 16, v137
	v_and_b32_e32 v95, 0xffff0000, v137
	v_pk_add_f32 v[76:77], v[76:77], v[94:95]
	v_lshlrev_b32_e32 v94, 16, v139
	v_and_b32_e32 v95, 0xffff0000, v139
	v_pk_add_f32 v[76:77], v[76:77], v[94:95]
	v_lshlrev_b32_e32 v94, 16, v141
	v_and_b32_e32 v95, 0xffff0000, v141
	v_pk_add_f32 v[76:77], v[76:77], v[94:95]
	v_lshlrev_b32_e32 v94, 16, v143
	v_and_b32_e32 v95, 0xffff0000, v143
	v_pk_add_f32 v[76:77], v[76:77], v[94:95]
	v_lshlrev_b32_e32 v94, 16, v145
	v_and_b32_e32 v95, 0xffff0000, v145
	v_pk_add_f32 v[76:77], v[76:77], v[94:95]
	v_lshlrev_b32_e32 v94, 16, v147
	v_and_b32_e32 v95, 0xffff0000, v147
	v_pk_add_f32 v[76:77], v[76:77], v[94:95]
	v_pk_add_f32 v[94:95], v[166:167], 0 op_sel_hi:[1,0]
	v_lshlrev_b32_e32 v180, 16, v126
	v_and_b32_e32 v181, 0xffff0000, v126
	v_pk_add_f32 v[94:95], v[94:95], v[172:173]
	v_lshlrev_b32_e32 v128, 16, v106
	v_pk_add_f32 v[94:95], v[94:95], v[180:181]
	v_and_b32_e32 v129, 0xffff0000, v106
	v_pk_add_f32 v[94:95], v[94:95], v[128:129]
	v_lshlrev_b32_e32 v128, 16, v112
	v_and_b32_e32 v129, 0xffff0000, v112
	v_pk_add_f32 v[94:95], v[94:95], v[128:129]
	v_lshlrev_b32_e32 v128, 16, v114
	v_and_b32_e32 v129, 0xffff0000, v114
	v_pk_add_f32 v[94:95], v[94:95], v[128:129]
	v_lshlrev_b32_e32 v128, 16, v116
	v_and_b32_e32 v129, 0xffff0000, v116
	v_pk_add_f32 v[94:95], v[94:95], v[128:129]
	v_lshlrev_b32_e32 v128, 16, v120
	v_and_b32_e32 v129, 0xffff0000, v120
	v_pk_add_f32 v[94:95], v[94:95], v[128:129]
	s_waitcnt vmcnt(8)
	v_lshlrev_b32_e32 v128, 16, v156
	v_and_b32_e32 v129, 0xffff0000, v156
	v_pk_add_f32 v[94:95], v[94:95], v[128:129]
	s_waitcnt vmcnt(5)
	v_lshlrev_b32_e32 v128, 16, v158
	v_and_b32_e32 v129, 0xffff0000, v158
	v_lshlrev_b32_e32 v168, 16, v75
	v_and_b32_e32 v169, 0xffff0000, v75
	v_pk_add_f32 v[94:95], v[94:95], v[128:129]
	s_waitcnt vmcnt(2)
	v_lshlrev_b32_e32 v128, 16, v160
	v_and_b32_e32 v129, 0xffff0000, v160
	v_pk_add_f32 v[94:95], v[94:95], v[128:129]
	v_pk_add_f32 v[128:129], v[168:169], 0 op_sel_hi:[1,0]
	v_lshlrev_b32_e32 v126, 16, v127
	v_and_b32_e32 v127, 0xffff0000, v127
	v_pk_add_f32 v[128:129], v[128:129], v[174:175]
	v_lshlrev_b32_e32 v106, 16, v107
	v_pk_add_f32 v[126:127], v[128:129], v[126:127]
	v_and_b32_e32 v107, 0xffff0000, v107
	v_pk_add_f32 v[106:107], v[126:127], v[106:107]
	v_lshlrev_b32_e32 v112, 16, v113
	v_and_b32_e32 v113, 0xffff0000, v113
	v_pk_add_f32 v[106:107], v[106:107], v[112:113]
	v_lshlrev_b32_e32 v112, 16, v115
	v_and_b32_e32 v113, 0xffff0000, v115
	v_pk_add_f32 v[106:107], v[106:107], v[112:113]
	v_lshlrev_b32_e32 v112, 16, v117
	v_and_b32_e32 v113, 0xffff0000, v117
	v_pk_add_f32 v[106:107], v[106:107], v[112:113]
	v_lshlrev_b32_e32 v112, 16, v121
	v_and_b32_e32 v113, 0xffff0000, v121
	v_pk_add_f32 v[106:107], v[106:107], v[112:113]
	v_lshlrev_b32_e32 v112, 16, v157
	v_and_b32_e32 v113, 0xffff0000, v157
	v_pk_add_f32 v[106:107], v[106:107], v[112:113]
	v_lshlrev_b32_e32 v112, 16, v159
	v_and_b32_e32 v113, 0xffff0000, v159
	v_pk_add_f32 v[106:107], v[106:107], v[112:113]
	v_lshlrev_b32_e32 v112, 16, v161
	v_and_b32_e32 v113, 0xffff0000, v161
	v_lshlrev_b32_e32 v176, 16, v102
	v_and_b32_e32 v177, 0xffff0000, v102
	v_lshlrev_b32_e32 v110, 16, v103
	v_and_b32_e32 v111, 0xffff0000, v103
	v_pk_add_f32 v[106:107], v[106:107], v[112:113]
	v_pk_add_f32 v[112:113], v[170:171], 0 op_sel_hi:[1,0]
	v_pk_add_f32 v[108:109], v[108:109], 0 op_sel_hi:[1,0]
	v_pk_add_f32 v[112:113], v[112:113], v[176:177]
	v_pk_add_f32 v[108:109], v[108:109], v[110:111]
	v_pk_add_f32 v[112:113], v[112:113], v[182:183]
	v_lshlrev_b32_e32 v114, 16, v78
	v_and_b32_e32 v115, 0xffff0000, v78
	v_pk_add_f32 v[108:109], v[108:109], v[118:119]
	v_lshlrev_b32_e32 v78, 16, v79
	v_and_b32_e32 v79, 0xffff0000, v79
	v_pk_add_f32 v[112:113], v[112:113], v[114:115]
	v_lshlrev_b32_e32 v114, 16, v82
	v_and_b32_e32 v115, 0xffff0000, v82
	v_pk_add_f32 v[78:79], v[108:109], v[78:79]
	v_lshlrev_b32_e32 v82, 16, v83
	v_and_b32_e32 v83, 0xffff0000, v83
	v_pk_add_f32 v[78:79], v[78:79], v[82:83]
	v_lshlrev_b32_e32 v82, 16, v85
	v_and_b32_e32 v83, 0xffff0000, v85
	v_pk_add_f32 v[78:79], v[78:79], v[82:83]
	v_lshlrev_b32_e32 v82, 16, v87
	v_and_b32_e32 v83, 0xffff0000, v87
	v_pk_add_f32 v[78:79], v[78:79], v[82:83]
	v_lshlrev_b32_e32 v82, 16, v89
	v_and_b32_e32 v83, 0xffff0000, v89
	v_pk_add_f32 v[78:79], v[78:79], v[82:83]
	v_lshlrev_b32_e32 v82, 16, v99
	v_and_b32_e32 v83, 0xffff0000, v99
	v_pk_add_f32 v[78:79], v[78:79], v[82:83]
	v_lshlrev_b32_e32 v82, 16, v97
	v_and_b32_e32 v83, 0xffff0000, v97
	v_lshlrev_b32_e32 v100, 16, v80
	v_and_b32_e32 v101, 0xffff0000, v80
	v_lshlrev_b32_e32 v74, 16, v81
	v_and_b32_e32 v75, 0xffff0000, v81
	v_pk_add_f32 v[78:79], v[78:79], v[82:83]
	s_waitcnt vmcnt(1)
	v_lshlrev_b32_e32 v82, 16, v93
	v_and_b32_e32 v83, 0xffff0000, v93
	v_lshlrev_b32_e32 v102, 16, v104
	v_and_b32_e32 v103, 0xffff0000, v104
	v_lshlrev_b32_e32 v80, 16, v105
	v_and_b32_e32 v81, 0xffff0000, v105
	v_pk_add_f32 v[78:79], v[78:79], v[82:83]
	v_pk_add_f32 v[82:83], v[100:101], 0 op_sel_hi:[1,0]
	v_pk_add_f32 v[74:75], v[74:75], 0 op_sel_hi:[1,0]
	v_lshlrev_b32_e32 v104, 16, v130
	v_and_b32_e32 v105, 0xffff0000, v130
	v_lshlrev_b32_e32 v90, 16, v131
	v_and_b32_e32 v91, 0xffff0000, v131
	v_pk_add_f32 v[82:83], v[82:83], v[102:103]
	v_pk_add_f32 v[74:75], v[74:75], v[80:81]
	v_pk_add_f32 v[112:113], v[112:113], v[114:115]
	v_lshlrev_b32_e32 v114, 16, v84
	v_and_b32_e32 v115, 0xffff0000, v84
	v_pk_add_f32 v[82:83], v[82:83], v[104:105]
	v_lshlrev_b32_e32 v84, 16, v56
	v_and_b32_e32 v85, 0xffff0000, v56
	v_pk_add_f32 v[74:75], v[74:75], v[90:91]
	v_lshlrev_b32_e32 v56, 16, v57
	v_and_b32_e32 v57, 0xffff0000, v57
	v_pk_add_f32 v[82:83], v[82:83], v[84:85]
	v_lshlrev_b32_e32 v84, 16, v58
	v_and_b32_e32 v85, 0xffff0000, v58
	v_pk_add_f32 v[56:57], v[74:75], v[56:57]
	v_lshlrev_b32_e32 v58, 16, v59
	v_and_b32_e32 v59, 0xffff0000, v59
	v_pk_add_f32 v[56:57], v[56:57], v[58:59]
	v_lshlrev_b32_e32 v58, 16, v61
	v_and_b32_e32 v59, 0xffff0000, v61
	v_pk_add_f32 v[112:113], v[112:113], v[114:115]
	v_lshlrev_b32_e32 v114, 16, v86
	v_and_b32_e32 v115, 0xffff0000, v86
	v_pk_add_f32 v[56:57], v[56:57], v[58:59]
	v_lshlrev_b32_e32 v58, 16, v63
	v_and_b32_e32 v59, 0xffff0000, v63
	v_pk_add_f32 v[112:113], v[112:113], v[114:115]
	v_lshlrev_b32_e32 v114, 16, v88
	v_and_b32_e32 v115, 0xffff0000, v88
	v_pk_add_f32 v[82:83], v[82:83], v[84:85]
	v_lshlrev_b32_e32 v84, 16, v60
	v_and_b32_e32 v85, 0xffff0000, v60
	v_pk_add_f32 v[56:57], v[56:57], v[58:59]
	v_lshlrev_b32_e32 v58, 16, v65
	v_and_b32_e32 v59, 0xffff0000, v65
	v_pk_add_f32 v[112:113], v[112:113], v[114:115]
	v_lshlrev_b32_e32 v114, 16, v98
	v_and_b32_e32 v115, 0xffff0000, v98
	v_pk_add_f32 v[82:83], v[82:83], v[84:85]
	v_lshlrev_b32_e32 v84, 16, v62
	v_and_b32_e32 v85, 0xffff0000, v62
	v_pk_add_f32 v[56:57], v[56:57], v[58:59]
	v_lshlrev_b32_e32 v58, 16, v71
	v_and_b32_e32 v59, 0xffff0000, v71
	v_pk_add_f32 v[112:113], v[112:113], v[114:115]
	v_lshlrev_b32_e32 v114, 16, v96
	v_and_b32_e32 v115, 0xffff0000, v96
	v_pk_add_f32 v[82:83], v[82:83], v[84:85]
	v_lshlrev_b32_e32 v84, 16, v64
	v_and_b32_e32 v85, 0xffff0000, v64
	v_pk_add_f32 v[56:57], v[56:57], v[58:59]
	v_lshlrev_b32_e32 v58, 16, v69
	v_and_b32_e32 v59, 0xffff0000, v69
	v_pk_add_f32 v[112:113], v[112:113], v[114:115]
	v_lshlrev_b32_e32 v114, 16, v92
	v_and_b32_e32 v115, 0xffff0000, v92
	v_pk_add_f32 v[82:83], v[82:83], v[84:85]
	v_lshlrev_b32_e32 v84, 16, v70
	v_and_b32_e32 v85, 0xffff0000, v70
	v_pk_add_f32 v[56:57], v[56:57], v[58:59]
	s_waitcnt vmcnt(0)
	v_lshlrev_b32_e32 v58, 16, v67
	v_and_b32_e32 v59, 0xffff0000, v67
	v_mov_b32_e32 v60, v73
	v_mov_b32_e32 v61, v77
	v_pk_add_f32 v[112:113], v[112:113], v[114:115]
	v_pk_add_f32 v[82:83], v[82:83], v[84:85]
	v_lshlrev_b32_e32 v84, 16, v68
	v_and_b32_e32 v85, 0xffff0000, v68
	v_pk_add_f32 v[56:57], v[56:57], v[58:59]
	v_mov_b32_e32 v58, v72
	v_mov_b32_e32 v59, v76
	v_pk_mul_f32 v[60:61], v[60:61], v[60:61]
	v_mov_b32_e32 v62, v95
	v_mov_b32_e32 v63, v107
	v_pk_add_f32 v[82:83], v[82:83], v[84:85]
	v_lshlrev_b32_e32 v84, 16, v66
	v_and_b32_e32 v85, 0xffff0000, v66
	v_pk_fma_f32 v[58:59], v[58:59], v[58:59], v[60:61]
	v_mov_b32_e32 v60, v94
	v_mov_b32_e32 v61, v106
	v_pk_mul_f32 v[62:63], v[62:63], v[62:63]
	v_mul_f32_e32 v22, v113, v113
	v_pk_add_f32 v[82:83], v[82:83], v[84:85]
	v_pk_fma_f32 v[60:61], v[60:61], v[60:61], v[62:63]
	v_pk_fma_f32 v[62:63], v[112:113], v[112:113], v[22:23] op_sel_hi:[1,1,0]
	v_mul_f32_e32 v22, v79, v79
	v_pk_add_f32 v[58:59], v[58:59], v[58:59] op_sel:[0,1] op_sel_hi:[1,0]
	v_pk_add_f32 v[60:61], v[60:61], v[60:61] op_sel:[0,1] op_sel_hi:[1,0]
	v_pk_fma_f32 v[64:65], v[78:79], v[78:79], v[22:23] op_sel_hi:[1,1,0]
	v_pk_mul_f32 v[66:67], v[82:83], v[82:83]
	v_pk_mul_f32 v[68:69], v[56:57], v[56:57]
	v_mov_b32_e32 v59, v66
	v_mov_b32_e32 v61, v67
	v_mov_b32_e32 v63, v68
	v_mov_b32_e32 v65, v69
	v_pk_add_f32 v[58:59], v[58:59], v[60:61]
	v_pk_add_f32 v[60:61], v[62:63], v[64:65]
	v_lshlrev_b32_e32 v64, 16, v50
	v_pk_add_f32 v[58:59], v[58:59], v[60:61]
	v_lshlrev_b32_e32 v68, 16, v48
	v_add_f32_e32 v22, v58, v59
	s_nop 1
	v_mov_b32_dpp v58, v22 quad_perm:[1,0,3,2] row_mask:0xf bank_mask:0xf
	v_lshlrev_b32_e32 v60, 16, v54
	v_lshlrev_b32_e32 v66, 16, v51
	v_and_b32_e32 v67, 0xffff0000, v51
	v_lshlrev_b32_e32 v70, 16, v49
	s_waitcnt lgkmcnt(0)
	v_add_f32_e32 v22, v22, v58
	s_nop 1
	v_mov_b32_dpp v58, v22 quad_perm:[2,3,0,1] row_mask:0xf bank_mask:0xf
	v_and_b32_e32 v71, 0xffff0000, v49
	v_lshlrev_b32_e32 v62, 16, v52
	s_waitcnt lgkmcnt(0)
	v_add_f32_e32 v22, v22, v58
	s_nop 1
	v_mov_b32_dpp v61, v22 row_half_mirror row_mask:0xf bank_mask:0xf
	v_lshl_add_u64 v[58:59], v[152:153], 4, s[14:15]
	s_mov_b64 s[14:15], -1
	s_waitcnt lgkmcnt(0)
	v_add_f32_e32 v22, v22, v61
	s_nop 1
	v_mov_b32_dpp v63, v22 row_mirror row_mask:0xf bank_mask:0xf
	v_and_b32_e32 v61, 0xffff0000, v54
	v_lshlrev_b32_e32 v54, 16, v55
	v_and_b32_e32 v55, 0xffff0000, v55
	s_waitcnt lgkmcnt(0)
	v_add_f32_e32 v22, v22, v63
	v_mov_b32_e32 v65, v22
	s_nop 1
	v_permlane16_swap_b32 v22, v65
	v_and_b32_e32 v63, 0xffff0000, v52
	v_lshlrev_b32_e32 v52, 16, v53
	v_and_b32_e32 v53, 0xffff0000, v53
	s_waitcnt lgkmcnt(0)
	v_add_f32_e32 v22, v22, v65
	v_mov_b32_e32 v69, v22
	s_nop 1
	v_permlane32_swap_b32 v22, v69
	v_and_b32_e32 v65, 0xffff0000, v50
	s_waitcnt lgkmcnt(0)
	v_add_f32_e32 v22, v22, v69
	v_fmamk_f32 v22, v22, 0x3a800000, v122
	v_mul_f32_e32 v50, 0x4b800000, v22
	v_cmp_gt_f32_e32 vcc, s67, v22
	v_and_b32_e32 v69, 0xffff0000, v48
	s_nop 0
	v_cndmask_b32_e32 v22, v22, v50, vcc
	v_rsq_f32_e32 v22, v22
	s_nop 0
	v_mul_f32_e32 v48, 0x45800000, v22
	v_cndmask_b32_e32 v22, v22, v48, vcc
	v_pk_mul_f32 v[48:49], v[72:73], v[22:23] op_sel_hi:[1,0]
	v_pk_mul_f32 v[50:51], v[76:77], v[22:23] op_sel_hi:[1,0]
	v_pk_fma_f32 v[48:49], v[8:9], v[48:49], v[60:61]
	v_pk_fma_f32 v[50:51], v[10:11], v[50:51], v[54:55]
	global_store_dwordx4 v[58:59], v[48:51], off
	s_nop 1
	v_pk_mul_f32 v[48:49], v[94:95], v[22:23] op_sel_hi:[1,0]
	v_pk_mul_f32 v[50:51], v[106:107], v[22:23] op_sel_hi:[1,0]
	v_pk_fma_f32 v[48:49], v[0:1], v[48:49], v[62:63]
	v_pk_fma_f32 v[50:51], v[2:3], v[50:51], v[52:53]
	global_store_dwordx4 v[58:59], v[48:51], off offset:1024
	s_nop 1
	v_pk_mul_f32 v[48:49], v[112:113], v[22:23] op_sel_hi:[1,0]
	v_pk_mul_f32 v[50:51], v[78:79], v[22:23] op_sel_hi:[1,0]
	v_pk_fma_f32 v[48:49], v[4:5], v[48:49], v[64:65]
	v_pk_fma_f32 v[50:51], v[6:7], v[50:51], v[66:67]
	global_store_dwordx4 v[58:59], v[48:51], off offset:2048
	s_nop 1
	v_pk_mul_f32 v[48:49], v[82:83], v[22:23] op_sel_hi:[1,0]
	v_pk_mul_f32 v[50:51], v[56:57], v[22:23] op_sel_hi:[1,0]
	v_pk_fma_f32 v[48:49], v[12:13], v[48:49], v[68:69]
	v_pk_fma_f32 v[50:51], v[14:15], v[50:51], v[70:71]
	global_store_dwordx4 v[58:59], v[48:51], off offset:3072
	s_cbranch_scc1 .LBB0_2449
	s_add_u32 s2, s30, s4
	s_addc_u32 s14, 0, s5
	s_add_u32 s16, s2, 1
	s_addc_u32 s17, s14, 0
	s_mov_b64 s[14:15], 0

.LBB0_2479:
	s_or_b64 exec, exec, s[24:25]
	s_lshl_b64 s[16:17], s[16:17], 12
	s_add_u32 s16, s20, s16
	s_addc_u32 s17, s21, s17
	v_lshl_add_u64 v[24:25], v[152:153], 3, s[16:17]
	s_lshl_b64 s[16:17], s[8:9], 11
	global_load_dwordx2 v[26:27], v[24:25], off offset:2048
	global_load_dwordx2 v[28:29], v[24:25], off offset:2560
	global_load_dwordx2 v[30:31], v[24:25], off offset:3072
	global_load_dwordx2 v[32:33], v[24:25], off offset:3584
	v_lshl_add_u64 v[24:25], v[18:19], 0, s[16:17]
	global_load_dwordx2 v[34:35], v[24:25], off
	global_load_dwordx2 v[36:37], v[24:25], off offset:512
	global_load_dwordx2 v[38:39], v[24:25], off offset:1024
	global_load_dwordx2 v[40:41], v[24:25], off offset:1536
	s_waitcnt vmcnt(8)
	s_nop 1
	v_mov_b32_dpp v24, v22 quad_perm:[1,0,3,2] row_mask:0xf bank_mask:0xf
	s_lshl_b64 s[4:5], s[4:5], 12
	s_add_u32 s4, s14, s4
	s_addc_u32 s5, s15, s5
	v_lshl_add_u64 v[42:43], v[152:153], 4, s[4:5]
	s_waitcnt lgkmcnt(0)
	v_add_f32_e32 v22, v22, v24
	s_nop 1
	v_mov_b32_dpp v24, v22 quad_perm:[2,3,0,1] row_mask:0xf bank_mask:0xf
	s_mov_b64 s[14:15], -1
	s_waitcnt lgkmcnt(0)
	v_add_f32_e32 v22, v22, v24
	s_nop 1
	v_mov_b32_dpp v24, v22 row_half_mirror row_mask:0xf bank_mask:0xf
	s_waitcnt lgkmcnt(0)
	v_add_f32_e32 v22, v22, v24
	s_nop 1
	v_mov_b32_dpp v24, v22 row_mirror row_mask:0xf bank_mask:0xf
	s_waitcnt lgkmcnt(0)
	v_add_f32_e32 v22, v22, v24
	v_mov_b32_e32 v24, v22
	s_nop 1
	v_permlane16_swap_b32 v22, v24
	s_waitcnt lgkmcnt(0)
	v_add_f32_e32 v22, v22, v24
	v_mov_b32_e32 v24, v22
	s_nop 1
	v_permlane32_swap_b32 v22, v24
	s_waitcnt lgkmcnt(0)
	v_add_f32_e32 v22, v22, v24
	v_fmamk_f32 v22, v22, 0x3a800000, v122
	v_mul_f32_e32 v24, 0x4b800000, v22
	v_cmp_gt_f32_e32 vcc, s67, v22
	s_waitcnt vmcnt(7)
	v_and_b32_e32 v25, 0xffff0000, v26
	v_cndmask_b32_e32 v22, v22, v24, vcc
	v_rsq_f32_e32 v22, v22
	s_waitcnt vmcnt(5)
	v_lshlrev_b32_e32 v46, 16, v30
	v_and_b32_e32 v47, 0xffff0000, v30
	v_lshlrev_b32_e32 v48, 16, v31
	v_mul_f32_e32 v24, 0x45800000, v22
	v_cndmask_b32_e32 v22, v22, v24, vcc
	v_and_b32_e32 v49, 0xffff0000, v31
	s_waitcnt vmcnt(4)
	v_lshlrev_b32_e32 v50, 16, v32
	v_and_b32_e32 v51, 0xffff0000, v32
	v_lshlrev_b32_e32 v52, 16, v33
	v_and_b32_e32 v53, 0xffff0000, v33
	s_waitcnt vmcnt(3)
	v_lshlrev_b32_e32 v30, 16, v34
	v_and_b32_e32 v31, 0xffff0000, v34
	v_lshlrev_b32_e32 v32, 16, v35
	v_and_b32_e32 v33, 0xffff0000, v35
	s_waitcnt vmcnt(2)
	v_lshlrev_b32_e32 v34, 16, v36
	v_and_b32_e32 v35, 0xffff0000, v36
	v_lshlrev_b32_e32 v36, 16, v37
	v_and_b32_e32 v37, 0xffff0000, v37
	s_waitcnt vmcnt(1)
	v_lshlrev_b32_e32 v54, 16, v38
	v_and_b32_e32 v55, 0xffff0000, v38
	v_lshlrev_b32_e32 v38, 16, v39
	v_and_b32_e32 v39, 0xffff0000, v39
	s_waitcnt vmcnt(0)
	v_lshlrev_b32_e32 v56, 16, v40
	v_and_b32_e32 v57, 0xffff0000, v40
	v_lshlrev_b32_e32 v40, 16, v41
	v_and_b32_e32 v41, 0xffff0000, v41
	v_lshlrev_b32_e32 v24, 16, v26
	v_lshlrev_b32_e32 v26, 16, v27
	v_and_b32_e32 v27, 0xffff0000, v27
	v_pk_mul_f32 v[30:31], v[22:23], v[30:31] op_sel_hi:[0,1]
	v_pk_mul_f32 v[32:33], v[22:23], v[32:33] op_sel_hi:[0,1]
	v_pk_mul_f32 v[34:35], v[22:23], v[34:35] op_sel_hi:[0,1]
	v_pk_mul_f32 v[36:37], v[22:23], v[36:37] op_sel_hi:[0,1]
	v_pk_mul_f32 v[54:55], v[22:23], v[54:55] op_sel_hi:[0,1]
	v_pk_mul_f32 v[38:39], v[22:23], v[38:39] op_sel_hi:[0,1]
	v_pk_mul_f32 v[56:57], v[22:23], v[56:57] op_sel_hi:[0,1]
	v_pk_mul_f32 v[40:41], v[22:23], v[40:41] op_sel_hi:[0,1]
	v_cndmask_b32_e64 v22, 0, 1, s[12:13]
	v_lshlrev_b32_e32 v44, 16, v28
	v_and_b32_e32 v45, 0xffff0000, v28
	v_lshlrev_b32_e32 v28, 16, v29
	v_and_b32_e32 v29, 0xffff0000, v29
	v_pk_fma_f32 v[26:27], v[10:11], v[32:33], v[26:27]
	v_pk_fma_f32 v[24:25], v[8:9], v[30:31], v[24:25]
	v_cmp_ne_u32_e64 s[4:5], 1, v22
	s_andn2_b64 vcc, exec, s[12:13]
	v_pk_fma_f32 v[30:31], v[2:3], v[36:37], v[28:29]
	v_pk_fma_f32 v[28:29], v[0:1], v[34:35], v[44:45]
	v_pk_fma_f32 v[34:35], v[6:7], v[38:39], v[48:49]
	v_pk_fma_f32 v[32:33], v[4:5], v[54:55], v[46:47]
	v_pk_fma_f32 v[38:39], v[14:15], v[40:41], v[52:53]
	v_pk_fma_f32 v[36:37], v[12:13], v[56:57], v[50:51]
	global_store_dwordx4 v[42:43], v[24:27], off
	global_store_dwordx4 v[42:43], v[28:31], off offset:1024
	global_store_dwordx4 v[42:43], v[32:35], off offset:2048
	global_store_dwordx4 v[42:43], v[36:39], off offset:3072
	s_cbranch_vccnz .LBB0_2481
	s_add_i32 s2, s8, 0xffffbf81
	s_mov_b64 s[14:15], 0
	s_mov_b64 s[12:13], s[2:3]

.LBB0_2495:
	s_or_b64 exec, exec, s[24:25]
	s_lshl_b64 s[16:17], s[16:17], 12
	s_add_u32 s16, s20, s16
	s_addc_u32 s17, s21, s17
	v_lshl_add_u64 v[24:25], v[152:153], 3, s[16:17]
	s_lshl_b64 s[16:17], s[2:3], 11
	global_load_dwordx2 v[26:27], v[24:25], off offset:2048
	global_load_dwordx2 v[28:29], v[24:25], off offset:2560
	global_load_dwordx2 v[30:31], v[24:25], off offset:3072
	global_load_dwordx2 v[32:33], v[24:25], off offset:3584
	v_lshl_add_u64 v[24:25], v[18:19], 0, s[16:17]
	global_load_dwordx2 v[34:35], v[24:25], off
	global_load_dwordx2 v[36:37], v[24:25], off offset:512
	global_load_dwordx2 v[38:39], v[24:25], off offset:1024
	global_load_dwordx2 v[40:41], v[24:25], off offset:1536
	s_waitcnt vmcnt(8)
	s_nop 1
	v_mov_b32_dpp v24, v22 quad_perm:[1,0,3,2] row_mask:0xf bank_mask:0xf
	s_lshl_b64 s[12:13], s[12:13], 12
	s_add_u32 s12, s14, s12
	s_addc_u32 s13, s15, s13
	v_lshl_add_u64 v[42:43], v[152:153], 4, s[12:13]
	s_waitcnt lgkmcnt(0)
	v_add_f32_e32 v22, v22, v24
	s_nop 1
	v_mov_b32_dpp v24, v22 quad_perm:[2,3,0,1] row_mask:0xf bank_mask:0xf
	s_mov_b64 s[14:15], -1
	s_waitcnt lgkmcnt(0)
	v_add_f32_e32 v22, v22, v24
	s_nop 1
	v_mov_b32_dpp v24, v22 row_half_mirror row_mask:0xf bank_mask:0xf
	s_waitcnt lgkmcnt(0)
	v_add_f32_e32 v22, v22, v24
	s_nop 1
	v_mov_b32_dpp v24, v22 row_mirror row_mask:0xf bank_mask:0xf
	s_waitcnt lgkmcnt(0)
	v_add_f32_e32 v22, v22, v24
	v_mov_b32_e32 v24, v22
	s_nop 1
	v_permlane16_swap_b32 v22, v24
	s_waitcnt lgkmcnt(0)
	v_add_f32_e32 v22, v22, v24
	v_mov_b32_e32 v24, v22
	s_nop 1
	v_permlane32_swap_b32 v22, v24
	s_waitcnt lgkmcnt(0)
	v_add_f32_e32 v22, v22, v24
	v_fmamk_f32 v22, v22, 0x3a800000, v122
	v_mul_f32_e32 v24, 0x4b800000, v22
	v_cmp_gt_f32_e32 vcc, s67, v22
	s_waitcnt vmcnt(7)
	v_and_b32_e32 v25, 0xffff0000, v26
	v_cndmask_b32_e32 v22, v22, v24, vcc
	v_rsq_f32_e32 v22, v22
	s_waitcnt vmcnt(5)
	v_lshlrev_b32_e32 v46, 16, v30
	v_and_b32_e32 v47, 0xffff0000, v30
	v_lshlrev_b32_e32 v48, 16, v31
	v_mul_f32_e32 v24, 0x45800000, v22
	v_cndmask_b32_e32 v22, v22, v24, vcc
	v_and_b32_e32 v49, 0xffff0000, v31
	s_waitcnt vmcnt(4)
	v_lshlrev_b32_e32 v50, 16, v32
	v_and_b32_e32 v51, 0xffff0000, v32
	v_lshlrev_b32_e32 v52, 16, v33
	v_and_b32_e32 v53, 0xffff0000, v33
	s_waitcnt vmcnt(3)
	v_lshlrev_b32_e32 v30, 16, v34
	v_and_b32_e32 v31, 0xffff0000, v34
	v_lshlrev_b32_e32 v32, 16, v35
	v_and_b32_e32 v33, 0xffff0000, v35
	v_lshlrev_b32_e32 v24, 16, v26
	v_lshlrev_b32_e32 v26, 16, v27
	v_and_b32_e32 v27, 0xffff0000, v27
	s_waitcnt vmcnt(2)
	v_lshlrev_b32_e32 v34, 16, v36
	v_and_b32_e32 v35, 0xffff0000, v36
	v_lshlrev_b32_e32 v36, 16, v37
	v_and_b32_e32 v37, 0xffff0000, v37
	s_waitcnt vmcnt(1)
	v_lshlrev_b32_e32 v54, 16, v38
	v_and_b32_e32 v55, 0xffff0000, v38
	v_lshlrev_b32_e32 v38, 16, v39
	v_and_b32_e32 v39, 0xffff0000, v39
	s_waitcnt vmcnt(0)
	v_lshlrev_b32_e32 v56, 16, v40
	v_and_b32_e32 v57, 0xffff0000, v40
	v_lshlrev_b32_e32 v40, 16, v41
	v_and_b32_e32 v41, 0xffff0000, v41
	v_pk_mul_f32 v[30:31], v[22:23], v[30:31] op_sel_hi:[0,1]
	v_pk_mul_f32 v[32:33], v[22:23], v[32:33] op_sel_hi:[0,1]
	v_lshlrev_b32_e32 v44, 16, v28
	v_and_b32_e32 v45, 0xffff0000, v28
	v_lshlrev_b32_e32 v28, 16, v29
	v_and_b32_e32 v29, 0xffff0000, v29
	v_pk_mul_f32 v[34:35], v[22:23], v[34:35] op_sel_hi:[0,1]
	v_pk_mul_f32 v[36:37], v[22:23], v[36:37] op_sel_hi:[0,1]
	v_pk_mul_f32 v[54:55], v[22:23], v[54:55] op_sel_hi:[0,1]
	v_pk_mul_f32 v[38:39], v[22:23], v[38:39] op_sel_hi:[0,1]
	v_pk_mul_f32 v[56:57], v[22:23], v[56:57] op_sel_hi:[0,1]
	v_pk_mul_f32 v[40:41], v[22:23], v[40:41] op_sel_hi:[0,1]
	v_pk_fma_f32 v[26:27], v[10:11], v[32:33], v[26:27]
	v_pk_fma_f32 v[24:25], v[8:9], v[30:31], v[24:25]
	s_and_b64 vcc, exec, s[4:5]
	v_pk_fma_f32 v[30:31], v[2:3], v[36:37], v[28:29]
	v_pk_fma_f32 v[28:29], v[0:1], v[34:35], v[44:45]
	v_pk_fma_f32 v[34:35], v[6:7], v[38:39], v[48:49]
	v_pk_fma_f32 v[32:33], v[4:5], v[54:55], v[46:47]
	v_pk_fma_f32 v[38:39], v[14:15], v[40:41], v[52:53]
	v_pk_fma_f32 v[36:37], v[12:13], v[56:57], v[50:51]
	global_store_dwordx4 v[42:43], v[24:27], off
	global_store_dwordx4 v[42:43], v[28:31], off offset:1024
	global_store_dwordx4 v[42:43], v[32:35], off offset:2048
	global_store_dwordx4 v[42:43], v[36:39], off offset:3072
	s_cbranch_vccnz .LBB0_2497
	s_add_i32 s2, s8, 0xffffbf82
	s_mov_b64 s[14:15], 0
	s_mov_b64 s[12:13], s[2:3]

.LBB0_2511:
	s_or_b64 exec, exec, s[24:25]
	s_lshl_b64 s[16:17], s[16:17], 12
	s_add_u32 s16, s20, s16
	s_addc_u32 s17, s21, s17
	v_lshl_add_u64 v[24:25], v[152:153], 3, s[16:17]
	s_lshl_b64 s[16:17], s[2:3], 11
	global_load_dwordx2 v[26:27], v[24:25], off offset:2048
	global_load_dwordx2 v[28:29], v[24:25], off offset:2560
	global_load_dwordx2 v[30:31], v[24:25], off offset:3072
	global_load_dwordx2 v[32:33], v[24:25], off offset:3584
	v_lshl_add_u64 v[24:25], v[18:19], 0, s[16:17]
	global_load_dwordx2 v[34:35], v[24:25], off
	global_load_dwordx2 v[36:37], v[24:25], off offset:512
	global_load_dwordx2 v[38:39], v[24:25], off offset:1024
	global_load_dwordx2 v[40:41], v[24:25], off offset:1536
	s_waitcnt vmcnt(8)
	s_nop 1
	v_mov_b32_dpp v24, v22 quad_perm:[1,0,3,2] row_mask:0xf bank_mask:0xf
	s_lshl_b64 s[12:13], s[12:13], 12
	s_add_u32 s12, s14, s12
	s_addc_u32 s13, s15, s13
	v_lshl_add_u64 v[42:43], v[152:153], 4, s[12:13]
	s_waitcnt lgkmcnt(0)
	v_add_f32_e32 v22, v22, v24
	s_nop 1
	v_mov_b32_dpp v24, v22 quad_perm:[2,3,0,1] row_mask:0xf bank_mask:0xf
	s_mov_b64 s[14:15], -1
	s_waitcnt lgkmcnt(0)
	v_add_f32_e32 v22, v22, v24
	s_nop 1
	v_mov_b32_dpp v24, v22 row_half_mirror row_mask:0xf bank_mask:0xf
	s_waitcnt lgkmcnt(0)
	v_add_f32_e32 v22, v22, v24
	s_nop 1
	v_mov_b32_dpp v24, v22 row_mirror row_mask:0xf bank_mask:0xf
	s_waitcnt lgkmcnt(0)
	v_add_f32_e32 v22, v22, v24
	v_mov_b32_e32 v24, v22
	s_nop 1
	v_permlane16_swap_b32 v22, v24
	s_waitcnt lgkmcnt(0)
	v_add_f32_e32 v22, v22, v24
	v_mov_b32_e32 v24, v22
	s_nop 1
	v_permlane32_swap_b32 v22, v24
	s_waitcnt lgkmcnt(0)
	v_add_f32_e32 v22, v22, v24
	v_fmamk_f32 v22, v22, 0x3a800000, v122
	v_mul_f32_e32 v24, 0x4b800000, v22
	v_cmp_gt_f32_e32 vcc, s67, v22
	s_waitcnt vmcnt(7)
	v_and_b32_e32 v25, 0xffff0000, v26
	v_cndmask_b32_e32 v22, v22, v24, vcc
	v_rsq_f32_e32 v22, v22
	s_waitcnt vmcnt(5)
	v_lshlrev_b32_e32 v46, 16, v30
	v_and_b32_e32 v47, 0xffff0000, v30
	v_lshlrev_b32_e32 v48, 16, v31
	v_mul_f32_e32 v24, 0x45800000, v22
	v_cndmask_b32_e32 v22, v22, v24, vcc
	v_and_b32_e32 v49, 0xffff0000, v31
	s_waitcnt vmcnt(4)
	v_lshlrev_b32_e32 v50, 16, v32
	v_and_b32_e32 v51, 0xffff0000, v32
	v_lshlrev_b32_e32 v52, 16, v33
	v_and_b32_e32 v53, 0xffff0000, v33
	s_waitcnt vmcnt(3)
	v_lshlrev_b32_e32 v30, 16, v34
	v_and_b32_e32 v31, 0xffff0000, v34
	v_lshlrev_b32_e32 v32, 16, v35
	v_and_b32_e32 v33, 0xffff0000, v35
	v_lshlrev_b32_e32 v24, 16, v26
	v_lshlrev_b32_e32 v26, 16, v27
	v_and_b32_e32 v27, 0xffff0000, v27
	s_waitcnt vmcnt(2)
	v_lshlrev_b32_e32 v34, 16, v36
	v_and_b32_e32 v35, 0xffff0000, v36
	v_lshlrev_b32_e32 v36, 16, v37
	v_and_b32_e32 v37, 0xffff0000, v37
	s_waitcnt vmcnt(1)
	v_lshlrev_b32_e32 v54, 16, v38
	v_and_b32_e32 v55, 0xffff0000, v38
	v_lshlrev_b32_e32 v38, 16, v39
	v_and_b32_e32 v39, 0xffff0000, v39
	s_waitcnt vmcnt(0)
	v_lshlrev_b32_e32 v56, 16, v40
	v_and_b32_e32 v57, 0xffff0000, v40
	v_lshlrev_b32_e32 v40, 16, v41
	v_and_b32_e32 v41, 0xffff0000, v41
	v_pk_mul_f32 v[30:31], v[22:23], v[30:31] op_sel_hi:[0,1]
	v_pk_mul_f32 v[32:33], v[22:23], v[32:33] op_sel_hi:[0,1]
	v_lshlrev_b32_e32 v44, 16, v28
	v_and_b32_e32 v45, 0xffff0000, v28
	v_lshlrev_b32_e32 v28, 16, v29
	v_and_b32_e32 v29, 0xffff0000, v29
	v_pk_mul_f32 v[34:35], v[22:23], v[34:35] op_sel_hi:[0,1]
	v_pk_mul_f32 v[36:37], v[22:23], v[36:37] op_sel_hi:[0,1]
	v_pk_mul_f32 v[54:55], v[22:23], v[54:55] op_sel_hi:[0,1]
	v_pk_mul_f32 v[38:39], v[22:23], v[38:39] op_sel_hi:[0,1]
	v_pk_mul_f32 v[56:57], v[22:23], v[56:57] op_sel_hi:[0,1]
	v_pk_mul_f32 v[40:41], v[22:23], v[40:41] op_sel_hi:[0,1]
	v_pk_fma_f32 v[26:27], v[10:11], v[32:33], v[26:27]
	v_pk_fma_f32 v[24:25], v[8:9], v[30:31], v[24:25]
	s_and_b64 vcc, exec, s[4:5]
	v_pk_fma_f32 v[30:31], v[2:3], v[36:37], v[28:29]
	v_pk_fma_f32 v[28:29], v[0:1], v[34:35], v[44:45]
	v_pk_fma_f32 v[34:35], v[6:7], v[38:39], v[48:49]
	v_pk_fma_f32 v[32:33], v[4:5], v[54:55], v[46:47]
	v_pk_fma_f32 v[38:39], v[14:15], v[40:41], v[52:53]
	v_pk_fma_f32 v[36:37], v[12:13], v[56:57], v[50:51]
	global_store_dwordx4 v[42:43], v[24:27], off
	global_store_dwordx4 v[42:43], v[28:31], off offset:1024
	global_store_dwordx4 v[42:43], v[32:35], off offset:2048
	global_store_dwordx4 v[42:43], v[36:39], off offset:3072
	s_cbranch_vccnz .LBB0_2513
	s_add_i32 s2, s8, 0xffffbf83
	s_mov_b64 s[14:15], 0
	s_mov_b64 s[12:13], s[2:3]
